# K-loops: per-segment s_setprio flips and the redundant post-barrier lgkmcnt(0) deleted (fewer issue slots between barrier release and first MFMA)
# speedup vs baseline: 1.0070x; 1.0051x over previous
.LBB0_150:
	ds_read_b128 v[48:51], v214
	ds_read_b128 v[52:55], v214 offset:1024
	ds_read_b128 v[56:59], v214 offset:2048
	ds_read_b128 v[60:63], v214 offset:3072
	ds_read_b128 v[168:171], v215
	ds_read_b128 v[172:175], v215 offset:1024
	ds_read_b128 v[176:179], v215 offset:2048
	ds_read_b128 v[180:183], v215 offset:3072
	s_add_u32 s4, s2, 0xfffc0080
	s_addc_u32 s5, s3, -1
	s_cmp_eq_u32 s89, 12
	s_cselect_b32 s7, s8, s5
	s_cselect_b32 s6, s9, s4
	s_cselect_b32 s5, s79, s88
	s_cselect_b32 s4, s81, s87
	v_lshl_add_u64 v[212:213], s[2:3], 0, v[158:159]
	s_add_i32 m0, s68, 0xc000
	ds_read_b128 v[184:187], v216
	ds_read_b128 v[188:191], v216 offset:1024
	ds_read_b128 v[192:195], v216 offset:2048
	ds_read_b128 v[196:199], v216 offset:3072
	ds_read_b128 v[200:203], v216 offset:4096
	ds_read_b128 v[204:207], v216 offset:5120
	ds_read_b128 v[208:211], v216 offset:6144
	ds_read_b128 v[220:223], v216 offset:7168
	global_load_lds_dwordx4 v[212:213], off
	v_lshl_add_u64 v[212:213], s[2:3], 0, v[160:161]
	s_add_i32 m0, s68, 0xe000
	s_nop 0
	global_load_lds_dwordx4 v[212:213], off
	s_waitcnt vmcnt(8)
	s_waitcnt lgkmcnt(0)
	s_barrier

	v_mfma_f32_16x16x32_bf16 v[140:143], v[48:51], v[184:187], v[140:143]
	v_mfma_f32_16x16x32_bf16 v[136:139], v[56:59], v[184:187], v[136:139]
	v_mfma_f32_16x16x32_bf16 v[124:127], v[48:51], v[192:195], v[124:127]
	v_mfma_f32_16x16x32_bf16 v[120:123], v[56:59], v[192:195], v[120:123]
	v_mfma_f32_16x16x32_bf16 v[108:111], v[48:51], v[200:203], v[108:111]
	v_mfma_f32_16x16x32_bf16 v[104:107], v[56:59], v[200:203], v[104:107]
	v_mfma_f32_16x16x32_bf16 v[92:95], v[48:51], v[208:211], v[92:95]
	v_mfma_f32_16x16x32_bf16 v[88:91], v[56:59], v[208:211], v[88:91]
	v_mfma_f32_16x16x32_bf16 v[140:143], v[52:55], v[188:191], v[140:143]
	v_mfma_f32_16x16x32_bf16 v[136:139], v[60:63], v[188:191], v[136:139]
	v_mfma_f32_16x16x32_bf16 v[124:127], v[52:55], v[196:199], v[124:127]
	v_mfma_f32_16x16x32_bf16 v[120:123], v[60:63], v[196:199], v[120:123]
	v_mfma_f32_16x16x32_bf16 v[108:111], v[52:55], v[204:207], v[108:111]
	v_mfma_f32_16x16x32_bf16 v[104:107], v[60:63], v[204:207], v[104:107]
	v_mfma_f32_16x16x32_bf16 v[92:95], v[52:55], v[220:223], v[92:95]
	v_mfma_f32_16x16x32_bf16 v[88:91], v[60:63], v[220:223], v[88:91]

	v_mfma_f32_16x16x32_bf16 v[132:135], v[168:171], v[184:187], v[132:135]
	v_mfma_f32_16x16x32_bf16 v[128:131], v[176:179], v[184:187], v[128:131]
	v_mfma_f32_16x16x32_bf16 v[116:119], v[168:171], v[192:195], v[116:119]
	v_mfma_f32_16x16x32_bf16 v[112:115], v[176:179], v[192:195], v[112:115]
	v_mfma_f32_16x16x32_bf16 v[100:103], v[168:171], v[200:203], v[100:103]
	v_mfma_f32_16x16x32_bf16 v[96:99], v[176:179], v[200:203], v[96:99]
	v_mfma_f32_16x16x32_bf16 v[84:87], v[168:171], v[208:211], v[84:87]
	v_mfma_f32_16x16x32_bf16 v[80:83], v[176:179], v[208:211], v[80:83]
	v_mfma_f32_16x16x32_bf16 v[132:135], v[172:175], v[188:191], v[132:135]
	v_mfma_f32_16x16x32_bf16 v[128:131], v[180:183], v[188:191], v[128:131]
	v_mfma_f32_16x16x32_bf16 v[116:119], v[172:175], v[196:199], v[116:119]
	v_mfma_f32_16x16x32_bf16 v[112:115], v[180:183], v[196:199], v[112:115]
	v_mfma_f32_16x16x32_bf16 v[100:103], v[172:175], v[204:207], v[100:103]
	v_mfma_f32_16x16x32_bf16 v[96:99], v[180:183], v[204:207], v[96:99]
	v_mfma_f32_16x16x32_bf16 v[84:87], v[172:175], v[220:223], v[84:87]
	v_mfma_f32_16x16x32_bf16 v[80:83], v[180:183], v[220:223], v[80:83]

	s_barrier
	s_add_i32 s90, s72, s61
	v_lshl_add_u64 v[212:213], s[4:5], 0, v[146:147]
	s_mov_b32 m0, s90
	ds_read_b128 v[184:187], v216 offset:16384
	ds_read_b128 v[188:191], v216 offset:17408
	ds_read_b128 v[192:195], v216 offset:18432
	ds_read_b128 v[196:199], v216 offset:19456
	ds_read_b128 v[200:203], v216 offset:20480
	ds_read_b128 v[204:207], v216 offset:21504
	ds_read_b128 v[208:211], v216 offset:22528
	ds_read_b128 v[220:223], v216 offset:23552
	global_load_lds_dwordx4 v[212:213], off
	s_add_i32 m0, s90, 0x2000
	s_add_u32 s90, s4, 0x40000
	v_lshl_add_u64 v[224:225], s[4:5], 0, v[150:151]
	s_addc_u32 s91, s5, 0
	s_add_i32 s93, s73, s61
	global_load_lds_dwordx4 v[224:225], off
	v_lshl_add_u64 v[226:227], s[90:91], 0, v[146:147]
	s_mov_b32 m0, s93
	v_lshl_add_u64 v[228:229], s[6:7], 0, v[148:149]
	global_load_lds_dwordx4 v[226:227], off
	v_lshl_add_u64 v[226:227], s[90:91], 0, v[150:151]
	s_add_i32 m0, s93, 0x2000
	s_nop 0
	global_load_lds_dwordx4 v[226:227], off
	v_lshl_add_u64 v[226:227], s[6:7], 0, v[144:145]
	s_mov_b32 m0, s68
	s_nop 0
	global_load_lds_dwordx4 v[226:227], off
	s_mov_b32 m0, s69
	s_nop 0
	global_load_lds_dwordx4 v[228:229], off
	s_waitcnt vmcnt(8)
	s_waitcnt lgkmcnt(0)
	s_barrier

	v_mfma_f32_16x16x32_bf16 v[76:79], v[48:51], v[184:187], v[76:79]
	v_mfma_f32_16x16x32_bf16 v[72:75], v[56:59], v[184:187], v[72:75]
	v_mfma_f32_16x16x32_bf16 v[44:47], v[48:51], v[192:195], v[44:47]
	v_mfma_f32_16x16x32_bf16 v[40:43], v[56:59], v[192:195], v[40:43]
	v_mfma_f32_16x16x32_bf16 v[28:31], v[48:51], v[200:203], v[28:31]
	v_mfma_f32_16x16x32_bf16 v[24:27], v[56:59], v[200:203], v[24:27]
	v_mfma_f32_16x16x32_bf16 v[12:15], v[48:51], v[208:211], v[12:15]
	v_mfma_f32_16x16x32_bf16 v[8:11], v[56:59], v[208:211], v[8:11]
	v_mfma_f32_16x16x32_bf16 v[76:79], v[52:55], v[188:191], v[76:79]
	v_mfma_f32_16x16x32_bf16 v[72:75], v[60:63], v[188:191], v[72:75]
	v_mfma_f32_16x16x32_bf16 v[44:47], v[52:55], v[196:199], v[44:47]
	v_mfma_f32_16x16x32_bf16 v[40:43], v[60:63], v[196:199], v[40:43]
	v_mfma_f32_16x16x32_bf16 v[28:31], v[52:55], v[204:207], v[28:31]
	v_mfma_f32_16x16x32_bf16 v[24:27], v[60:63], v[204:207], v[24:27]
	v_mfma_f32_16x16x32_bf16 v[12:15], v[52:55], v[220:223], v[12:15]
	v_mfma_f32_16x16x32_bf16 v[8:11], v[60:63], v[220:223], v[8:11]

	v_mfma_f32_16x16x32_bf16 v[36:39], v[168:171], v[192:195], v[36:39]
	v_mfma_f32_16x16x32_bf16 v[32:35], v[176:179], v[192:195], v[32:35]
	v_mfma_f32_16x16x32_bf16 v[20:23], v[168:171], v[200:203], v[20:23]
	v_mfma_f32_16x16x32_bf16 v[16:19], v[176:179], v[200:203], v[16:19]
	v_mfma_f32_16x16x32_bf16 v[4:7], v[168:171], v[208:211], v[4:7]
	v_mfma_f32_16x16x32_bf16 v[0:3], v[176:179], v[208:211], v[0:3]
	v_mfma_f32_16x16x32_bf16 v[48:51], v[168:171], v[184:187], v[68:71]
	v_mfma_f32_16x16x32_bf16 v[52:55], v[176:179], v[184:187], v[64:67]
	v_mfma_f32_16x16x32_bf16 v[36:39], v[172:175], v[196:199], v[36:39]
	v_mfma_f32_16x16x32_bf16 v[32:35], v[180:183], v[196:199], v[32:35]
	v_mfma_f32_16x16x32_bf16 v[20:23], v[172:175], v[204:207], v[20:23]
	v_mfma_f32_16x16x32_bf16 v[16:19], v[180:183], v[204:207], v[16:19]
	v_mfma_f32_16x16x32_bf16 v[4:7], v[172:175], v[220:223], v[4:7]
	v_mfma_f32_16x16x32_bf16 v[0:3], v[180:183], v[220:223], v[0:3]
	v_mfma_f32_16x16x32_bf16 v[48:51], v[172:175], v[188:191], v[48:51]
	v_mfma_f32_16x16x32_bf16 v[52:55], v[180:183], v[188:191], v[52:55]

	s_barrier
	s_add_i32 s90, 0, 0x18000
	s_add_i32 s91, 0, 0x1c000
	v_add_u32_e32 v68, s90, v167
	v_add_u32_e32 v154, s91, v167
	ds_read_b128 v[56:59], v68
	ds_read_b128 v[60:63], v68 offset:1024
	ds_read_b128 v[64:67], v68 offset:2048
	ds_read_b128 v[68:71], v68 offset:3072
	ds_read_b128 v[168:171], v154
	ds_read_b128 v[172:175], v154 offset:1024
	ds_read_b128 v[176:179], v154 offset:2048
	ds_read_b128 v[180:183], v154 offset:3072
	s_add_u32 s6, s6, 0x40000
	s_addc_u32 s7, s7, 0
	s_mov_b32 m0, s70
	v_lshl_add_u64 v[230:231], s[6:7], 0, v[144:145]
	ds_read_b128 v[184:187], v216 offset:32768
	ds_read_b128 v[188:191], v216 offset:33792
	ds_read_b128 v[192:195], v216 offset:34816
	ds_read_b128 v[196:199], v216 offset:35840
	ds_read_b128 v[200:203], v216 offset:36864
	ds_read_b128 v[204:207], v216 offset:37888
	ds_read_b128 v[208:211], v216 offset:38912
	ds_read_b128 v[220:223], v216 offset:39936
	global_load_lds_dwordx4 v[230:231], off
	v_lshl_add_u64 v[230:231], s[6:7], 0, v[148:149]
	s_mov_b32 m0, s77
	s_nop 0
	global_load_lds_dwordx4 v[230:231], off
	s_waitcnt vmcnt(8)
	s_waitcnt lgkmcnt(0)
	s_barrier

	v_mfma_f32_16x16x32_bf16 v[140:143], v[56:59], v[184:187], v[140:143]
	v_mfma_f32_16x16x32_bf16 v[136:139], v[64:67], v[184:187], v[136:139]
	v_mfma_f32_16x16x32_bf16 v[124:127], v[56:59], v[192:195], v[124:127]
	v_mfma_f32_16x16x32_bf16 v[120:123], v[64:67], v[192:195], v[120:123]
	v_mfma_f32_16x16x32_bf16 v[108:111], v[56:59], v[200:203], v[108:111]
	v_mfma_f32_16x16x32_bf16 v[104:107], v[64:67], v[200:203], v[104:107]
	v_mfma_f32_16x16x32_bf16 v[92:95], v[56:59], v[208:211], v[92:95]
	v_mfma_f32_16x16x32_bf16 v[88:91], v[64:67], v[208:211], v[88:91]
	v_mfma_f32_16x16x32_bf16 v[140:143], v[60:63], v[188:191], v[140:143]
	v_mfma_f32_16x16x32_bf16 v[136:139], v[68:71], v[188:191], v[136:139]
	v_mfma_f32_16x16x32_bf16 v[124:127], v[60:63], v[196:199], v[124:127]
	v_mfma_f32_16x16x32_bf16 v[120:123], v[68:71], v[196:199], v[120:123]
	v_mfma_f32_16x16x32_bf16 v[108:111], v[60:63], v[204:207], v[108:111]
	v_mfma_f32_16x16x32_bf16 v[104:107], v[68:71], v[204:207], v[104:107]
	v_mfma_f32_16x16x32_bf16 v[92:95], v[60:63], v[220:223], v[92:95]
	v_mfma_f32_16x16x32_bf16 v[88:91], v[68:71], v[220:223], v[88:91]

	v_mfma_f32_16x16x32_bf16 v[132:135], v[168:171], v[184:187], v[132:135]
	v_mfma_f32_16x16x32_bf16 v[128:131], v[176:179], v[184:187], v[128:131]
	v_mfma_f32_16x16x32_bf16 v[116:119], v[168:171], v[192:195], v[116:119]
	v_mfma_f32_16x16x32_bf16 v[112:115], v[176:179], v[192:195], v[112:115]
	v_mfma_f32_16x16x32_bf16 v[100:103], v[168:171], v[200:203], v[100:103]
	v_mfma_f32_16x16x32_bf16 v[96:99], v[176:179], v[200:203], v[96:99]
	v_mfma_f32_16x16x32_bf16 v[84:87], v[168:171], v[208:211], v[84:87]
	v_mfma_f32_16x16x32_bf16 v[80:83], v[176:179], v[208:211], v[80:83]
	v_mfma_f32_16x16x32_bf16 v[132:135], v[172:175], v[188:191], v[132:135]
	v_mfma_f32_16x16x32_bf16 v[128:131], v[180:183], v[188:191], v[128:131]
	v_mfma_f32_16x16x32_bf16 v[116:119], v[172:175], v[196:199], v[116:119]
	v_mfma_f32_16x16x32_bf16 v[112:115], v[180:183], v[196:199], v[112:115]
	v_mfma_f32_16x16x32_bf16 v[100:103], v[172:175], v[204:207], v[100:103]
	v_mfma_f32_16x16x32_bf16 v[96:99], v[180:183], v[204:207], v[96:99]
	v_mfma_f32_16x16x32_bf16 v[84:87], v[172:175], v[220:223], v[84:87]
	v_mfma_f32_16x16x32_bf16 v[80:83], v[180:183], v[220:223], v[80:83]

	s_barrier
	s_add_i32 s6, s90, s61
	v_lshl_add_u64 v[212:213], v[212:213], 0, s[56:57]
	s_mov_b32 m0, s6
	ds_read_b128 v[184:187], v216 offset:49152
	ds_read_b128 v[188:191], v216 offset:50176
	ds_read_b128 v[192:195], v216 offset:51200
	ds_read_b128 v[196:199], v216 offset:52224
	ds_read_b128 v[200:203], v216 offset:53248
	ds_read_b128 v[204:207], v216 offset:54272
	ds_read_b128 v[208:211], v216 offset:55296
	ds_read_b128 v[220:223], v216 offset:56320
	global_load_lds_dwordx4 v[212:213], off
	s_add_i32 m0, s6, 0x2000
	s_add_u32 s4, s4, 0x40080
	v_lshl_add_u64 v[212:213], v[224:225], 0, s[56:57]
	s_addc_u32 s5, s5, 0
	s_add_i32 s6, s91, s61
	global_load_lds_dwordx4 v[212:213], off
	v_lshl_add_u64 v[212:213], s[4:5], 0, v[146:147]
	s_mov_b32 m0, s6
	s_nop 0
	global_load_lds_dwordx4 v[212:213], off
	v_lshl_add_u64 v[212:213], s[4:5], 0, v[150:151]
	s_add_i32 m0, s6, 0x2000
	s_nop 0
	global_load_lds_dwordx4 v[212:213], off
	v_lshl_add_u64 v[212:213], v[226:227], 0, s[56:57]
	s_mov_b32 m0, s96
	s_nop 0
	global_load_lds_dwordx4 v[212:213], off
	v_lshl_add_u64 v[212:213], v[228:229], 0, s[56:57]
	s_mov_b32 m0, s71
	s_nop 0
	global_load_lds_dwordx4 v[212:213], off
	s_waitcnt vmcnt(8)
	s_waitcnt lgkmcnt(0)
	s_barrier

	v_mfma_f32_16x16x32_bf16 v[76:79], v[56:59], v[184:187], v[76:79]
	v_mfma_f32_16x16x32_bf16 v[72:75], v[64:67], v[184:187], v[72:75]
	v_mfma_f32_16x16x32_bf16 v[44:47], v[56:59], v[192:195], v[44:47]
	v_mfma_f32_16x16x32_bf16 v[40:43], v[64:67], v[192:195], v[40:43]
	v_mfma_f32_16x16x32_bf16 v[28:31], v[56:59], v[200:203], v[28:31]
	v_mfma_f32_16x16x32_bf16 v[24:27], v[64:67], v[200:203], v[24:27]
	v_mfma_f32_16x16x32_bf16 v[12:15], v[56:59], v[208:211], v[12:15]
	v_mfma_f32_16x16x32_bf16 v[8:11], v[64:67], v[208:211], v[8:11]
	v_mfma_f32_16x16x32_bf16 v[76:79], v[60:63], v[188:191], v[76:79]
	v_mfma_f32_16x16x32_bf16 v[72:75], v[68:71], v[188:191], v[72:75]
	v_mfma_f32_16x16x32_bf16 v[44:47], v[60:63], v[196:199], v[44:47]
	v_mfma_f32_16x16x32_bf16 v[40:43], v[68:71], v[196:199], v[40:43]
	v_mfma_f32_16x16x32_bf16 v[28:31], v[60:63], v[204:207], v[28:31]
	v_mfma_f32_16x16x32_bf16 v[24:27], v[68:71], v[204:207], v[24:27]
	v_mfma_f32_16x16x32_bf16 v[12:15], v[60:63], v[220:223], v[12:15]
	v_mfma_f32_16x16x32_bf16 v[8:11], v[68:71], v[220:223], v[8:11]

	v_mfma_f32_16x16x32_bf16 v[48:51], v[168:171], v[184:187], v[48:51]
	v_mfma_f32_16x16x32_bf16 v[68:71], v[172:175], v[188:191], v[48:51]
	v_mfma_f32_16x16x32_bf16 v[48:51], v[176:179], v[184:187], v[52:55]
	v_mfma_f32_16x16x32_bf16 v[36:39], v[168:171], v[192:195], v[36:39]
	v_mfma_f32_16x16x32_bf16 v[32:35], v[176:179], v[192:195], v[32:35]
	v_mfma_f32_16x16x32_bf16 v[20:23], v[168:171], v[200:203], v[20:23]
	v_mfma_f32_16x16x32_bf16 v[16:19], v[176:179], v[200:203], v[16:19]
	v_mfma_f32_16x16x32_bf16 v[4:7], v[168:171], v[208:211], v[4:7]
	v_mfma_f32_16x16x32_bf16 v[0:3], v[176:179], v[208:211], v[0:3]
	v_mfma_f32_16x16x32_bf16 v[64:67], v[180:183], v[188:191], v[48:51]
	v_mfma_f32_16x16x32_bf16 v[36:39], v[172:175], v[196:199], v[36:39]
	v_mfma_f32_16x16x32_bf16 v[32:35], v[180:183], v[196:199], v[32:35]
	v_mfma_f32_16x16x32_bf16 v[20:23], v[172:175], v[204:207], v[20:23]
	v_mfma_f32_16x16x32_bf16 v[16:19], v[180:183], v[204:207], v[16:19]
	v_mfma_f32_16x16x32_bf16 v[4:7], v[172:175], v[220:223], v[4:7]
	v_mfma_f32_16x16x32_bf16 v[0:3], v[180:183], v[220:223], v[0:3]

	s_barrier
	s_add_i32 s89, s89, 2
	s_add_u32 s2, s2, 0x100
	s_addc_u32 s3, s3, 0
	s_add_u32 s87, s87, 0x100
	s_addc_u32 s88, s88, 0
	s_cmp_gt_u32 s89, 13
	s_cbranch_scc0 .LBB0_150
	s_and_b64 vcc, exec, s[58:59]
	s_cbranch_vccz .LBB0_153
	s_barrier

.LBB0_741:
	ds_read_b128 v[128:131], v187
	ds_read_b128 v[132:135], v187 offset:1024
	ds_read_b128 v[136:139], v187 offset:2048
	ds_read_b128 v[140:143], v187 offset:3072
	ds_read_b128 v[144:147], v188
	ds_read_b128 v[148:151], v188 offset:1024
	ds_read_b128 v[168:171], v188 offset:2048
	ds_read_b128 v[172:175], v188 offset:3072
	s_add_u32 s58, s52, 0xfffc0080
	s_addc_u32 s59, s53, -1
	s_cmp_eq_u32 s83, 12
	s_cselect_b32 s61, s6, s59
	s_cselect_b32 s60, s11, s58
	s_cselect_b32 s59, s13, s82
	s_cselect_b32 s58, s80, s81
	v_lshl_add_u64 v[216:217], s[52:53], 0, v[160:161]
	s_add_i32 m0, s62, 0xc000
	ds_read_b128 v[176:179], v189
	ds_read_b128 v[180:183], v189 offset:1024
	ds_read_b128 v[192:195], v189 offset:2048
	ds_read_b128 v[196:199], v189 offset:3072
	ds_read_b128 v[200:203], v189 offset:4096
	ds_read_b128 v[204:207], v189 offset:5120
	ds_read_b128 v[208:211], v189 offset:6144
	ds_read_b128 v[212:215], v189 offset:7168
	global_load_lds_dwordx4 v[216:217], off
	v_lshl_add_u64 v[216:217], s[52:53], 0, v[162:163]
	s_add_i32 m0, s62, 0xe000
	s_nop 0
	global_load_lds_dwordx4 v[216:217], off
	s_waitcnt vmcnt(8)
	s_waitcnt lgkmcnt(0)
	s_barrier

	v_mfma_f32_16x16x32_bf16 v[124:127], v[128:131], v[176:179], v[124:127]
	v_mfma_f32_16x16x32_bf16 v[120:123], v[136:139], v[176:179], v[120:123]
	v_mfma_f32_16x16x32_bf16 v[108:111], v[128:131], v[192:195], v[108:111]
	v_mfma_f32_16x16x32_bf16 v[104:107], v[136:139], v[192:195], v[104:107]
	v_mfma_f32_16x16x32_bf16 v[92:95], v[128:131], v[200:203], v[92:95]
	v_mfma_f32_16x16x32_bf16 v[88:91], v[136:139], v[200:203], v[88:91]
	v_mfma_f32_16x16x32_bf16 v[76:79], v[128:131], v[208:211], v[76:79]
	v_mfma_f32_16x16x32_bf16 v[72:75], v[136:139], v[208:211], v[72:75]
	v_mfma_f32_16x16x32_bf16 v[124:127], v[132:135], v[180:183], v[124:127]
	v_mfma_f32_16x16x32_bf16 v[120:123], v[140:143], v[180:183], v[120:123]
	v_mfma_f32_16x16x32_bf16 v[108:111], v[132:135], v[196:199], v[108:111]
	v_mfma_f32_16x16x32_bf16 v[104:107], v[140:143], v[196:199], v[104:107]
	v_mfma_f32_16x16x32_bf16 v[92:95], v[132:135], v[204:207], v[92:95]
	v_mfma_f32_16x16x32_bf16 v[88:91], v[140:143], v[204:207], v[88:91]
	v_mfma_f32_16x16x32_bf16 v[76:79], v[132:135], v[212:215], v[76:79]
	v_mfma_f32_16x16x32_bf16 v[72:75], v[140:143], v[212:215], v[72:75]

	v_mfma_f32_16x16x32_bf16 v[116:119], v[144:147], v[176:179], v[116:119]
	v_mfma_f32_16x16x32_bf16 v[112:115], v[168:171], v[176:179], v[112:115]
	v_mfma_f32_16x16x32_bf16 v[100:103], v[144:147], v[192:195], v[100:103]
	v_mfma_f32_16x16x32_bf16 v[96:99], v[168:171], v[192:195], v[96:99]
	v_mfma_f32_16x16x32_bf16 v[84:87], v[144:147], v[200:203], v[84:87]
	v_mfma_f32_16x16x32_bf16 v[80:83], v[168:171], v[200:203], v[80:83]
	v_mfma_f32_16x16x32_bf16 v[68:71], v[144:147], v[208:211], v[68:71]
	v_mfma_f32_16x16x32_bf16 v[64:67], v[168:171], v[208:211], v[64:67]
	v_mfma_f32_16x16x32_bf16 v[116:119], v[148:151], v[180:183], v[116:119]
	v_mfma_f32_16x16x32_bf16 v[112:115], v[172:175], v[180:183], v[112:115]
	v_mfma_f32_16x16x32_bf16 v[100:103], v[148:151], v[196:199], v[100:103]
	v_mfma_f32_16x16x32_bf16 v[96:99], v[172:175], v[196:199], v[96:99]
	v_mfma_f32_16x16x32_bf16 v[84:87], v[148:151], v[204:207], v[84:87]
	v_mfma_f32_16x16x32_bf16 v[80:83], v[172:175], v[204:207], v[80:83]
	v_mfma_f32_16x16x32_bf16 v[68:71], v[148:151], v[212:215], v[68:71]
	v_mfma_f32_16x16x32_bf16 v[64:67], v[172:175], v[212:215], v[64:67]

	s_barrier
	s_add_i32 s84, s71, s57
	v_lshl_add_u64 v[216:217], s[58:59], 0, v[154:155]
	s_mov_b32 m0, s84
	ds_read_b128 v[176:179], v189 offset:16384
	ds_read_b128 v[180:183], v189 offset:17408
	ds_read_b128 v[192:195], v189 offset:18432
	ds_read_b128 v[196:199], v189 offset:19456
	ds_read_b128 v[200:203], v189 offset:20480
	ds_read_b128 v[204:207], v189 offset:21504
	ds_read_b128 v[208:211], v189 offset:22528
	ds_read_b128 v[212:215], v189 offset:23552
	global_load_lds_dwordx4 v[216:217], off
	s_add_i32 m0, s84, 0x2000
	s_add_u32 s84, s58, 0x40000
	v_lshl_add_u64 v[218:219], s[58:59], 0, v[158:159]
	s_addc_u32 s85, s59, 0
	s_add_i32 s86, s72, s57
	global_load_lds_dwordx4 v[218:219], off
	v_lshl_add_u64 v[220:221], s[84:85], 0, v[154:155]
	s_mov_b32 m0, s86
	v_lshl_add_u64 v[222:223], s[60:61], 0, v[156:157]
	global_load_lds_dwordx4 v[220:221], off
	v_lshl_add_u64 v[220:221], s[84:85], 0, v[158:159]
	s_add_i32 m0, s86, 0x2000
	s_nop 0
	global_load_lds_dwordx4 v[220:221], off
	v_lshl_add_u64 v[220:221], s[60:61], 0, v[152:153]
	s_mov_b32 m0, s62
	s_nop 0
	global_load_lds_dwordx4 v[220:221], off
	s_mov_b32 m0, s63
	s_nop 0
	global_load_lds_dwordx4 v[222:223], off
	s_waitcnt vmcnt(8)
	s_waitcnt lgkmcnt(0)
	s_barrier

	v_mfma_f32_16x16x32_bf16 v[60:63], v[128:131], v[176:179], v[60:63]
	v_mfma_f32_16x16x32_bf16 v[56:59], v[136:139], v[176:179], v[56:59]
	v_mfma_f32_16x16x32_bf16 v[44:47], v[128:131], v[192:195], v[44:47]
	v_mfma_f32_16x16x32_bf16 v[40:43], v[136:139], v[192:195], v[40:43]
	v_mfma_f32_16x16x32_bf16 v[28:31], v[128:131], v[200:203], v[28:31]
	v_mfma_f32_16x16x32_bf16 v[24:27], v[136:139], v[200:203], v[24:27]
	v_mfma_f32_16x16x32_bf16 v[12:15], v[128:131], v[208:211], v[12:15]
	v_mfma_f32_16x16x32_bf16 v[8:11], v[136:139], v[208:211], v[8:11]
	v_mfma_f32_16x16x32_bf16 v[60:63], v[132:135], v[180:183], v[60:63]
	v_mfma_f32_16x16x32_bf16 v[56:59], v[140:143], v[180:183], v[56:59]
	v_mfma_f32_16x16x32_bf16 v[44:47], v[132:135], v[196:199], v[44:47]
	v_mfma_f32_16x16x32_bf16 v[40:43], v[140:143], v[196:199], v[40:43]
	v_mfma_f32_16x16x32_bf16 v[28:31], v[132:135], v[204:207], v[28:31]
	v_mfma_f32_16x16x32_bf16 v[24:27], v[140:143], v[204:207], v[24:27]
	v_mfma_f32_16x16x32_bf16 v[12:15], v[132:135], v[212:215], v[12:15]
	v_mfma_f32_16x16x32_bf16 v[8:11], v[140:143], v[212:215], v[8:11]

	v_mfma_f32_16x16x32_bf16 v[52:55], v[144:147], v[176:179], v[52:55]
	v_mfma_f32_16x16x32_bf16 v[48:51], v[168:171], v[176:179], v[48:51]
	v_mfma_f32_16x16x32_bf16 v[36:39], v[144:147], v[192:195], v[36:39]
	v_mfma_f32_16x16x32_bf16 v[32:35], v[168:171], v[192:195], v[32:35]
	v_mfma_f32_16x16x32_bf16 v[20:23], v[144:147], v[200:203], v[20:23]
	v_mfma_f32_16x16x32_bf16 v[16:19], v[168:171], v[200:203], v[16:19]
	v_mfma_f32_16x16x32_bf16 v[4:7], v[144:147], v[208:211], v[4:7]
	v_mfma_f32_16x16x32_bf16 v[0:3], v[168:171], v[208:211], v[0:3]
	v_mfma_f32_16x16x32_bf16 v[52:55], v[148:151], v[180:183], v[52:55]
	v_mfma_f32_16x16x32_bf16 v[48:51], v[172:175], v[180:183], v[48:51]
	v_mfma_f32_16x16x32_bf16 v[36:39], v[148:151], v[196:199], v[36:39]
	v_mfma_f32_16x16x32_bf16 v[32:35], v[172:175], v[196:199], v[32:35]
	v_mfma_f32_16x16x32_bf16 v[20:23], v[148:151], v[204:207], v[20:23]
	v_mfma_f32_16x16x32_bf16 v[16:19], v[172:175], v[204:207], v[16:19]
	v_mfma_f32_16x16x32_bf16 v[4:7], v[148:151], v[212:215], v[4:7]
	v_mfma_f32_16x16x32_bf16 v[0:3], v[172:175], v[212:215], v[0:3]

	s_barrier
	s_add_i32 s84, 0, 0x18000
	s_add_i32 s85, 0, 0x1c000
	v_add_u32_e32 v140, s84, v185
	v_add_u32_e32 v172, s85, v185
	ds_read_b128 v[128:131], v140
	ds_read_b128 v[132:135], v140 offset:1024
	ds_read_b128 v[136:139], v140 offset:2048
	ds_read_b128 v[140:143], v140 offset:3072
	ds_read_b128 v[144:147], v172
	ds_read_b128 v[148:151], v172 offset:1024
	ds_read_b128 v[168:171], v172 offset:2048
	ds_read_b128 v[172:175], v172 offset:3072
	s_add_u32 s60, s60, 0x40000
	s_addc_u32 s61, s61, 0
	s_mov_b32 m0, s64
	v_lshl_add_u64 v[224:225], s[60:61], 0, v[152:153]
	ds_read_b128 v[176:179], v189 offset:32768
	ds_read_b128 v[180:183], v189 offset:33792
	ds_read_b128 v[192:195], v189 offset:34816
	ds_read_b128 v[196:199], v189 offset:35840
	ds_read_b128 v[200:203], v189 offset:36864
	ds_read_b128 v[204:207], v189 offset:37888
	ds_read_b128 v[208:211], v189 offset:38912
	ds_read_b128 v[212:215], v189 offset:39936
	global_load_lds_dwordx4 v[224:225], off
	v_lshl_add_u64 v[224:225], s[60:61], 0, v[156:157]
	s_mov_b32 m0, s65
	s_nop 0
	global_load_lds_dwordx4 v[224:225], off
	s_waitcnt vmcnt(8)
	s_waitcnt lgkmcnt(0)
	s_barrier

	v_mfma_f32_16x16x32_bf16 v[124:127], v[128:131], v[176:179], v[124:127]
	v_mfma_f32_16x16x32_bf16 v[120:123], v[136:139], v[176:179], v[120:123]
	v_mfma_f32_16x16x32_bf16 v[108:111], v[128:131], v[192:195], v[108:111]
	v_mfma_f32_16x16x32_bf16 v[104:107], v[136:139], v[192:195], v[104:107]
	v_mfma_f32_16x16x32_bf16 v[92:95], v[128:131], v[200:203], v[92:95]
	v_mfma_f32_16x16x32_bf16 v[88:91], v[136:139], v[200:203], v[88:91]
	v_mfma_f32_16x16x32_bf16 v[76:79], v[128:131], v[208:211], v[76:79]
	v_mfma_f32_16x16x32_bf16 v[72:75], v[136:139], v[208:211], v[72:75]
	v_mfma_f32_16x16x32_bf16 v[124:127], v[132:135], v[180:183], v[124:127]
	v_mfma_f32_16x16x32_bf16 v[120:123], v[140:143], v[180:183], v[120:123]
	v_mfma_f32_16x16x32_bf16 v[108:111], v[132:135], v[196:199], v[108:111]
	v_mfma_f32_16x16x32_bf16 v[104:107], v[140:143], v[196:199], v[104:107]
	v_mfma_f32_16x16x32_bf16 v[92:95], v[132:135], v[204:207], v[92:95]
	v_mfma_f32_16x16x32_bf16 v[88:91], v[140:143], v[204:207], v[88:91]
	v_mfma_f32_16x16x32_bf16 v[76:79], v[132:135], v[212:215], v[76:79]
	v_mfma_f32_16x16x32_bf16 v[72:75], v[140:143], v[212:215], v[72:75]

	v_mfma_f32_16x16x32_bf16 v[116:119], v[144:147], v[176:179], v[116:119]
	v_mfma_f32_16x16x32_bf16 v[112:115], v[168:171], v[176:179], v[112:115]
	v_mfma_f32_16x16x32_bf16 v[100:103], v[144:147], v[192:195], v[100:103]
	v_mfma_f32_16x16x32_bf16 v[96:99], v[168:171], v[192:195], v[96:99]
	v_mfma_f32_16x16x32_bf16 v[84:87], v[144:147], v[200:203], v[84:87]
	v_mfma_f32_16x16x32_bf16 v[80:83], v[168:171], v[200:203], v[80:83]
	v_mfma_f32_16x16x32_bf16 v[68:71], v[144:147], v[208:211], v[68:71]
	v_mfma_f32_16x16x32_bf16 v[64:67], v[168:171], v[208:211], v[64:67]
	v_mfma_f32_16x16x32_bf16 v[116:119], v[148:151], v[180:183], v[116:119]
	v_mfma_f32_16x16x32_bf16 v[112:115], v[172:175], v[180:183], v[112:115]
	v_mfma_f32_16x16x32_bf16 v[100:103], v[148:151], v[196:199], v[100:103]
	v_mfma_f32_16x16x32_bf16 v[96:99], v[172:175], v[196:199], v[96:99]
	v_mfma_f32_16x16x32_bf16 v[84:87], v[148:151], v[204:207], v[84:87]
	v_mfma_f32_16x16x32_bf16 v[80:83], v[172:175], v[204:207], v[80:83]
	v_mfma_f32_16x16x32_bf16 v[68:71], v[148:151], v[212:215], v[68:71]
	v_mfma_f32_16x16x32_bf16 v[64:67], v[172:175], v[212:215], v[64:67]

	s_barrier
	s_add_i32 s60, s84, s57
	v_lshl_add_u64 v[216:217], v[216:217], 0, s[8:9]
	s_mov_b32 m0, s60
	ds_read_b128 v[176:179], v189 offset:49152
	ds_read_b128 v[180:183], v189 offset:50176
	ds_read_b128 v[192:195], v189 offset:51200
	ds_read_b128 v[196:199], v189 offset:52224
	ds_read_b128 v[200:203], v189 offset:53248
	ds_read_b128 v[204:207], v189 offset:54272
	ds_read_b128 v[208:211], v189 offset:55296
	ds_read_b128 v[212:215], v189 offset:56320
	global_load_lds_dwordx4 v[216:217], off
	s_add_i32 m0, s60, 0x2000
	s_add_u32 s58, s58, 0x40080
	v_lshl_add_u64 v[216:217], v[218:219], 0, s[8:9]
	s_addc_u32 s59, s59, 0
	s_add_i32 s60, s85, s57
	global_load_lds_dwordx4 v[216:217], off
	v_lshl_add_u64 v[216:217], s[58:59], 0, v[154:155]
	s_mov_b32 m0, s60
	s_nop 0
	global_load_lds_dwordx4 v[216:217], off
	v_lshl_add_u64 v[216:217], s[58:59], 0, v[158:159]
	s_add_i32 m0, s60, 0x2000
	s_nop 0
	global_load_lds_dwordx4 v[216:217], off
	v_lshl_add_u64 v[216:217], v[220:221], 0, s[8:9]
	s_mov_b32 m0, s67
	s_nop 0
	global_load_lds_dwordx4 v[216:217], off
	v_lshl_add_u64 v[216:217], v[222:223], 0, s[8:9]
	s_mov_b32 m0, s68
	s_nop 0
	global_load_lds_dwordx4 v[216:217], off
	s_waitcnt vmcnt(8)
	s_waitcnt lgkmcnt(0)
	s_barrier

	v_mfma_f32_16x16x32_bf16 v[60:63], v[128:131], v[176:179], v[60:63]
	v_mfma_f32_16x16x32_bf16 v[56:59], v[136:139], v[176:179], v[56:59]
	v_mfma_f32_16x16x32_bf16 v[44:47], v[128:131], v[192:195], v[44:47]
	v_mfma_f32_16x16x32_bf16 v[40:43], v[136:139], v[192:195], v[40:43]
	v_mfma_f32_16x16x32_bf16 v[28:31], v[128:131], v[200:203], v[28:31]
	v_mfma_f32_16x16x32_bf16 v[24:27], v[136:139], v[200:203], v[24:27]
	v_mfma_f32_16x16x32_bf16 v[12:15], v[128:131], v[208:211], v[12:15]
	v_mfma_f32_16x16x32_bf16 v[8:11], v[136:139], v[208:211], v[8:11]
	v_mfma_f32_16x16x32_bf16 v[60:63], v[132:135], v[180:183], v[60:63]
	v_mfma_f32_16x16x32_bf16 v[56:59], v[140:143], v[180:183], v[56:59]
	v_mfma_f32_16x16x32_bf16 v[44:47], v[132:135], v[196:199], v[44:47]
	v_mfma_f32_16x16x32_bf16 v[40:43], v[140:143], v[196:199], v[40:43]
	v_mfma_f32_16x16x32_bf16 v[28:31], v[132:135], v[204:207], v[28:31]
	v_mfma_f32_16x16x32_bf16 v[24:27], v[140:143], v[204:207], v[24:27]
	v_mfma_f32_16x16x32_bf16 v[12:15], v[132:135], v[212:215], v[12:15]
	v_mfma_f32_16x16x32_bf16 v[8:11], v[140:143], v[212:215], v[8:11]

	v_mfma_f32_16x16x32_bf16 v[52:55], v[144:147], v[176:179], v[52:55]
	v_mfma_f32_16x16x32_bf16 v[48:51], v[168:171], v[176:179], v[48:51]
	v_mfma_f32_16x16x32_bf16 v[36:39], v[144:147], v[192:195], v[36:39]
	v_mfma_f32_16x16x32_bf16 v[32:35], v[168:171], v[192:195], v[32:35]
	v_mfma_f32_16x16x32_bf16 v[20:23], v[144:147], v[200:203], v[20:23]
	v_mfma_f32_16x16x32_bf16 v[16:19], v[168:171], v[200:203], v[16:19]
	v_mfma_f32_16x16x32_bf16 v[4:7], v[144:147], v[208:211], v[4:7]
	v_mfma_f32_16x16x32_bf16 v[0:3], v[168:171], v[208:211], v[0:3]
	v_mfma_f32_16x16x32_bf16 v[52:55], v[148:151], v[180:183], v[52:55]
	v_mfma_f32_16x16x32_bf16 v[48:51], v[172:175], v[180:183], v[48:51]
	v_mfma_f32_16x16x32_bf16 v[36:39], v[148:151], v[196:199], v[36:39]
	v_mfma_f32_16x16x32_bf16 v[32:35], v[172:175], v[196:199], v[32:35]
	v_mfma_f32_16x16x32_bf16 v[20:23], v[148:151], v[204:207], v[20:23]
	v_mfma_f32_16x16x32_bf16 v[16:19], v[172:175], v[204:207], v[16:19]
	v_mfma_f32_16x16x32_bf16 v[4:7], v[148:151], v[212:215], v[4:7]
	v_mfma_f32_16x16x32_bf16 v[0:3], v[172:175], v[212:215], v[0:3]

	s_barrier
	s_add_i32 s83, s83, 2
	s_add_u32 s52, s52, 0x100
	s_addc_u32 s53, s53, 0
	s_add_u32 s81, s81, 0x100
	s_addc_u32 s82, s82, 0
	s_cmp_gt_u32 s83, 13
	s_cbranch_scc0 .LBB0_741
	v_lshl_add_u32 v168, s79, 8, v184
	v_lshl_or_b32 v128, s78, 8, v186
	v_ashrrev_i32_e32 v169, 31, v168
	v_ashrrev_i32_e32 v129, 31, v128
	v_lshlrev_b64 v[130:131], 11, v[168:169]
	v_lshl_add_u64 v[130:131], s[34:35], 0, v[130:131]
	v_lshlrev_b64 v[170:171], 1, v[128:129]
	v_lshl_add_u64 v[200:201], v[130:131], 0, v[170:171]
	global_load_dwordx4 v[192:195], v[200:201], off
	global_load_dwordx4 v[196:199], v[200:201], off offset:256
	v_or_b32_e32 v180, 16, v168
	v_or_b32_e32 v176, 32, v168
	v_or_b32_e32 v172, 48, v168
	v_ashrrev_i32_e32 v181, 31, v180
	v_ashrrev_i32_e32 v177, 31, v176
	v_ashrrev_i32_e32 v173, 31, v172
	v_lshlrev_b64 v[128:129], 11, v[180:181]
	v_lshlrev_b64 v[130:131], 11, v[176:177]
	v_lshlrev_b64 v[132:133], 11, v[172:173]
	v_lshl_add_u64 v[128:129], s[34:35], 0, v[128:129]
	v_lshl_add_u64 v[130:131], s[34:35], 0, v[130:131]
	v_lshl_add_u64 v[132:133], s[34:35], 0, v[132:133]
	v_lshl_add_u64 v[182:183], v[128:129], 0, v[170:171]
	v_lshl_add_u64 v[178:179], v[130:131], 0, v[170:171]
	v_lshl_add_u64 v[174:175], v[132:133], 0, v[170:171]
	global_load_dwordx4 v[148:151], v[182:183], off
	global_load_dwordx4 v[144:147], v[182:183], off offset:256
	global_load_dwordx4 v[140:143], v[178:179], off
	global_load_dwordx4 v[136:139], v[178:179], off offset:256
	global_load_dwordx4 v[132:135], v[174:175], off
	global_load_dwordx4 v[128:131], v[174:175], off offset:256
	v_and_b32_e32 v202, 64, v190
	v_xor_b32_e32 v191, 16, v190
	v_add_u32_e32 v202, 64, v202
	v_xor_b32_e32 v203, 32, v190
	v_cmp_lt_i32_e32 vcc, v191, v202
	s_lshl_b32 s52, s78, 2
	s_ashr_i32 s53, s52, 31
	v_cndmask_b32_e32 v191, v190, v191, vcc
	v_cmp_lt_i32_e32 vcc, v203, v202
	v_lshlrev_b32_e32 v191, 2, v191
	s_waitcnt vmcnt(0)
	v_lshlrev_b32_e32 v202, 16, v192
	v_cndmask_b32_e32 v210, v190, v203, vcc
	v_and_b32_e32 v203, 0xffff0000, v192
	v_lshlrev_b32_e32 v192, 16, v193
	v_and_b32_e32 v193, 0xffff0000, v193
	v_lshlrev_b32_e32 v204, 16, v194
	v_and_b32_e32 v205, 0xffff0000, v194
	v_lshlrev_b32_e32 v194, 16, v195
	v_and_b32_e32 v195, 0xffff0000, v195
	v_lshlrev_b32_e32 v206, 16, v196
	v_and_b32_e32 v207, 0xffff0000, v196
	v_lshlrev_b32_e32 v196, 16, v197
	v_and_b32_e32 v197, 0xffff0000, v197
	v_lshlrev_b32_e32 v208, 16, v198
	v_and_b32_e32 v209, 0xffff0000, v198
	v_lshlrev_b32_e32 v198, 16, v199
	v_and_b32_e32 v199, 0xffff0000, v199
	v_pk_add_f32 v[126:127], v[126:127], v[192:193]
	v_pk_add_f32 v[124:125], v[124:125], v[202:203]
	v_pk_add_f32 v[122:123], v[122:123], v[194:195]
	v_pk_add_f32 v[120:121], v[120:121], v[204:205]
	v_pk_add_f32 v[118:119], v[118:119], v[196:197]
	v_pk_add_f32 v[116:117], v[116:117], v[206:207]
	v_pk_add_f32 v[192:193], v[114:115], v[198:199]
	v_pk_add_f32 v[194:195], v[112:113], v[208:209]
	v_cvt_pk_bf16_f32 v112, v124, v125
	v_cvt_pk_bf16_f32 v113, v126, v127
	v_mul_f32_e32 v114, v125, v125
	v_mul_f32_e32 v115, v127, v127
	v_mul_f32_e32 v125, v121, v121
	v_mul_f32_e32 v127, v123, v123
	v_mul_f32_e32 v196, v117, v117
	v_mul_f32_e32 v197, v119, v119
	v_mul_f32_e32 v198, v195, v195
	v_mul_f32_e32 v199, v193, v193
	v_fmac_f32_e32 v114, v124, v124
	v_fmac_f32_e32 v115, v126, v126
	v_fmac_f32_e32 v125, v120, v120
	v_fmac_f32_e32 v127, v122, v122
	v_fmac_f32_e32 v196, v116, v116
	v_fmac_f32_e32 v197, v118, v118
	v_fmac_f32_e32 v198, v194, v194
	v_fmac_f32_e32 v199, v192, v192
	v_add_f32_e32 v114, v114, v115
	v_add_f32_e32 v115, v125, v127
	v_add_f32_e32 v124, v196, v197
	v_add_f32_e32 v125, v198, v199
	v_add_f32_e32 v114, v114, v115
	v_add_f32_e32 v115, v124, v125
	v_add_f32_e32 v124, v114, v115
	ds_bpermute_b32 v125, v191, v124
	v_cvt_pk_bf16_f32 v114, v120, v121
	v_cvt_pk_bf16_f32 v115, v122, v123
	global_store_dwordx4 v[200:201], v[112:115], off
	v_cvt_pk_bf16_f32 v116, v116, v117
	v_cvt_pk_bf16_f32 v117, v118, v119
	s_waitcnt lgkmcnt(0)
	v_add_f32_e32 v113, v124, v125
	v_lshlrev_b32_e32 v112, 2, v210
	ds_bpermute_b32 v114, v112, v113
	v_cvt_pk_bf16_f32 v118, v194, v195
	v_cvt_pk_bf16_f32 v119, v192, v193
	global_store_dwordx4 v[200:201], v[116:119], off offset:256
	s_and_saveexec_b64 s[58:59], s[0:1]
	s_cbranch_execz .LBB0_744
	s_waitcnt lgkmcnt(0)
	v_add_f32_e32 v113, v113, v114
	v_lshlrev_b64 v[114:115], 6, v[168:169]
	v_lshl_add_u64 v[114:115], s[74:75], 0, v[114:115]
	v_lshl_add_u64 v[114:115], s[52:53], 2, v[114:115]
	s_lshl_b32 s6, s66, 2
	v_lshl_add_u64 v[114:115], v[114:115], 0, s[6:7]
	global_store_dword v[114:115], v113, off

.LBB0_876:
	ds_read_b128 v[96:99], v182
	ds_read_b128 v[100:103], v182 offset:1024
	ds_read_b128 v[104:107], v182 offset:2048
	ds_read_b128 v[108:111], v182 offset:3072
	ds_read_b128 v[112:115], v183
	ds_read_b128 v[116:119], v183 offset:1024
	ds_read_b128 v[120:123], v183 offset:2048
	ds_read_b128 v[124:127], v183 offset:3072
	s_add_u32 s88, s86, 0xfff80080
	s_addc_u32 s89, s87, -1
	s_cmp_eq_u32 s68, 12
	s_cselect_b32 s91, s3, s5
	s_cselect_b32 s90, s61, s4
	s_cselect_b32 s89, s65, s89
	s_cselect_b32 s88, s73, s88
	v_lshl_add_u64 v[168:169], s[86:87], 0, v[142:143]
	s_add_i32 m0, s41, 0xc000
	ds_read_b128 v[128:131], v184
	ds_read_b128 v[150:153], v184 offset:1024
	ds_read_b128 v[154:157], v184 offset:2048
	ds_read_b128 v[158:161], v184 offset:3072
	ds_read_b128 v[162:165], v184 offset:4096
	ds_read_b128 v[176:179], v184 offset:5120
	ds_read_b128 v[188:191], v184 offset:6144
	ds_read_b128 v[192:195], v184 offset:7168
	global_load_lds_dwordx4 v[168:169], off
	v_lshl_add_u64 v[168:169], s[86:87], 0, v[144:145]
	s_add_i32 m0, s41, 0xe000
	s_nop 0
	global_load_lds_dwordx4 v[168:169], off
	s_waitcnt vmcnt(8)
	s_waitcnt lgkmcnt(0)
	s_barrier

	v_mfma_f32_16x16x32_bf16 v[92:95], v[96:99], v[128:131], v[92:95]
	v_mfma_f32_16x16x32_bf16 v[88:91], v[104:107], v[128:131], v[88:91]
	v_mfma_f32_16x16x32_bf16 v[84:87], v[96:99], v[154:157], v[84:87]
	v_mfma_f32_16x16x32_bf16 v[80:83], v[104:107], v[154:157], v[80:83]
	v_mfma_f32_16x16x32_bf16 v[68:71], v[96:99], v[162:165], v[68:71]
	v_mfma_f32_16x16x32_bf16 v[64:67], v[104:107], v[162:165], v[64:67]
	v_mfma_f32_16x16x32_bf16 v[52:55], v[96:99], v[188:191], v[52:55]
	v_mfma_f32_16x16x32_bf16 v[48:51], v[104:107], v[188:191], v[48:51]
	v_mfma_f32_16x16x32_bf16 v[92:95], v[100:103], v[150:153], v[92:95]
	v_mfma_f32_16x16x32_bf16 v[88:91], v[108:111], v[150:153], v[88:91]
	v_mfma_f32_16x16x32_bf16 v[84:87], v[100:103], v[158:161], v[84:87]
	v_mfma_f32_16x16x32_bf16 v[80:83], v[108:111], v[158:161], v[80:83]
	v_mfma_f32_16x16x32_bf16 v[68:71], v[100:103], v[176:179], v[68:71]
	v_mfma_f32_16x16x32_bf16 v[64:67], v[108:111], v[176:179], v[64:67]
	v_mfma_f32_16x16x32_bf16 v[52:55], v[100:103], v[192:195], v[52:55]
	v_mfma_f32_16x16x32_bf16 v[48:51], v[108:111], v[192:195], v[48:51]

	v_mfma_f32_16x16x32_bf16 v[76:79], v[112:115], v[128:131], v[76:79]
	v_mfma_f32_16x16x32_bf16 v[72:75], v[120:123], v[128:131], v[72:75]
	v_mfma_f32_16x16x32_bf16 v[60:63], v[112:115], v[154:157], v[60:63]
	v_mfma_f32_16x16x32_bf16 v[56:59], v[120:123], v[154:157], v[56:59]
	v_mfma_f32_16x16x32_bf16 v[44:47], v[112:115], v[162:165], v[44:47]
	v_mfma_f32_16x16x32_bf16 v[40:43], v[120:123], v[162:165], v[40:43]
	v_mfma_f32_16x16x32_bf16 v[36:39], v[112:115], v[188:191], v[36:39]
	v_mfma_f32_16x16x32_bf16 v[32:35], v[120:123], v[188:191], v[32:35]
	v_mfma_f32_16x16x32_bf16 v[76:79], v[116:119], v[150:153], v[76:79]
	v_mfma_f32_16x16x32_bf16 v[72:75], v[124:127], v[150:153], v[72:75]
	v_mfma_f32_16x16x32_bf16 v[60:63], v[116:119], v[158:161], v[60:63]
	v_mfma_f32_16x16x32_bf16 v[56:59], v[124:127], v[158:161], v[56:59]
	v_mfma_f32_16x16x32_bf16 v[44:47], v[116:119], v[176:179], v[44:47]
	v_mfma_f32_16x16x32_bf16 v[40:43], v[124:127], v[176:179], v[40:43]
	v_mfma_f32_16x16x32_bf16 v[36:39], v[116:119], v[192:195], v[36:39]
	v_mfma_f32_16x16x32_bf16 v[32:35], v[124:127], v[192:195], v[32:35]

	s_barrier
	s_add_i32 s92, s76, s15
	v_lshl_add_u64 v[168:169], s[88:89], 0, v[134:135]
	s_mov_b32 m0, s92
	ds_read_b128 v[96:99], v185 offset:16384
	ds_read_b128 v[100:103], v185 offset:17408
	ds_read_b128 v[104:107], v185 offset:18432
	ds_read_b128 v[108:111], v185 offset:19456
	global_load_lds_dwordx4 v[168:169], off
	s_add_i32 m0, s92, 0x2000
	s_add_u32 s92, s88, 0x40000
	v_lshl_add_u64 v[172:173], s[88:89], 0, v[138:139]
	s_addc_u32 s93, s89, 0
	s_add_i32 vcc_lo, s77, s15
	global_load_lds_dwordx4 v[172:173], off
	v_lshl_add_u64 v[112:113], s[92:93], 0, v[134:135]
	s_mov_b32 m0, vcc_lo
	v_lshl_add_u64 v[180:181], s[90:91], 0, v[132:133]
	global_load_lds_dwordx4 v[112:113], off
	v_lshl_add_u64 v[112:113], s[92:93], 0, v[138:139]
	s_add_i32 m0, vcc_lo, 0x2000
	v_lshl_add_u64 v[196:197], s[90:91], 0, v[136:137]
	global_load_lds_dwordx4 v[112:113], off
	s_mov_b32 m0, s41
	s_nop 0
	global_load_lds_dwordx4 v[180:181], off
	s_mov_b32 m0, s52
	s_nop 0
	global_load_lds_dwordx4 v[196:197], off
	s_waitcnt vmcnt(8)
	s_waitcnt lgkmcnt(0)
	s_barrier

	v_mfma_f32_16x16x32_bf16 v[28:31], v[96:99], v[128:131], v[28:31]
	v_mfma_f32_16x16x32_bf16 v[24:27], v[104:107], v[128:131], v[24:27]
	v_mfma_f32_16x16x32_bf16 v[20:23], v[96:99], v[154:157], v[20:23]
	v_mfma_f32_16x16x32_bf16 v[16:19], v[104:107], v[154:157], v[16:19]
	v_mfma_f32_16x16x32_bf16 v[12:15], v[96:99], v[162:165], v[12:15]
	v_mfma_f32_16x16x32_bf16 v[8:11], v[104:107], v[162:165], v[8:11]
	v_mfma_f32_16x16x32_bf16 v[4:7], v[96:99], v[188:191], v[4:7]
	v_mfma_f32_16x16x32_bf16 v[0:3], v[104:107], v[188:191], v[0:3]
	v_mfma_f32_16x16x32_bf16 v[28:31], v[100:103], v[150:153], v[28:31]
	v_mfma_f32_16x16x32_bf16 v[24:27], v[108:111], v[150:153], v[24:27]
	v_mfma_f32_16x16x32_bf16 v[20:23], v[100:103], v[158:161], v[20:23]
	v_mfma_f32_16x16x32_bf16 v[16:19], v[108:111], v[158:161], v[16:19]
	v_mfma_f32_16x16x32_bf16 v[12:15], v[100:103], v[176:179], v[12:15]
	v_mfma_f32_16x16x32_bf16 v[8:11], v[108:111], v[176:179], v[8:11]
	v_mfma_f32_16x16x32_bf16 v[4:7], v[100:103], v[192:195], v[4:7]
	v_mfma_f32_16x16x32_bf16 v[0:3], v[108:111], v[192:195], v[0:3]

	s_barrier
	s_add_i32 s92, 0, 0x18000
	s_add_i32 s93, 0, 0x1c000
	v_add_u32_e32 v108, s92, v171
	v_add_u32_e32 v124, s93, v171
	ds_read_b128 v[96:99], v108
	ds_read_b128 v[100:103], v108 offset:1024
	ds_read_b128 v[104:107], v108 offset:2048
	ds_read_b128 v[108:111], v108 offset:3072
	ds_read_b128 v[112:115], v124
	ds_read_b128 v[116:119], v124 offset:1024
	ds_read_b128 v[120:123], v124 offset:2048
	ds_read_b128 v[124:127], v124 offset:3072
	s_add_u32 s90, s88, 0x80000
	s_addc_u32 s91, s89, 0
	s_mov_b32 m0, s53
	v_lshl_add_u64 v[198:199], s[90:91], 0, v[134:135]
	ds_read_b128 v[128:131], v184 offset:32768
	ds_read_b128 v[150:153], v184 offset:33792
	ds_read_b128 v[154:157], v184 offset:34816
	ds_read_b128 v[158:161], v184 offset:35840
	ds_read_b128 v[162:165], v184 offset:36864
	ds_read_b128 v[176:179], v184 offset:37888
	ds_read_b128 v[188:191], v184 offset:38912
	ds_read_b128 v[192:195], v184 offset:39936
	global_load_lds_dwordx4 v[198:199], off
	v_lshl_add_u64 v[198:199], s[90:91], 0, v[138:139]
	s_mov_b32 m0, s54
	s_nop 0
	global_load_lds_dwordx4 v[198:199], off
	s_waitcnt vmcnt(8)
	s_waitcnt lgkmcnt(0)
	s_barrier

	v_mfma_f32_16x16x32_bf16 v[92:95], v[96:99], v[128:131], v[92:95]
	v_mfma_f32_16x16x32_bf16 v[88:91], v[104:107], v[128:131], v[88:91]
	v_mfma_f32_16x16x32_bf16 v[84:87], v[96:99], v[154:157], v[84:87]
	v_mfma_f32_16x16x32_bf16 v[80:83], v[104:107], v[154:157], v[80:83]
	v_mfma_f32_16x16x32_bf16 v[68:71], v[96:99], v[162:165], v[68:71]
	v_mfma_f32_16x16x32_bf16 v[64:67], v[104:107], v[162:165], v[64:67]
	v_mfma_f32_16x16x32_bf16 v[52:55], v[96:99], v[188:191], v[52:55]
	v_mfma_f32_16x16x32_bf16 v[48:51], v[104:107], v[188:191], v[48:51]
	v_mfma_f32_16x16x32_bf16 v[92:95], v[100:103], v[150:153], v[92:95]
	v_mfma_f32_16x16x32_bf16 v[88:91], v[108:111], v[150:153], v[88:91]
	v_mfma_f32_16x16x32_bf16 v[84:87], v[100:103], v[158:161], v[84:87]
	v_mfma_f32_16x16x32_bf16 v[80:83], v[108:111], v[158:161], v[80:83]
	v_mfma_f32_16x16x32_bf16 v[68:71], v[100:103], v[176:179], v[68:71]
	v_mfma_f32_16x16x32_bf16 v[64:67], v[108:111], v[176:179], v[64:67]
	v_mfma_f32_16x16x32_bf16 v[52:55], v[100:103], v[192:195], v[52:55]
	v_mfma_f32_16x16x32_bf16 v[48:51], v[108:111], v[192:195], v[48:51]

	v_mfma_f32_16x16x32_bf16 v[76:79], v[112:115], v[128:131], v[76:79]
	v_mfma_f32_16x16x32_bf16 v[72:75], v[120:123], v[128:131], v[72:75]
	v_mfma_f32_16x16x32_bf16 v[60:63], v[112:115], v[154:157], v[60:63]
	v_mfma_f32_16x16x32_bf16 v[56:59], v[120:123], v[154:157], v[56:59]
	v_mfma_f32_16x16x32_bf16 v[44:47], v[112:115], v[162:165], v[44:47]
	v_mfma_f32_16x16x32_bf16 v[40:43], v[120:123], v[162:165], v[40:43]
	v_mfma_f32_16x16x32_bf16 v[36:39], v[112:115], v[188:191], v[36:39]
	v_mfma_f32_16x16x32_bf16 v[32:35], v[120:123], v[188:191], v[32:35]
	v_mfma_f32_16x16x32_bf16 v[76:79], v[116:119], v[150:153], v[76:79]
	v_mfma_f32_16x16x32_bf16 v[72:75], v[124:127], v[150:153], v[72:75]
	v_mfma_f32_16x16x32_bf16 v[60:63], v[116:119], v[158:161], v[60:63]
	v_mfma_f32_16x16x32_bf16 v[56:59], v[124:127], v[158:161], v[56:59]
	v_mfma_f32_16x16x32_bf16 v[44:47], v[116:119], v[176:179], v[44:47]
	v_mfma_f32_16x16x32_bf16 v[40:43], v[124:127], v[176:179], v[40:43]
	v_mfma_f32_16x16x32_bf16 v[36:39], v[116:119], v[192:195], v[36:39]
	v_mfma_f32_16x16x32_bf16 v[32:35], v[124:127], v[192:195], v[32:35]

	s_barrier
	s_add_i32 s90, s92, s15
	v_lshl_add_u64 v[112:113], v[168:169], 0, s[10:11]
	s_mov_b32 m0, s90
	ds_read_b128 v[96:99], v185 offset:49152
	ds_read_b128 v[100:103], v185 offset:50176
	ds_read_b128 v[104:107], v185 offset:51200
	ds_read_b128 v[108:111], v185 offset:52224
	global_load_lds_dwordx4 v[112:113], off
	s_add_i32 m0, s90, 0x2000
	s_add_u32 s88, s88, 0x40080
	v_lshl_add_u64 v[112:113], v[172:173], 0, s[10:11]
	s_addc_u32 s89, s89, 0
	s_add_i32 s90, s93, s15
	global_load_lds_dwordx4 v[112:113], off
	v_lshl_add_u64 v[112:113], s[88:89], 0, v[134:135]
	s_mov_b32 m0, s90
	s_nop 0
	global_load_lds_dwordx4 v[112:113], off
	v_lshl_add_u64 v[112:113], s[88:89], 0, v[138:139]
	s_add_i32 m0, s90, 0x2000
	s_nop 0
	global_load_lds_dwordx4 v[112:113], off
	v_lshl_add_u64 v[112:113], v[180:181], 0, s[10:11]
	s_mov_b32 m0, s55
	s_nop 0
	global_load_lds_dwordx4 v[112:113], off
	v_lshl_add_u64 v[112:113], v[196:197], 0, s[10:11]
	s_mov_b32 m0, s56
	s_nop 0
	global_load_lds_dwordx4 v[112:113], off
	s_waitcnt vmcnt(8)
	s_waitcnt lgkmcnt(0)
	s_barrier

	v_mfma_f32_16x16x32_bf16 v[28:31], v[96:99], v[128:131], v[28:31]
	v_mfma_f32_16x16x32_bf16 v[24:27], v[104:107], v[128:131], v[24:27]
	v_mfma_f32_16x16x32_bf16 v[20:23], v[96:99], v[154:157], v[20:23]
	v_mfma_f32_16x16x32_bf16 v[16:19], v[104:107], v[154:157], v[16:19]
	v_mfma_f32_16x16x32_bf16 v[12:15], v[96:99], v[162:165], v[12:15]
	v_mfma_f32_16x16x32_bf16 v[8:11], v[104:107], v[162:165], v[8:11]
	v_mfma_f32_16x16x32_bf16 v[4:7], v[96:99], v[188:191], v[4:7]
	v_mfma_f32_16x16x32_bf16 v[0:3], v[104:107], v[188:191], v[0:3]
	v_mfma_f32_16x16x32_bf16 v[28:31], v[100:103], v[150:153], v[28:31]
	v_mfma_f32_16x16x32_bf16 v[24:27], v[108:111], v[150:153], v[24:27]
	v_mfma_f32_16x16x32_bf16 v[20:23], v[100:103], v[158:161], v[20:23]
	v_mfma_f32_16x16x32_bf16 v[16:19], v[108:111], v[158:161], v[16:19]
	v_mfma_f32_16x16x32_bf16 v[12:15], v[100:103], v[176:179], v[12:15]
	v_mfma_f32_16x16x32_bf16 v[8:11], v[108:111], v[176:179], v[8:11]
	v_mfma_f32_16x16x32_bf16 v[4:7], v[100:103], v[192:195], v[4:7]
	v_mfma_f32_16x16x32_bf16 v[0:3], v[108:111], v[192:195], v[0:3]

	s_barrier
	s_add_i32 s68, s68, 2
	s_add_u32 s4, s4, 0x100
	s_addc_u32 s5, s5, 0
	s_add_u32 s86, s86, 0x100
	s_addc_u32 s87, s87, 0
	s_cmp_gt_u32 s68, 13
	s_cbranch_scc0 .LBB0_876
	s_mov_b64 s[86:87], 0
	s_branch .LBB0_879

.LBB0_881:
	ds_read_b128 v[128:131], v182
	ds_read_b128 v[150:153], v182 offset:1024
	ds_read_b128 v[154:157], v182 offset:2048
	ds_read_b128 v[158:161], v182 offset:3072
	ds_read_b128 v[162:165], v183
	ds_read_b128 v[176:179], v183 offset:1024
	ds_read_b128 v[188:191], v183 offset:2048
	ds_read_b128 v[192:195], v183 offset:3072
	s_add_u32 s92, s84, 0xfffc0080
	s_addc_u32 s93, s85, -1
	s_cmp_eq_u32 s5, 12
	s_cselect_b64 s[90:91], -1, 0
	s_and_b64 s[88:89], s[90:91], exec
	s_cselect_b32 s89, s65, s71
	s_cselect_b32 s88, s73, s69
	s_cselect_b32 s93, s3, s93
	s_cselect_b32 s92, s61, s92
	v_lshl_add_u64 v[168:169], s[84:85], 0, v[146:147]
	s_add_i32 m0, s41, 0xc000
	ds_read_b128 v[196:199], v184
	ds_read_b128 v[200:203], v184 offset:1024
	ds_read_b128 v[204:207], v184 offset:2048
	ds_read_b128 v[208:211], v184 offset:3072
	ds_read_b128 v[212:215], v184 offset:4096
	ds_read_b128 v[216:219], v184 offset:5120
	ds_read_b128 v[220:223], v184 offset:6144
	ds_read_b128 v[224:227], v184 offset:7168
	global_load_lds_dwordx4 v[168:169], off
	v_lshl_add_u64 v[168:169], s[84:85], 0, v[136:137]
	s_add_i32 m0, s41, 0xe000
	s_nop 0
	global_load_lds_dwordx4 v[168:169], off
	s_waitcnt vmcnt(8)
	s_waitcnt lgkmcnt(0)
	s_barrier

	v_mfma_f32_16x16x32_bf16 v[92:95], v[128:131], v[196:199], v[92:95]
	v_mfma_f32_16x16x32_bf16 v[88:91], v[154:157], v[196:199], v[88:91]
	v_mfma_f32_16x16x32_bf16 v[84:87], v[128:131], v[204:207], v[84:87]
	v_mfma_f32_16x16x32_bf16 v[80:83], v[154:157], v[204:207], v[80:83]
	v_mfma_f32_16x16x32_bf16 v[68:71], v[128:131], v[212:215], v[68:71]
	v_mfma_f32_16x16x32_bf16 v[64:67], v[154:157], v[212:215], v[64:67]
	v_mfma_f32_16x16x32_bf16 v[52:55], v[128:131], v[220:223], v[52:55]
	v_mfma_f32_16x16x32_bf16 v[48:51], v[154:157], v[220:223], v[48:51]
	v_mfma_f32_16x16x32_bf16 v[92:95], v[150:153], v[200:203], v[92:95]
	v_mfma_f32_16x16x32_bf16 v[88:91], v[158:161], v[200:203], v[88:91]
	v_mfma_f32_16x16x32_bf16 v[84:87], v[150:153], v[208:211], v[84:87]
	v_mfma_f32_16x16x32_bf16 v[80:83], v[158:161], v[208:211], v[80:83]
	v_mfma_f32_16x16x32_bf16 v[68:71], v[150:153], v[216:219], v[68:71]
	v_mfma_f32_16x16x32_bf16 v[64:67], v[158:161], v[216:219], v[64:67]
	v_mfma_f32_16x16x32_bf16 v[52:55], v[150:153], v[224:227], v[52:55]
	v_mfma_f32_16x16x32_bf16 v[48:51], v[158:161], v[224:227], v[48:51]

	v_mfma_f32_16x16x32_bf16 v[76:79], v[162:165], v[196:199], v[76:79]
	v_mfma_f32_16x16x32_bf16 v[72:75], v[188:191], v[196:199], v[72:75]
	v_mfma_f32_16x16x32_bf16 v[60:63], v[162:165], v[204:207], v[60:63]
	v_mfma_f32_16x16x32_bf16 v[56:59], v[188:191], v[204:207], v[56:59]
	v_mfma_f32_16x16x32_bf16 v[44:47], v[162:165], v[212:215], v[44:47]
	v_mfma_f32_16x16x32_bf16 v[40:43], v[188:191], v[212:215], v[40:43]
	v_mfma_f32_16x16x32_bf16 v[36:39], v[162:165], v[220:223], v[36:39]
	v_mfma_f32_16x16x32_bf16 v[32:35], v[188:191], v[220:223], v[32:35]
	v_mfma_f32_16x16x32_bf16 v[76:79], v[176:179], v[200:203], v[76:79]
	v_mfma_f32_16x16x32_bf16 v[72:75], v[192:195], v[200:203], v[72:75]
	v_mfma_f32_16x16x32_bf16 v[60:63], v[176:179], v[208:211], v[60:63]
	v_mfma_f32_16x16x32_bf16 v[56:59], v[192:195], v[208:211], v[56:59]
	v_mfma_f32_16x16x32_bf16 v[44:47], v[176:179], v[216:219], v[44:47]
	v_mfma_f32_16x16x32_bf16 v[40:43], v[192:195], v[216:219], v[40:43]
	v_mfma_f32_16x16x32_bf16 v[36:39], v[176:179], v[224:227], v[36:39]
	v_mfma_f32_16x16x32_bf16 v[32:35], v[192:195], v[224:227], v[32:35]

	s_barrier
	s_add_i32 vcc_lo, s76, s15
	v_lshl_add_u64 v[168:169], s[88:89], 0, v[134:135]
	s_mov_b32 m0, vcc_lo
	ds_read_b128 v[196:199], v184 offset:16384
	ds_read_b128 v[200:203], v184 offset:17408
	ds_read_b128 v[204:207], v184 offset:18432
	ds_read_b128 v[208:211], v184 offset:19456
	ds_read_b128 v[212:215], v184 offset:20480
	ds_read_b128 v[216:219], v184 offset:21504
	ds_read_b128 v[220:223], v184 offset:22528
	ds_read_b128 v[224:227], v184 offset:23552
	global_load_lds_dwordx4 v[168:169], off
	s_add_i32 m0, vcc_lo, 0x2000
	s_add_u32 vcc_lo, s88, 0x40000
	v_lshl_add_u64 v[172:173], s[88:89], 0, v[138:139]
	s_addc_u32 vcc_hi, s89, 0
	s_add_i32 s6, s77, s15
	global_load_lds_dwordx4 v[172:173], off
	v_lshl_add_u64 v[180:181], vcc, 0, v[134:135]
	s_mov_b32 m0, s6
	v_lshl_add_u64 v[228:229], s[92:93], 0, v[136:137]
	global_load_lds_dwordx4 v[180:181], off
	v_lshl_add_u64 v[180:181], vcc, 0, v[138:139]
	s_add_i32 m0, s6, 0x2000
	s_nop 0
	global_load_lds_dwordx4 v[180:181], off
	v_lshl_add_u64 v[180:181], s[92:93], 0, v[132:133]
	s_mov_b32 m0, s41
	s_nop 0
	global_load_lds_dwordx4 v[180:181], off
	s_mov_b32 m0, s52
	s_nop 0
	global_load_lds_dwordx4 v[228:229], off
	s_waitcnt vmcnt(8)
	s_waitcnt lgkmcnt(0)
	s_barrier

	v_mfma_f32_16x16x32_bf16 v[28:31], v[128:131], v[196:199], v[28:31]
	v_mfma_f32_16x16x32_bf16 v[24:27], v[154:157], v[196:199], v[24:27]
	v_mfma_f32_16x16x32_bf16 v[20:23], v[128:131], v[204:207], v[20:23]
	v_mfma_f32_16x16x32_bf16 v[16:19], v[154:157], v[204:207], v[16:19]
	v_mfma_f32_16x16x32_bf16 v[12:15], v[128:131], v[212:215], v[12:15]
	v_mfma_f32_16x16x32_bf16 v[8:11], v[154:157], v[212:215], v[8:11]
	v_mfma_f32_16x16x32_bf16 v[4:7], v[128:131], v[220:223], v[4:7]
	v_mfma_f32_16x16x32_bf16 v[0:3], v[154:157], v[220:223], v[0:3]
	v_mfma_f32_16x16x32_bf16 v[28:31], v[150:153], v[200:203], v[28:31]
	v_mfma_f32_16x16x32_bf16 v[24:27], v[158:161], v[200:203], v[24:27]
	v_mfma_f32_16x16x32_bf16 v[20:23], v[150:153], v[208:211], v[20:23]
	v_mfma_f32_16x16x32_bf16 v[16:19], v[158:161], v[208:211], v[16:19]
	v_mfma_f32_16x16x32_bf16 v[12:15], v[150:153], v[216:219], v[12:15]
	v_mfma_f32_16x16x32_bf16 v[8:11], v[158:161], v[216:219], v[8:11]
	v_mfma_f32_16x16x32_bf16 v[4:7], v[150:153], v[224:227], v[4:7]
	v_mfma_f32_16x16x32_bf16 v[0:3], v[158:161], v[224:227], v[0:3]

	v_mfma_f32_16x16x32_bf16 v[124:127], v[162:165], v[196:199], v[124:127]
	v_mfma_f32_16x16x32_bf16 v[120:123], v[188:191], v[196:199], v[120:123]
	v_mfma_f32_16x16x32_bf16 v[116:119], v[162:165], v[204:207], v[116:119]
	v_mfma_f32_16x16x32_bf16 v[112:115], v[188:191], v[204:207], v[112:115]
	v_mfma_f32_16x16x32_bf16 v[108:111], v[162:165], v[212:215], v[108:111]
	v_mfma_f32_16x16x32_bf16 v[104:107], v[188:191], v[212:215], v[104:107]
	v_mfma_f32_16x16x32_bf16 v[100:103], v[162:165], v[220:223], v[100:103]
	v_mfma_f32_16x16x32_bf16 v[96:99], v[188:191], v[220:223], v[96:99]
	v_mfma_f32_16x16x32_bf16 v[124:127], v[176:179], v[200:203], v[124:127]
	v_mfma_f32_16x16x32_bf16 v[120:123], v[192:195], v[200:203], v[120:123]
	v_mfma_f32_16x16x32_bf16 v[116:119], v[176:179], v[208:211], v[116:119]
	v_mfma_f32_16x16x32_bf16 v[112:115], v[192:195], v[208:211], v[112:115]
	v_mfma_f32_16x16x32_bf16 v[108:111], v[176:179], v[216:219], v[108:111]
	v_mfma_f32_16x16x32_bf16 v[104:107], v[192:195], v[216:219], v[104:107]
	v_mfma_f32_16x16x32_bf16 v[100:103], v[176:179], v[224:227], v[100:103]
	v_mfma_f32_16x16x32_bf16 v[96:99], v[192:195], v[224:227], v[96:99]

	s_barrier
	s_add_i32 s6, 0, 0x18000
	s_add_i32 s7, 0, 0x1c000
	v_add_u32_e32 v158, s6, v171
	v_add_u32_e32 v166, s7, v171
	ds_read_b128 v[128:131], v158
	ds_read_b128 v[150:153], v158 offset:1024
	ds_read_b128 v[154:157], v158 offset:2048
	ds_read_b128 v[158:161], v158 offset:3072
	ds_read_b128 v[162:165], v166
	ds_read_b128 v[176:179], v166 offset:1024
	ds_read_b128 v[188:191], v166 offset:2048
	ds_read_b128 v[192:195], v166 offset:3072
	s_and_b64 s[90:91], s[62:63], s[90:91]
	s_and_b64 vcc, s[90:91], s[86:87]
	s_add_u32 s92, s92, 0x40000
	s_addc_u32 s93, s93, 0
	s_and_b64 s[90:91], vcc, exec
	s_mov_b32 m0, s53
	v_cndmask_b32_e32 v166, v132, v134, vcc
	s_cselect_b32 s91, s4, s93
	s_cselect_b32 s90, s68, s92
	ds_read_b128 v[196:199], v184 offset:32768
	ds_read_b128 v[200:203], v184 offset:33792
	ds_read_b128 v[204:207], v184 offset:34816
	ds_read_b128 v[208:211], v184 offset:35840
	ds_read_b128 v[212:215], v184 offset:36864
	ds_read_b128 v[216:219], v184 offset:37888
	ds_read_b128 v[220:223], v184 offset:38912
	ds_read_b128 v[224:227], v184 offset:39936
	v_cndmask_b32_e32 v170, v136, v138, vcc
	global_load_lds_dwordx4 v166, s[90:91]
	s_mov_b32 m0, s54
	s_nop 0
	global_load_lds_dwordx4 v170, s[90:91]
	s_waitcnt vmcnt(8)
	s_waitcnt lgkmcnt(0)
	s_barrier

	v_mfma_f32_16x16x32_bf16 v[92:95], v[128:131], v[196:199], v[92:95]
	v_mfma_f32_16x16x32_bf16 v[88:91], v[154:157], v[196:199], v[88:91]
	v_mfma_f32_16x16x32_bf16 v[84:87], v[128:131], v[204:207], v[84:87]
	v_mfma_f32_16x16x32_bf16 v[80:83], v[154:157], v[204:207], v[80:83]
	v_mfma_f32_16x16x32_bf16 v[68:71], v[128:131], v[212:215], v[68:71]
	v_mfma_f32_16x16x32_bf16 v[64:67], v[154:157], v[212:215], v[64:67]
	v_mfma_f32_16x16x32_bf16 v[52:55], v[128:131], v[220:223], v[52:55]
	v_mfma_f32_16x16x32_bf16 v[48:51], v[154:157], v[220:223], v[48:51]
	v_mfma_f32_16x16x32_bf16 v[92:95], v[150:153], v[200:203], v[92:95]
	v_mfma_f32_16x16x32_bf16 v[88:91], v[158:161], v[200:203], v[88:91]
	v_mfma_f32_16x16x32_bf16 v[84:87], v[150:153], v[208:211], v[84:87]
	v_mfma_f32_16x16x32_bf16 v[80:83], v[158:161], v[208:211], v[80:83]
	v_mfma_f32_16x16x32_bf16 v[68:71], v[150:153], v[216:219], v[68:71]
	v_mfma_f32_16x16x32_bf16 v[64:67], v[158:161], v[216:219], v[64:67]
	v_mfma_f32_16x16x32_bf16 v[52:55], v[150:153], v[224:227], v[52:55]
	v_mfma_f32_16x16x32_bf16 v[48:51], v[158:161], v[224:227], v[48:51]

	v_mfma_f32_16x16x32_bf16 v[76:79], v[162:165], v[196:199], v[76:79]
	v_mfma_f32_16x16x32_bf16 v[72:75], v[188:191], v[196:199], v[72:75]
	v_mfma_f32_16x16x32_bf16 v[60:63], v[162:165], v[204:207], v[60:63]
	v_mfma_f32_16x16x32_bf16 v[56:59], v[188:191], v[204:207], v[56:59]
	v_mfma_f32_16x16x32_bf16 v[44:47], v[162:165], v[212:215], v[44:47]
	v_mfma_f32_16x16x32_bf16 v[40:43], v[188:191], v[212:215], v[40:43]
	v_mfma_f32_16x16x32_bf16 v[36:39], v[162:165], v[220:223], v[36:39]
	v_mfma_f32_16x16x32_bf16 v[32:35], v[188:191], v[220:223], v[32:35]
	v_mfma_f32_16x16x32_bf16 v[76:79], v[176:179], v[200:203], v[76:79]
	v_mfma_f32_16x16x32_bf16 v[72:75], v[192:195], v[200:203], v[72:75]
	v_mfma_f32_16x16x32_bf16 v[60:63], v[176:179], v[208:211], v[60:63]
	v_mfma_f32_16x16x32_bf16 v[56:59], v[192:195], v[208:211], v[56:59]
	v_mfma_f32_16x16x32_bf16 v[44:47], v[176:179], v[216:219], v[44:47]
	v_mfma_f32_16x16x32_bf16 v[40:43], v[192:195], v[216:219], v[40:43]
	v_mfma_f32_16x16x32_bf16 v[36:39], v[176:179], v[224:227], v[36:39]
	v_mfma_f32_16x16x32_bf16 v[32:35], v[192:195], v[224:227], v[32:35]

	s_barrier
	s_add_i32 s6, s6, s15
	v_lshl_add_u64 v[168:169], v[168:169], 0, s[10:11]
	s_mov_b32 m0, s6
	ds_read_b128 v[196:199], v184 offset:49152
	ds_read_b128 v[200:203], v184 offset:50176
	ds_read_b128 v[204:207], v184 offset:51200
	ds_read_b128 v[208:211], v184 offset:52224
	ds_read_b128 v[212:215], v184 offset:53248
	ds_read_b128 v[216:219], v184 offset:54272
	ds_read_b128 v[220:223], v184 offset:55296
	ds_read_b128 v[224:227], v184 offset:56320
	global_load_lds_dwordx4 v[168:169], off
	s_add_i32 m0, s6, 0x2000
	s_add_u32 s88, s88, 0x40080
	v_lshl_add_u64 v[168:169], v[172:173], 0, s[10:11]
	s_addc_u32 s89, s89, 0
	s_add_i32 s6, s7, s15
	global_load_lds_dwordx4 v[168:169], off
	v_lshl_add_u64 v[168:169], s[88:89], 0, v[134:135]
	s_mov_b32 m0, s6
	s_nop 0
	global_load_lds_dwordx4 v[168:169], off
	v_lshl_add_u64 v[168:169], s[88:89], 0, v[138:139]
	s_add_i32 m0, s6, 0x2000
	s_nop 0
	global_load_lds_dwordx4 v[168:169], off
	v_lshl_add_u64 v[168:169], v[180:181], 0, s[10:11]
	s_mov_b32 m0, s55
	s_nop 0
	global_load_lds_dwordx4 v[168:169], off
	v_lshl_add_u64 v[168:169], v[228:229], 0, s[10:11]
	s_mov_b32 m0, s56
	s_nop 0
	global_load_lds_dwordx4 v[168:169], off
	s_waitcnt vmcnt(8)
	s_waitcnt lgkmcnt(0)
	s_barrier

	v_mfma_f32_16x16x32_bf16 v[28:31], v[128:131], v[196:199], v[28:31]
	v_mfma_f32_16x16x32_bf16 v[24:27], v[154:157], v[196:199], v[24:27]
	v_mfma_f32_16x16x32_bf16 v[20:23], v[128:131], v[204:207], v[20:23]
	v_mfma_f32_16x16x32_bf16 v[16:19], v[154:157], v[204:207], v[16:19]
	v_mfma_f32_16x16x32_bf16 v[12:15], v[128:131], v[212:215], v[12:15]
	v_mfma_f32_16x16x32_bf16 v[8:11], v[154:157], v[212:215], v[8:11]
	v_mfma_f32_16x16x32_bf16 v[4:7], v[128:131], v[220:223], v[4:7]
	v_mfma_f32_16x16x32_bf16 v[0:3], v[154:157], v[220:223], v[0:3]
	v_mfma_f32_16x16x32_bf16 v[28:31], v[150:153], v[200:203], v[28:31]
	v_mfma_f32_16x16x32_bf16 v[24:27], v[158:161], v[200:203], v[24:27]
	v_mfma_f32_16x16x32_bf16 v[20:23], v[150:153], v[208:211], v[20:23]
	v_mfma_f32_16x16x32_bf16 v[16:19], v[158:161], v[208:211], v[16:19]
	v_mfma_f32_16x16x32_bf16 v[12:15], v[150:153], v[216:219], v[12:15]
	v_mfma_f32_16x16x32_bf16 v[8:11], v[158:161], v[216:219], v[8:11]
	v_mfma_f32_16x16x32_bf16 v[4:7], v[150:153], v[224:227], v[4:7]
	v_mfma_f32_16x16x32_bf16 v[0:3], v[158:161], v[224:227], v[0:3]

	v_mfma_f32_16x16x32_bf16 v[124:127], v[162:165], v[196:199], v[124:127]
	v_mfma_f32_16x16x32_bf16 v[120:123], v[188:191], v[196:199], v[120:123]
	v_mfma_f32_16x16x32_bf16 v[116:119], v[162:165], v[204:207], v[116:119]
	v_mfma_f32_16x16x32_bf16 v[112:115], v[188:191], v[204:207], v[112:115]
	v_mfma_f32_16x16x32_bf16 v[108:111], v[162:165], v[212:215], v[108:111]
	v_mfma_f32_16x16x32_bf16 v[104:107], v[188:191], v[212:215], v[104:107]
	v_mfma_f32_16x16x32_bf16 v[100:103], v[162:165], v[220:223], v[100:103]
	v_mfma_f32_16x16x32_bf16 v[96:99], v[188:191], v[220:223], v[96:99]
	v_mfma_f32_16x16x32_bf16 v[124:127], v[176:179], v[200:203], v[124:127]
	v_mfma_f32_16x16x32_bf16 v[120:123], v[192:195], v[200:203], v[120:123]
	v_mfma_f32_16x16x32_bf16 v[116:119], v[176:179], v[208:211], v[116:119]
	v_mfma_f32_16x16x32_bf16 v[112:115], v[192:195], v[208:211], v[112:115]
	v_mfma_f32_16x16x32_bf16 v[108:111], v[176:179], v[216:219], v[108:111]
	v_mfma_f32_16x16x32_bf16 v[104:107], v[192:195], v[216:219], v[104:107]
	v_mfma_f32_16x16x32_bf16 v[100:103], v[176:179], v[224:227], v[100:103]
	v_mfma_f32_16x16x32_bf16 v[96:99], v[192:195], v[224:227], v[96:99]

	s_barrier
	s_add_i32 s5, s5, 2
	s_add_u32 s84, s84, 0x100
	s_addc_u32 s85, s85, 0
	s_add_u32 s69, s69, 0x100
	s_addc_u32 s71, s71, 0
	s_cmp_gt_u32 s5, 13
	s_cbranch_scc0 .LBB0_881

.LBB0_971:
	ds_read_b128 v[120:123], v237
	ds_read_b128 v[128:131], v237 offset:1024
	ds_read_b128 v[136:139], v237 offset:2048
	ds_read_b128 v[140:143], v237 offset:3072
	ds_read_b128 v[144:147], v238
	ds_read_b128 v[148:151], v238 offset:1024
	ds_read_b128 v[152:155], v238 offset:2048
	ds_read_b128 v[156:159], v238 offset:3072
	s_add_u32 s6, s4, 0xfffc0080
	s_addc_u32 s7, s5, -1
	s_cmp_eq_u32 s88, 12
	s_cselect_b32 s83, s65, s7
	s_cselect_b32 s82, s73, s6
	s_cselect_b32 s7, s67, s87
	s_cselect_b32 s6, s76, s86
	v_lshl_add_u64 v[210:211], s[4:5], 0, v[190:191]
	s_add_i32 m0, s53, 0xc000
	ds_read_b128 v[160:163], v239
	ds_read_b128 v[164:167], v239 offset:1024
	ds_read_b128 v[168:171], v239 offset:2048
	ds_read_b128 v[172:175], v239 offset:3072
	ds_read_b128 v[176:179], v239 offset:4096
	ds_read_b128 v[198:201], v239 offset:5120
	ds_read_b128 v[202:205], v239 offset:6144
	ds_read_b128 v[206:209], v239 offset:7168
	global_load_lds_dwordx4 v[210:211], off
	v_lshl_add_u64 v[210:211], s[4:5], 0, v[192:193]
	s_add_i32 m0, s53, 0xe000
	s_nop 0
	global_load_lds_dwordx4 v[210:211], off
	s_waitcnt vmcnt(8)
	s_waitcnt lgkmcnt(0)
	s_barrier

	v_mfma_f32_16x16x32_bf16 v[132:135], v[120:123], v[160:163], v[132:135]
	v_mfma_f32_16x16x32_bf16 v[124:127], v[136:139], v[160:163], v[124:127]
	v_mfma_f32_16x16x32_bf16 v[116:119], v[120:123], v[168:171], v[116:119]
	v_mfma_f32_16x16x32_bf16 v[112:115], v[136:139], v[168:171], v[112:115]
	v_mfma_f32_16x16x32_bf16 v[108:111], v[120:123], v[176:179], v[108:111]
	v_mfma_f32_16x16x32_bf16 v[104:107], v[136:139], v[176:179], v[104:107]
	v_mfma_f32_16x16x32_bf16 v[100:103], v[120:123], v[202:205], v[100:103]
	v_mfma_f32_16x16x32_bf16 v[96:99], v[136:139], v[202:205], v[96:99]
	v_mfma_f32_16x16x32_bf16 v[132:135], v[128:131], v[164:167], v[132:135]
	v_mfma_f32_16x16x32_bf16 v[124:127], v[140:143], v[164:167], v[124:127]
	v_mfma_f32_16x16x32_bf16 v[116:119], v[128:131], v[172:175], v[116:119]
	v_mfma_f32_16x16x32_bf16 v[112:115], v[140:143], v[172:175], v[112:115]
	v_mfma_f32_16x16x32_bf16 v[108:111], v[128:131], v[198:201], v[108:111]
	v_mfma_f32_16x16x32_bf16 v[104:107], v[140:143], v[198:201], v[104:107]
	v_mfma_f32_16x16x32_bf16 v[100:103], v[128:131], v[206:209], v[100:103]
	v_mfma_f32_16x16x32_bf16 v[96:99], v[140:143], v[206:209], v[96:99]

	v_mfma_f32_16x16x32_bf16 v[92:95], v[144:147], v[160:163], v[92:95]
	v_mfma_f32_16x16x32_bf16 v[88:91], v[152:155], v[160:163], v[88:91]
	v_mfma_f32_16x16x32_bf16 v[84:87], v[144:147], v[168:171], v[84:87]
	v_mfma_f32_16x16x32_bf16 v[80:83], v[152:155], v[168:171], v[80:83]
	v_mfma_f32_16x16x32_bf16 v[76:79], v[144:147], v[176:179], v[76:79]
	v_mfma_f32_16x16x32_bf16 v[72:75], v[152:155], v[176:179], v[72:75]
	v_mfma_f32_16x16x32_bf16 v[68:71], v[144:147], v[202:205], v[68:71]
	v_mfma_f32_16x16x32_bf16 v[64:67], v[152:155], v[202:205], v[64:67]
	v_mfma_f32_16x16x32_bf16 v[92:95], v[148:151], v[164:167], v[92:95]
	v_mfma_f32_16x16x32_bf16 v[88:91], v[156:159], v[164:167], v[88:91]
	v_mfma_f32_16x16x32_bf16 v[84:87], v[148:151], v[172:175], v[84:87]
	v_mfma_f32_16x16x32_bf16 v[80:83], v[156:159], v[172:175], v[80:83]
	v_mfma_f32_16x16x32_bf16 v[76:79], v[148:151], v[198:201], v[76:79]
	v_mfma_f32_16x16x32_bf16 v[72:75], v[156:159], v[198:201], v[72:75]
	v_mfma_f32_16x16x32_bf16 v[68:71], v[148:151], v[206:209], v[68:71]
	v_mfma_f32_16x16x32_bf16 v[64:67], v[156:159], v[206:209], v[64:67]

	s_barrier
	s_add_i32 s89, s68, s52
	v_lshl_add_u64 v[210:211], s[6:7], 0, v[182:183]
	s_mov_b32 m0, s89
	ds_read_b128 v[160:163], v239 offset:16384
	ds_read_b128 v[164:167], v239 offset:17408
	ds_read_b128 v[168:171], v239 offset:18432
	ds_read_b128 v[172:175], v239 offset:19456
	ds_read_b128 v[176:179], v239 offset:20480
	ds_read_b128 v[198:201], v239 offset:21504
	ds_read_b128 v[202:205], v239 offset:22528
	ds_read_b128 v[206:209], v239 offset:23552
	global_load_lds_dwordx4 v[210:211], off
	s_add_i32 m0, s89, 0x2000
	s_add_u32 s90, s6, 0x40000
	v_lshl_add_u64 v[212:213], s[6:7], 0, v[186:187]
	s_addc_u32 s91, s7, 0
	s_add_i32 s89, s69, s52
	global_load_lds_dwordx4 v[212:213], off
	v_lshl_add_u64 v[214:215], s[90:91], 0, v[182:183]
	s_mov_b32 m0, s89
	v_lshl_add_u64 v[216:217], s[82:83], 0, v[184:185]
	global_load_lds_dwordx4 v[214:215], off
	v_lshl_add_u64 v[214:215], s[90:91], 0, v[186:187]
	s_add_i32 m0, s89, 0x2000
	s_nop 0
	global_load_lds_dwordx4 v[214:215], off
	v_lshl_add_u64 v[214:215], s[82:83], 0, v[180:181]
	s_mov_b32 m0, s53
	s_nop 0
	global_load_lds_dwordx4 v[214:215], off
	s_mov_b32 m0, s54
	s_nop 0
	global_load_lds_dwordx4 v[216:217], off
	s_waitcnt vmcnt(8)
	s_waitcnt lgkmcnt(0)
	s_barrier

	v_mfma_f32_16x16x32_bf16 v[60:63], v[120:123], v[160:163], v[60:63]
	v_mfma_f32_16x16x32_bf16 v[56:59], v[136:139], v[160:163], v[56:59]
	v_mfma_f32_16x16x32_bf16 v[52:55], v[120:123], v[168:171], v[52:55]
	v_mfma_f32_16x16x32_bf16 v[48:51], v[136:139], v[168:171], v[48:51]
	v_mfma_f32_16x16x32_bf16 v[44:47], v[120:123], v[176:179], v[44:47]
	v_mfma_f32_16x16x32_bf16 v[40:43], v[136:139], v[176:179], v[40:43]
	v_mfma_f32_16x16x32_bf16 v[36:39], v[120:123], v[202:205], v[36:39]
	v_mfma_f32_16x16x32_bf16 v[32:35], v[136:139], v[202:205], v[32:35]
	v_mfma_f32_16x16x32_bf16 v[60:63], v[128:131], v[164:167], v[60:63]
	v_mfma_f32_16x16x32_bf16 v[56:59], v[140:143], v[164:167], v[56:59]
	v_mfma_f32_16x16x32_bf16 v[52:55], v[128:131], v[172:175], v[52:55]
	v_mfma_f32_16x16x32_bf16 v[48:51], v[140:143], v[172:175], v[48:51]
	v_mfma_f32_16x16x32_bf16 v[44:47], v[128:131], v[198:201], v[44:47]
	v_mfma_f32_16x16x32_bf16 v[40:43], v[140:143], v[198:201], v[40:43]
	v_mfma_f32_16x16x32_bf16 v[36:39], v[128:131], v[206:209], v[36:39]
	v_mfma_f32_16x16x32_bf16 v[32:35], v[140:143], v[206:209], v[32:35]

	v_mfma_f32_16x16x32_bf16 v[28:31], v[144:147], v[160:163], v[28:31]
	v_mfma_f32_16x16x32_bf16 v[24:27], v[152:155], v[160:163], v[24:27]
	v_mfma_f32_16x16x32_bf16 v[20:23], v[144:147], v[168:171], v[20:23]
	v_mfma_f32_16x16x32_bf16 v[16:19], v[152:155], v[168:171], v[16:19]
	v_mfma_f32_16x16x32_bf16 v[12:15], v[144:147], v[176:179], v[12:15]
	v_mfma_f32_16x16x32_bf16 v[8:11], v[152:155], v[176:179], v[8:11]
	v_mfma_f32_16x16x32_bf16 v[4:7], v[144:147], v[202:205], v[4:7]
	v_mfma_f32_16x16x32_bf16 v[0:3], v[152:155], v[202:205], v[0:3]
	v_mfma_f32_16x16x32_bf16 v[28:31], v[148:151], v[164:167], v[28:31]
	v_mfma_f32_16x16x32_bf16 v[24:27], v[156:159], v[164:167], v[24:27]
	v_mfma_f32_16x16x32_bf16 v[20:23], v[148:151], v[172:175], v[20:23]
	v_mfma_f32_16x16x32_bf16 v[16:19], v[156:159], v[172:175], v[16:19]
	v_mfma_f32_16x16x32_bf16 v[12:15], v[148:151], v[198:201], v[12:15]
	v_mfma_f32_16x16x32_bf16 v[8:11], v[156:159], v[198:201], v[8:11]
	v_mfma_f32_16x16x32_bf16 v[4:7], v[148:151], v[206:209], v[4:7]
	v_mfma_f32_16x16x32_bf16 v[0:3], v[156:159], v[206:209], v[0:3]

	s_barrier
	s_add_i32 s89, 0, 0x18000
	s_add_i32 s90, 0, 0x1c000
	v_add_u32_e32 v140, s89, v235
	v_add_u32_e32 v156, s90, v235
	ds_read_b128 v[120:123], v140
	ds_read_b128 v[128:131], v140 offset:1024
	ds_read_b128 v[136:139], v140 offset:2048
	ds_read_b128 v[140:143], v140 offset:3072
	ds_read_b128 v[144:147], v156
	ds_read_b128 v[148:151], v156 offset:1024
	ds_read_b128 v[152:155], v156 offset:2048
	ds_read_b128 v[156:159], v156 offset:3072
	s_add_u32 s82, s82, 0x40000
	s_addc_u32 s83, s83, 0
	s_mov_b32 m0, s55
	v_lshl_add_u64 v[218:219], s[82:83], 0, v[180:181]
	ds_read_b128 v[160:163], v239 offset:32768
	ds_read_b128 v[164:167], v239 offset:33792
	ds_read_b128 v[168:171], v239 offset:34816
	ds_read_b128 v[172:175], v239 offset:35840
	ds_read_b128 v[176:179], v239 offset:36864
	ds_read_b128 v[198:201], v239 offset:37888
	ds_read_b128 v[202:205], v239 offset:38912
	ds_read_b128 v[206:209], v239 offset:39936
	global_load_lds_dwordx4 v[218:219], off
	v_lshl_add_u64 v[218:219], s[82:83], 0, v[184:185]
	s_mov_b32 m0, s56
	s_nop 0
	global_load_lds_dwordx4 v[218:219], off
	s_waitcnt vmcnt(8)
	s_waitcnt lgkmcnt(0)
	s_barrier

	v_mfma_f32_16x16x32_bf16 v[132:135], v[120:123], v[160:163], v[132:135]
	v_mfma_f32_16x16x32_bf16 v[124:127], v[136:139], v[160:163], v[124:127]
	v_mfma_f32_16x16x32_bf16 v[116:119], v[120:123], v[168:171], v[116:119]
	v_mfma_f32_16x16x32_bf16 v[112:115], v[136:139], v[168:171], v[112:115]
	v_mfma_f32_16x16x32_bf16 v[108:111], v[120:123], v[176:179], v[108:111]
	v_mfma_f32_16x16x32_bf16 v[104:107], v[136:139], v[176:179], v[104:107]
	v_mfma_f32_16x16x32_bf16 v[100:103], v[120:123], v[202:205], v[100:103]
	v_mfma_f32_16x16x32_bf16 v[96:99], v[136:139], v[202:205], v[96:99]
	v_mfma_f32_16x16x32_bf16 v[132:135], v[128:131], v[164:167], v[132:135]
	v_mfma_f32_16x16x32_bf16 v[124:127], v[140:143], v[164:167], v[124:127]
	v_mfma_f32_16x16x32_bf16 v[116:119], v[128:131], v[172:175], v[116:119]
	v_mfma_f32_16x16x32_bf16 v[112:115], v[140:143], v[172:175], v[112:115]
	v_mfma_f32_16x16x32_bf16 v[108:111], v[128:131], v[198:201], v[108:111]
	v_mfma_f32_16x16x32_bf16 v[104:107], v[140:143], v[198:201], v[104:107]
	v_mfma_f32_16x16x32_bf16 v[100:103], v[128:131], v[206:209], v[100:103]
	v_mfma_f32_16x16x32_bf16 v[96:99], v[140:143], v[206:209], v[96:99]

	v_mfma_f32_16x16x32_bf16 v[92:95], v[144:147], v[160:163], v[92:95]
	v_mfma_f32_16x16x32_bf16 v[88:91], v[152:155], v[160:163], v[88:91]
	v_mfma_f32_16x16x32_bf16 v[84:87], v[144:147], v[168:171], v[84:87]
	v_mfma_f32_16x16x32_bf16 v[80:83], v[152:155], v[168:171], v[80:83]
	v_mfma_f32_16x16x32_bf16 v[76:79], v[144:147], v[176:179], v[76:79]
	v_mfma_f32_16x16x32_bf16 v[72:75], v[152:155], v[176:179], v[72:75]
	v_mfma_f32_16x16x32_bf16 v[68:71], v[144:147], v[202:205], v[68:71]
	v_mfma_f32_16x16x32_bf16 v[64:67], v[152:155], v[202:205], v[64:67]
	v_mfma_f32_16x16x32_bf16 v[92:95], v[148:151], v[164:167], v[92:95]
	v_mfma_f32_16x16x32_bf16 v[88:91], v[156:159], v[164:167], v[88:91]
	v_mfma_f32_16x16x32_bf16 v[84:87], v[148:151], v[172:175], v[84:87]
	v_mfma_f32_16x16x32_bf16 v[80:83], v[156:159], v[172:175], v[80:83]
	v_mfma_f32_16x16x32_bf16 v[76:79], v[148:151], v[198:201], v[76:79]
	v_mfma_f32_16x16x32_bf16 v[72:75], v[156:159], v[198:201], v[72:75]
	v_mfma_f32_16x16x32_bf16 v[68:71], v[148:151], v[206:209], v[68:71]
	v_mfma_f32_16x16x32_bf16 v[64:67], v[156:159], v[206:209], v[64:67]

	s_barrier
	s_add_i32 s82, s89, s52
	v_lshl_add_u64 v[210:211], v[210:211], 0, s[18:19]
	s_mov_b32 m0, s82
	ds_read_b128 v[160:163], v239 offset:49152
	ds_read_b128 v[164:167], v239 offset:50176
	ds_read_b128 v[168:171], v239 offset:51200
	ds_read_b128 v[172:175], v239 offset:52224
	ds_read_b128 v[176:179], v239 offset:53248
	ds_read_b128 v[198:201], v239 offset:54272
	ds_read_b128 v[202:205], v239 offset:55296
	ds_read_b128 v[206:209], v239 offset:56320
	global_load_lds_dwordx4 v[210:211], off
	s_add_i32 m0, s82, 0x2000
	s_add_u32 s6, s6, 0x40080
	v_lshl_add_u64 v[210:211], v[212:213], 0, s[18:19]
	s_addc_u32 s7, s7, 0
	s_add_i32 s82, s90, s52
	global_load_lds_dwordx4 v[210:211], off
	v_lshl_add_u64 v[210:211], s[6:7], 0, v[182:183]
	s_mov_b32 m0, s82
	s_nop 0
	global_load_lds_dwordx4 v[210:211], off
	v_lshl_add_u64 v[210:211], s[6:7], 0, v[186:187]
	s_add_i32 m0, s82, 0x2000
	s_nop 0
	global_load_lds_dwordx4 v[210:211], off
	v_lshl_add_u64 v[210:211], v[214:215], 0, s[18:19]
	s_mov_b32 m0, s58
	s_nop 0
	global_load_lds_dwordx4 v[210:211], off
	v_lshl_add_u64 v[210:211], v[216:217], 0, s[18:19]
	s_mov_b32 m0, s59
	s_nop 0
	global_load_lds_dwordx4 v[210:211], off
	s_waitcnt vmcnt(8)
	s_waitcnt lgkmcnt(0)
	s_barrier

	v_mfma_f32_16x16x32_bf16 v[60:63], v[120:123], v[160:163], v[60:63]
	v_mfma_f32_16x16x32_bf16 v[56:59], v[136:139], v[160:163], v[56:59]
	v_mfma_f32_16x16x32_bf16 v[52:55], v[120:123], v[168:171], v[52:55]
	v_mfma_f32_16x16x32_bf16 v[48:51], v[136:139], v[168:171], v[48:51]
	v_mfma_f32_16x16x32_bf16 v[44:47], v[120:123], v[176:179], v[44:47]
	v_mfma_f32_16x16x32_bf16 v[40:43], v[136:139], v[176:179], v[40:43]
	v_mfma_f32_16x16x32_bf16 v[36:39], v[120:123], v[202:205], v[36:39]
	v_mfma_f32_16x16x32_bf16 v[32:35], v[136:139], v[202:205], v[32:35]
	v_mfma_f32_16x16x32_bf16 v[60:63], v[128:131], v[164:167], v[60:63]
	v_mfma_f32_16x16x32_bf16 v[56:59], v[140:143], v[164:167], v[56:59]
	v_mfma_f32_16x16x32_bf16 v[52:55], v[128:131], v[172:175], v[52:55]
	v_mfma_f32_16x16x32_bf16 v[48:51], v[140:143], v[172:175], v[48:51]
	v_mfma_f32_16x16x32_bf16 v[44:47], v[128:131], v[198:201], v[44:47]
	v_mfma_f32_16x16x32_bf16 v[40:43], v[140:143], v[198:201], v[40:43]
	v_mfma_f32_16x16x32_bf16 v[36:39], v[128:131], v[206:209], v[36:39]
	v_mfma_f32_16x16x32_bf16 v[32:35], v[140:143], v[206:209], v[32:35]

	v_mfma_f32_16x16x32_bf16 v[28:31], v[144:147], v[160:163], v[28:31]
	v_mfma_f32_16x16x32_bf16 v[24:27], v[152:155], v[160:163], v[24:27]
	v_mfma_f32_16x16x32_bf16 v[20:23], v[144:147], v[168:171], v[20:23]
	v_mfma_f32_16x16x32_bf16 v[16:19], v[152:155], v[168:171], v[16:19]
	v_mfma_f32_16x16x32_bf16 v[12:15], v[144:147], v[176:179], v[12:15]
	v_mfma_f32_16x16x32_bf16 v[8:11], v[152:155], v[176:179], v[8:11]
	v_mfma_f32_16x16x32_bf16 v[4:7], v[144:147], v[202:205], v[4:7]
	v_mfma_f32_16x16x32_bf16 v[0:3], v[152:155], v[202:205], v[0:3]
	v_mfma_f32_16x16x32_bf16 v[28:31], v[148:151], v[164:167], v[28:31]
	v_mfma_f32_16x16x32_bf16 v[24:27], v[156:159], v[164:167], v[24:27]
	v_mfma_f32_16x16x32_bf16 v[20:23], v[148:151], v[172:175], v[20:23]
	v_mfma_f32_16x16x32_bf16 v[16:19], v[156:159], v[172:175], v[16:19]
	v_mfma_f32_16x16x32_bf16 v[12:15], v[148:151], v[198:201], v[12:15]
	v_mfma_f32_16x16x32_bf16 v[8:11], v[156:159], v[198:201], v[8:11]
	v_mfma_f32_16x16x32_bf16 v[4:7], v[148:151], v[206:209], v[4:7]
	v_mfma_f32_16x16x32_bf16 v[0:3], v[156:159], v[206:209], v[0:3]

	s_barrier
	s_add_i32 s88, s88, 2
	s_add_u32 s4, s4, 0x100
	s_addc_u32 s5, s5, 0
	s_add_u32 s86, s86, 0x100
	s_addc_u32 s87, s87, 0
	s_cmp_gt_u32 s88, 13
	s_cbranch_scc0 .LBB0_971
	s_and_b64 vcc, exec, s[36:37]
	s_cbranch_vccz .LBB0_974
	s_barrier

.LBB0_1080:
	ds_read_b128 v[128:131], v187
	ds_read_b128 v[132:135], v187 offset:1024
	ds_read_b128 v[136:139], v187 offset:2048
	ds_read_b128 v[140:143], v187 offset:3072
	ds_read_b128 v[144:147], v188
	ds_read_b128 v[148:151], v188 offset:1024
	ds_read_b128 v[168:171], v188 offset:2048
	ds_read_b128 v[172:175], v188 offset:3072
	s_add_u32 s38, s36, 0x100
	s_addc_u32 s39, s37, 0
	s_cmp_eq_u32 s77, 40
	s_cselect_b32 s61, s5, s39
	s_cselect_b32 s60, s4, s38
	s_cselect_b32 s45, s7, s76
	s_cselect_b32 s44, s6, s73
	v_lshl_add_u64 v[216:217], s[36:37], 0, v[160:161]
	s_add_i32 m0, s54, 0xc000
	ds_read_b128 v[176:179], v189
	ds_read_b128 v[180:183], v189 offset:1024
	ds_read_b128 v[192:195], v189 offset:2048
	ds_read_b128 v[196:199], v189 offset:3072
	ds_read_b128 v[200:203], v189 offset:4096
	ds_read_b128 v[204:207], v189 offset:5120
	ds_read_b128 v[208:211], v189 offset:6144
	ds_read_b128 v[212:215], v189 offset:7168
	global_load_lds_dwordx4 v[216:217], off
	v_lshl_add_u64 v[216:217], s[36:37], 0, v[162:163]
	s_add_i32 m0, s54, 0xe000
	s_nop 0
	global_load_lds_dwordx4 v[216:217], off
	s_waitcnt vmcnt(8)
	s_waitcnt lgkmcnt(0)
	s_barrier

	v_mfma_f32_16x16x32_bf16 v[124:127], v[128:131], v[176:179], v[124:127]
	v_mfma_f32_16x16x32_bf16 v[120:123], v[136:139], v[176:179], v[120:123]
	v_mfma_f32_16x16x32_bf16 v[108:111], v[128:131], v[192:195], v[108:111]
	v_mfma_f32_16x16x32_bf16 v[104:107], v[136:139], v[192:195], v[104:107]
	v_mfma_f32_16x16x32_bf16 v[92:95], v[128:131], v[200:203], v[92:95]
	v_mfma_f32_16x16x32_bf16 v[88:91], v[136:139], v[200:203], v[88:91]
	v_mfma_f32_16x16x32_bf16 v[76:79], v[128:131], v[208:211], v[76:79]
	v_mfma_f32_16x16x32_bf16 v[72:75], v[136:139], v[208:211], v[72:75]
	v_mfma_f32_16x16x32_bf16 v[124:127], v[132:135], v[180:183], v[124:127]
	v_mfma_f32_16x16x32_bf16 v[120:123], v[140:143], v[180:183], v[120:123]
	v_mfma_f32_16x16x32_bf16 v[108:111], v[132:135], v[196:199], v[108:111]
	v_mfma_f32_16x16x32_bf16 v[104:107], v[140:143], v[196:199], v[104:107]
	v_mfma_f32_16x16x32_bf16 v[92:95], v[132:135], v[204:207], v[92:95]
	v_mfma_f32_16x16x32_bf16 v[88:91], v[140:143], v[204:207], v[88:91]
	v_mfma_f32_16x16x32_bf16 v[76:79], v[132:135], v[212:215], v[76:79]
	v_mfma_f32_16x16x32_bf16 v[72:75], v[140:143], v[212:215], v[72:75]

	v_mfma_f32_16x16x32_bf16 v[116:119], v[144:147], v[176:179], v[116:119]
	v_mfma_f32_16x16x32_bf16 v[112:115], v[168:171], v[176:179], v[112:115]
	v_mfma_f32_16x16x32_bf16 v[100:103], v[144:147], v[192:195], v[100:103]
	v_mfma_f32_16x16x32_bf16 v[96:99], v[168:171], v[192:195], v[96:99]
	v_mfma_f32_16x16x32_bf16 v[84:87], v[144:147], v[200:203], v[84:87]
	v_mfma_f32_16x16x32_bf16 v[80:83], v[168:171], v[200:203], v[80:83]
	v_mfma_f32_16x16x32_bf16 v[68:71], v[144:147], v[208:211], v[68:71]
	v_mfma_f32_16x16x32_bf16 v[64:67], v[168:171], v[208:211], v[64:67]
	v_mfma_f32_16x16x32_bf16 v[116:119], v[148:151], v[180:183], v[116:119]
	v_mfma_f32_16x16x32_bf16 v[112:115], v[172:175], v[180:183], v[112:115]
	v_mfma_f32_16x16x32_bf16 v[100:103], v[148:151], v[196:199], v[100:103]
	v_mfma_f32_16x16x32_bf16 v[96:99], v[172:175], v[196:199], v[96:99]
	v_mfma_f32_16x16x32_bf16 v[84:87], v[148:151], v[204:207], v[84:87]
	v_mfma_f32_16x16x32_bf16 v[80:83], v[172:175], v[204:207], v[80:83]
	v_mfma_f32_16x16x32_bf16 v[68:71], v[148:151], v[212:215], v[68:71]
	v_mfma_f32_16x16x32_bf16 v[64:67], v[172:175], v[212:215], v[64:67]

	s_barrier
	s_add_i32 s36, s65, s53
	v_lshl_add_u64 v[216:217], s[44:45], 0, v[154:155]
	s_mov_b32 m0, s36
	ds_read_b128 v[176:179], v189 offset:16384
	ds_read_b128 v[180:183], v189 offset:17408
	ds_read_b128 v[192:195], v189 offset:18432
	ds_read_b128 v[196:199], v189 offset:19456
	ds_read_b128 v[200:203], v189 offset:20480
	ds_read_b128 v[204:207], v189 offset:21504
	ds_read_b128 v[208:211], v189 offset:22528
	ds_read_b128 v[212:215], v189 offset:23552
	global_load_lds_dwordx4 v[216:217], off
	s_add_i32 m0, s36, 0x2000
	s_add_u32 s36, s44, 0xb0000
	v_lshl_add_u64 v[218:219], s[44:45], 0, v[158:159]
	s_addc_u32 s37, s45, 0
	s_add_i32 s78, s66, s53
	global_load_lds_dwordx4 v[218:219], off
	v_lshl_add_u64 v[220:221], s[36:37], 0, v[154:155]
	s_mov_b32 m0, s78
	v_lshl_add_u64 v[222:223], s[60:61], 0, v[156:157]
	global_load_lds_dwordx4 v[220:221], off
	v_lshl_add_u64 v[220:221], s[36:37], 0, v[158:159]
	s_add_i32 m0, s78, 0x2000
	s_nop 0
	global_load_lds_dwordx4 v[220:221], off
	v_lshl_add_u64 v[220:221], s[60:61], 0, v[152:153]
	s_mov_b32 m0, s54
	s_nop 0
	global_load_lds_dwordx4 v[220:221], off
	s_mov_b32 m0, s55
	s_nop 0
	global_load_lds_dwordx4 v[222:223], off
	s_waitcnt vmcnt(8)
	s_waitcnt lgkmcnt(0)
	s_barrier

	v_mfma_f32_16x16x32_bf16 v[60:63], v[128:131], v[176:179], v[60:63]
	v_mfma_f32_16x16x32_bf16 v[56:59], v[136:139], v[176:179], v[56:59]
	v_mfma_f32_16x16x32_bf16 v[44:47], v[128:131], v[192:195], v[44:47]
	v_mfma_f32_16x16x32_bf16 v[40:43], v[136:139], v[192:195], v[40:43]
	v_mfma_f32_16x16x32_bf16 v[28:31], v[128:131], v[200:203], v[28:31]
	v_mfma_f32_16x16x32_bf16 v[24:27], v[136:139], v[200:203], v[24:27]
	v_mfma_f32_16x16x32_bf16 v[12:15], v[128:131], v[208:211], v[12:15]
	v_mfma_f32_16x16x32_bf16 v[8:11], v[136:139], v[208:211], v[8:11]
	v_mfma_f32_16x16x32_bf16 v[60:63], v[132:135], v[180:183], v[60:63]
	v_mfma_f32_16x16x32_bf16 v[56:59], v[140:143], v[180:183], v[56:59]
	v_mfma_f32_16x16x32_bf16 v[44:47], v[132:135], v[196:199], v[44:47]
	v_mfma_f32_16x16x32_bf16 v[40:43], v[140:143], v[196:199], v[40:43]
	v_mfma_f32_16x16x32_bf16 v[28:31], v[132:135], v[204:207], v[28:31]
	v_mfma_f32_16x16x32_bf16 v[24:27], v[140:143], v[204:207], v[24:27]
	v_mfma_f32_16x16x32_bf16 v[12:15], v[132:135], v[212:215], v[12:15]
	v_mfma_f32_16x16x32_bf16 v[8:11], v[140:143], v[212:215], v[8:11]

	v_mfma_f32_16x16x32_bf16 v[52:55], v[144:147], v[176:179], v[52:55]
	v_mfma_f32_16x16x32_bf16 v[48:51], v[168:171], v[176:179], v[48:51]
	v_mfma_f32_16x16x32_bf16 v[36:39], v[144:147], v[192:195], v[36:39]
	v_mfma_f32_16x16x32_bf16 v[32:35], v[168:171], v[192:195], v[32:35]
	v_mfma_f32_16x16x32_bf16 v[20:23], v[144:147], v[200:203], v[20:23]
	v_mfma_f32_16x16x32_bf16 v[16:19], v[168:171], v[200:203], v[16:19]
	v_mfma_f32_16x16x32_bf16 v[4:7], v[144:147], v[208:211], v[4:7]
	v_mfma_f32_16x16x32_bf16 v[0:3], v[168:171], v[208:211], v[0:3]
	v_mfma_f32_16x16x32_bf16 v[52:55], v[148:151], v[180:183], v[52:55]
	v_mfma_f32_16x16x32_bf16 v[48:51], v[172:175], v[180:183], v[48:51]
	v_mfma_f32_16x16x32_bf16 v[36:39], v[148:151], v[196:199], v[36:39]
	v_mfma_f32_16x16x32_bf16 v[32:35], v[172:175], v[196:199], v[32:35]
	v_mfma_f32_16x16x32_bf16 v[20:23], v[148:151], v[204:207], v[20:23]
	v_mfma_f32_16x16x32_bf16 v[16:19], v[172:175], v[204:207], v[16:19]
	v_mfma_f32_16x16x32_bf16 v[4:7], v[148:151], v[212:215], v[4:7]
	v_mfma_f32_16x16x32_bf16 v[0:3], v[172:175], v[212:215], v[0:3]

	s_barrier
	s_add_i32 s78, 0, 0x18000
	s_add_i32 s79, 0, 0x1c000
	v_add_u32_e32 v140, s78, v185
	v_add_u32_e32 v172, s79, v185
	ds_read_b128 v[128:131], v140
	ds_read_b128 v[132:135], v140 offset:1024
	ds_read_b128 v[136:139], v140 offset:2048
	ds_read_b128 v[140:143], v140 offset:3072
	ds_read_b128 v[144:147], v172
	ds_read_b128 v[148:151], v172 offset:1024
	ds_read_b128 v[168:171], v172 offset:2048
	ds_read_b128 v[172:175], v172 offset:3072
	s_add_u32 s36, s60, 0xb0000
	s_addc_u32 s37, s61, 0
	s_mov_b32 m0, s56
	v_lshl_add_u64 v[224:225], s[36:37], 0, v[152:153]
	ds_read_b128 v[176:179], v189 offset:32768
	ds_read_b128 v[180:183], v189 offset:33792
	ds_read_b128 v[192:195], v189 offset:34816
	ds_read_b128 v[196:199], v189 offset:35840
	ds_read_b128 v[200:203], v189 offset:36864
	ds_read_b128 v[204:207], v189 offset:37888
	ds_read_b128 v[208:211], v189 offset:38912
	ds_read_b128 v[212:215], v189 offset:39936
	global_load_lds_dwordx4 v[224:225], off
	v_lshl_add_u64 v[224:225], s[36:37], 0, v[156:157]
	s_mov_b32 m0, s57
	s_nop 0
	global_load_lds_dwordx4 v[224:225], off
	s_waitcnt vmcnt(8)
	s_waitcnt lgkmcnt(0)
	s_barrier

	v_mfma_f32_16x16x32_bf16 v[124:127], v[128:131], v[176:179], v[124:127]
	v_mfma_f32_16x16x32_bf16 v[120:123], v[136:139], v[176:179], v[120:123]
	v_mfma_f32_16x16x32_bf16 v[108:111], v[128:131], v[192:195], v[108:111]
	v_mfma_f32_16x16x32_bf16 v[104:107], v[136:139], v[192:195], v[104:107]
	v_mfma_f32_16x16x32_bf16 v[92:95], v[128:131], v[200:203], v[92:95]
	v_mfma_f32_16x16x32_bf16 v[88:91], v[136:139], v[200:203], v[88:91]
	v_mfma_f32_16x16x32_bf16 v[76:79], v[128:131], v[208:211], v[76:79]
	v_mfma_f32_16x16x32_bf16 v[72:75], v[136:139], v[208:211], v[72:75]
	v_mfma_f32_16x16x32_bf16 v[124:127], v[132:135], v[180:183], v[124:127]
	v_mfma_f32_16x16x32_bf16 v[120:123], v[140:143], v[180:183], v[120:123]
	v_mfma_f32_16x16x32_bf16 v[108:111], v[132:135], v[196:199], v[108:111]
	v_mfma_f32_16x16x32_bf16 v[104:107], v[140:143], v[196:199], v[104:107]
	v_mfma_f32_16x16x32_bf16 v[92:95], v[132:135], v[204:207], v[92:95]
	v_mfma_f32_16x16x32_bf16 v[88:91], v[140:143], v[204:207], v[88:91]
	v_mfma_f32_16x16x32_bf16 v[76:79], v[132:135], v[212:215], v[76:79]
	v_mfma_f32_16x16x32_bf16 v[72:75], v[140:143], v[212:215], v[72:75]

	v_mfma_f32_16x16x32_bf16 v[116:119], v[144:147], v[176:179], v[116:119]
	v_mfma_f32_16x16x32_bf16 v[112:115], v[168:171], v[176:179], v[112:115]
	v_mfma_f32_16x16x32_bf16 v[100:103], v[144:147], v[192:195], v[100:103]
	v_mfma_f32_16x16x32_bf16 v[96:99], v[168:171], v[192:195], v[96:99]
	v_mfma_f32_16x16x32_bf16 v[84:87], v[144:147], v[200:203], v[84:87]
	v_mfma_f32_16x16x32_bf16 v[80:83], v[168:171], v[200:203], v[80:83]
	v_mfma_f32_16x16x32_bf16 v[68:71], v[144:147], v[208:211], v[68:71]
	v_mfma_f32_16x16x32_bf16 v[64:67], v[168:171], v[208:211], v[64:67]
	v_mfma_f32_16x16x32_bf16 v[116:119], v[148:151], v[180:183], v[116:119]
	v_mfma_f32_16x16x32_bf16 v[112:115], v[172:175], v[180:183], v[112:115]
	v_mfma_f32_16x16x32_bf16 v[100:103], v[148:151], v[196:199], v[100:103]
	v_mfma_f32_16x16x32_bf16 v[96:99], v[172:175], v[196:199], v[96:99]
	v_mfma_f32_16x16x32_bf16 v[84:87], v[148:151], v[204:207], v[84:87]
	v_mfma_f32_16x16x32_bf16 v[80:83], v[172:175], v[204:207], v[80:83]
	v_mfma_f32_16x16x32_bf16 v[68:71], v[148:151], v[212:215], v[68:71]
	v_mfma_f32_16x16x32_bf16 v[64:67], v[172:175], v[212:215], v[64:67]

	s_barrier
	s_add_i32 s36, s78, s53
	v_lshl_add_u64 v[216:217], v[216:217], 0, s[14:15]
	s_mov_b32 m0, s36
	ds_read_b128 v[176:179], v189 offset:49152
	ds_read_b128 v[180:183], v189 offset:50176
	ds_read_b128 v[192:195], v189 offset:51200
	ds_read_b128 v[196:199], v189 offset:52224
	ds_read_b128 v[200:203], v189 offset:53248
	ds_read_b128 v[204:207], v189 offset:54272
	ds_read_b128 v[208:211], v189 offset:55296
	ds_read_b128 v[212:215], v189 offset:56320
	global_load_lds_dwordx4 v[216:217], off
	s_add_i32 m0, s36, 0x2000
	s_add_u32 s36, s44, 0xb0080
	v_lshl_add_u64 v[216:217], v[218:219], 0, s[14:15]
	s_addc_u32 s37, s45, 0
	s_add_i32 s44, s79, s53
	global_load_lds_dwordx4 v[216:217], off
	v_lshl_add_u64 v[216:217], s[36:37], 0, v[154:155]
	s_mov_b32 m0, s44
	s_nop 0
	global_load_lds_dwordx4 v[216:217], off
	v_lshl_add_u64 v[216:217], s[36:37], 0, v[158:159]
	s_add_i32 m0, s44, 0x2000
	s_nop 0
	global_load_lds_dwordx4 v[216:217], off
	v_lshl_add_u64 v[216:217], v[220:221], 0, s[14:15]
	s_mov_b32 m0, s59
	s_nop 0
	global_load_lds_dwordx4 v[216:217], off
	v_lshl_add_u64 v[216:217], v[222:223], 0, s[14:15]
	s_mov_b32 m0, s62
	s_nop 0
	global_load_lds_dwordx4 v[216:217], off
	s_waitcnt vmcnt(8)
	s_waitcnt lgkmcnt(0)
	s_barrier

	v_mfma_f32_16x16x32_bf16 v[60:63], v[128:131], v[176:179], v[60:63]
	v_mfma_f32_16x16x32_bf16 v[56:59], v[136:139], v[176:179], v[56:59]
	v_mfma_f32_16x16x32_bf16 v[44:47], v[128:131], v[192:195], v[44:47]
	v_mfma_f32_16x16x32_bf16 v[40:43], v[136:139], v[192:195], v[40:43]
	v_mfma_f32_16x16x32_bf16 v[28:31], v[128:131], v[200:203], v[28:31]
	v_mfma_f32_16x16x32_bf16 v[24:27], v[136:139], v[200:203], v[24:27]
	v_mfma_f32_16x16x32_bf16 v[12:15], v[128:131], v[208:211], v[12:15]
	v_mfma_f32_16x16x32_bf16 v[8:11], v[136:139], v[208:211], v[8:11]
	v_mfma_f32_16x16x32_bf16 v[60:63], v[132:135], v[180:183], v[60:63]
	v_mfma_f32_16x16x32_bf16 v[56:59], v[140:143], v[180:183], v[56:59]
	v_mfma_f32_16x16x32_bf16 v[44:47], v[132:135], v[196:199], v[44:47]
	v_mfma_f32_16x16x32_bf16 v[40:43], v[140:143], v[196:199], v[40:43]
	v_mfma_f32_16x16x32_bf16 v[28:31], v[132:135], v[204:207], v[28:31]
	v_mfma_f32_16x16x32_bf16 v[24:27], v[140:143], v[204:207], v[24:27]
	v_mfma_f32_16x16x32_bf16 v[12:15], v[132:135], v[212:215], v[12:15]
	v_mfma_f32_16x16x32_bf16 v[8:11], v[140:143], v[212:215], v[8:11]

	v_mfma_f32_16x16x32_bf16 v[52:55], v[144:147], v[176:179], v[52:55]
	v_mfma_f32_16x16x32_bf16 v[48:51], v[168:171], v[176:179], v[48:51]
	v_mfma_f32_16x16x32_bf16 v[36:39], v[144:147], v[192:195], v[36:39]
	v_mfma_f32_16x16x32_bf16 v[32:35], v[168:171], v[192:195], v[32:35]
	v_mfma_f32_16x16x32_bf16 v[20:23], v[144:147], v[200:203], v[20:23]
	v_mfma_f32_16x16x32_bf16 v[16:19], v[168:171], v[200:203], v[16:19]
	v_mfma_f32_16x16x32_bf16 v[4:7], v[144:147], v[208:211], v[4:7]
	v_mfma_f32_16x16x32_bf16 v[0:3], v[168:171], v[208:211], v[0:3]
	v_mfma_f32_16x16x32_bf16 v[52:55], v[148:151], v[180:183], v[52:55]
	v_mfma_f32_16x16x32_bf16 v[48:51], v[172:175], v[180:183], v[48:51]
	v_mfma_f32_16x16x32_bf16 v[36:39], v[148:151], v[196:199], v[36:39]
	v_mfma_f32_16x16x32_bf16 v[32:35], v[172:175], v[196:199], v[32:35]
	v_mfma_f32_16x16x32_bf16 v[20:23], v[148:151], v[204:207], v[20:23]
	v_mfma_f32_16x16x32_bf16 v[16:19], v[172:175], v[204:207], v[16:19]
	v_mfma_f32_16x16x32_bf16 v[4:7], v[148:151], v[212:215], v[4:7]
	v_mfma_f32_16x16x32_bf16 v[0:3], v[172:175], v[212:215], v[0:3]

	s_barrier
	s_add_i32 s77, s77, 2
	s_add_u32 s73, s73, 0x100
	s_addc_u32 s76, s76, 0
	s_cmp_gt_u32 s77, 41
	s_mov_b64 s[36:37], s[38:39]
	s_cbranch_scc0 .LBB0_1080
	v_lshl_add_u32 v168, s72, 8, v184
	v_lshl_or_b32 v128, s18, 8, v186
	v_ashrrev_i32_e32 v169, 31, v168
	v_ashrrev_i32_e32 v129, 31, v128
	v_lshlrev_b64 v[130:131], 11, v[168:169]
	v_lshl_add_u64 v[130:131], s[34:35], 0, v[130:131]
	v_lshlrev_b64 v[170:171], 1, v[128:129]
	v_lshl_add_u64 v[200:201], v[130:131], 0, v[170:171]
	global_load_dwordx4 v[192:195], v[200:201], off
	global_load_dwordx4 v[196:199], v[200:201], off offset:256
	v_or_b32_e32 v180, 16, v168
	v_or_b32_e32 v176, 32, v168
	v_or_b32_e32 v172, 48, v168
	v_ashrrev_i32_e32 v181, 31, v180
	v_ashrrev_i32_e32 v177, 31, v176
	v_ashrrev_i32_e32 v173, 31, v172
	v_lshlrev_b64 v[128:129], 11, v[180:181]
	v_lshlrev_b64 v[130:131], 11, v[176:177]
	v_lshlrev_b64 v[132:133], 11, v[172:173]
	v_lshl_add_u64 v[128:129], s[34:35], 0, v[128:129]
	v_lshl_add_u64 v[130:131], s[34:35], 0, v[130:131]
	v_lshl_add_u64 v[132:133], s[34:35], 0, v[132:133]
	v_lshl_add_u64 v[182:183], v[128:129], 0, v[170:171]
	v_lshl_add_u64 v[178:179], v[130:131], 0, v[170:171]
	v_lshl_add_u64 v[174:175], v[132:133], 0, v[170:171]
	global_load_dwordx4 v[148:151], v[182:183], off
	global_load_dwordx4 v[144:147], v[182:183], off offset:256
	global_load_dwordx4 v[140:143], v[178:179], off
	global_load_dwordx4 v[136:139], v[178:179], off offset:256
	global_load_dwordx4 v[132:135], v[174:175], off
	global_load_dwordx4 v[128:131], v[174:175], off offset:256
	v_and_b32_e32 v202, 64, v190
	v_xor_b32_e32 v191, 16, v190
	v_add_u32_e32 v202, 64, v202
	v_xor_b32_e32 v203, 32, v190
	v_cmp_lt_i32_e32 vcc, v191, v202
	s_lshl_b32 s36, s18, 2
	s_ashr_i32 s37, s36, 31
	v_cndmask_b32_e32 v191, v190, v191, vcc
	v_cmp_lt_i32_e32 vcc, v203, v202
	v_lshlrev_b32_e32 v191, 2, v191
	s_waitcnt vmcnt(0)
	v_lshlrev_b32_e32 v202, 16, v192
	v_cndmask_b32_e32 v210, v190, v203, vcc
	v_and_b32_e32 v203, 0xffff0000, v192
	v_lshlrev_b32_e32 v192, 16, v193
	v_and_b32_e32 v193, 0xffff0000, v193
	v_lshlrev_b32_e32 v204, 16, v194
	v_and_b32_e32 v205, 0xffff0000, v194
	v_lshlrev_b32_e32 v194, 16, v195
	v_and_b32_e32 v195, 0xffff0000, v195
	v_lshlrev_b32_e32 v206, 16, v196
	v_and_b32_e32 v207, 0xffff0000, v196
	v_lshlrev_b32_e32 v196, 16, v197
	v_and_b32_e32 v197, 0xffff0000, v197
	v_lshlrev_b32_e32 v208, 16, v198
	v_and_b32_e32 v209, 0xffff0000, v198
	v_lshlrev_b32_e32 v198, 16, v199
	v_and_b32_e32 v199, 0xffff0000, v199
	v_pk_add_f32 v[126:127], v[126:127], v[192:193]
	v_pk_add_f32 v[124:125], v[124:125], v[202:203]
	v_pk_add_f32 v[122:123], v[122:123], v[194:195]
	v_pk_add_f32 v[120:121], v[120:121], v[204:205]
	v_pk_add_f32 v[118:119], v[118:119], v[196:197]
	v_pk_add_f32 v[116:117], v[116:117], v[206:207]
	v_pk_add_f32 v[192:193], v[114:115], v[198:199]
	v_pk_add_f32 v[194:195], v[112:113], v[208:209]
	v_cvt_pk_bf16_f32 v112, v124, v125
	v_cvt_pk_bf16_f32 v113, v126, v127
	v_mul_f32_e32 v114, v125, v125
	v_mul_f32_e32 v115, v127, v127
	v_mul_f32_e32 v125, v121, v121
	v_mul_f32_e32 v127, v123, v123
	v_mul_f32_e32 v196, v117, v117
	v_mul_f32_e32 v197, v119, v119
	v_mul_f32_e32 v198, v195, v195
	v_mul_f32_e32 v199, v193, v193
	v_fmac_f32_e32 v114, v124, v124
	v_fmac_f32_e32 v115, v126, v126
	v_fmac_f32_e32 v125, v120, v120
	v_fmac_f32_e32 v127, v122, v122
	v_fmac_f32_e32 v196, v116, v116
	v_fmac_f32_e32 v197, v118, v118
	v_fmac_f32_e32 v198, v194, v194
	v_fmac_f32_e32 v199, v192, v192
	v_add_f32_e32 v114, v114, v115
	v_add_f32_e32 v115, v125, v127
	v_add_f32_e32 v124, v196, v197
	v_add_f32_e32 v125, v198, v199
	v_add_f32_e32 v114, v114, v115
	v_add_f32_e32 v115, v124, v125
	v_add_f32_e32 v124, v114, v115
	ds_bpermute_b32 v125, v191, v124
	v_cvt_pk_bf16_f32 v114, v120, v121
	v_cvt_pk_bf16_f32 v115, v122, v123
	global_store_dwordx4 v[200:201], v[112:115], off
	v_cvt_pk_bf16_f32 v116, v116, v117
	v_cvt_pk_bf16_f32 v117, v118, v119
	s_waitcnt lgkmcnt(0)
	v_add_f32_e32 v113, v124, v125
	v_lshlrev_b32_e32 v112, 2, v210
	ds_bpermute_b32 v114, v112, v113
	v_cvt_pk_bf16_f32 v118, v194, v195
	v_cvt_pk_bf16_f32 v119, v192, v193
	global_store_dwordx4 v[200:201], v[116:119], off offset:256
	s_and_saveexec_b64 s[38:39], s[0:1]
	s_cbranch_execz .LBB0_1083
	s_waitcnt lgkmcnt(0)
	v_add_f32_e32 v113, v113, v114
	v_lshlrev_b64 v[114:115], 6, v[168:169]
	v_lshl_add_u64 v[114:115], s[74:75], 0, v[114:115]
	v_lshl_add_u64 v[114:115], s[36:37], 2, v[114:115]
	s_lshl_b32 s18, s58, 2
	v_lshl_add_u64 v[114:115], v[114:115], 0, s[18:19]
	global_store_dword v[114:115], v113, off

.LBB0_1181:
	ds_read_b128 v[128:131], v175
	ds_read_b128 v[152:155], v175 offset:1024
	ds_read_b128 v[156:159], v175 offset:2048
	ds_read_b128 v[160:163], v175 offset:3072
	ds_read_b128 v[164:167], v176
	ds_read_b128 v[168:171], v176 offset:1024
	ds_read_b128 v[180:183], v176 offset:2048
	ds_read_b128 v[184:187], v176 offset:3072
	s_add_u32 s57, s2, 0xfffc0080
	s_addc_u32 s58, s3, -1
	s_cmp_eq_u32 s56, 12
	s_cselect_b32 s65, s37, s58
	s_cselect_b32 s64, s52, s57
	s_cselect_b32 s63, s39, s55
	s_cselect_b32 s62, s53, s54
	v_lshl_add_u64 v[220:221], s[2:3], 0, v[144:145]
	s_add_i32 m0, s79, 0xc000
	ds_read_b128 v[188:191], v177
	ds_read_b128 v[192:195], v177 offset:1024
	ds_read_b128 v[196:199], v177 offset:2048
	ds_read_b128 v[200:203], v177 offset:3072
	ds_read_b128 v[204:207], v177 offset:4096
	ds_read_b128 v[208:211], v177 offset:5120
	ds_read_b128 v[212:215], v177 offset:6144
	ds_read_b128 v[216:219], v177 offset:7168
	global_load_lds_dwordx4 v[220:221], off
	v_lshl_add_u64 v[220:221], s[2:3], 0, v[146:147]
	s_add_i32 m0, s79, 0xe000
	s_nop 0
	global_load_lds_dwordx4 v[220:221], off
	s_waitcnt vmcnt(8)
	s_waitcnt lgkmcnt(0)
	s_barrier

	v_mfma_f32_16x16x32_bf16 v[124:127], v[128:131], v[188:191], v[124:127]
	v_mfma_f32_16x16x32_bf16 v[120:123], v[156:159], v[188:191], v[120:123]
	v_mfma_f32_16x16x32_bf16 v[116:119], v[128:131], v[196:199], v[116:119]
	v_mfma_f32_16x16x32_bf16 v[112:115], v[156:159], v[196:199], v[112:115]
	v_mfma_f32_16x16x32_bf16 v[100:103], v[128:131], v[204:207], v[100:103]
	v_mfma_f32_16x16x32_bf16 v[96:99], v[156:159], v[204:207], v[96:99]
	v_mfma_f32_16x16x32_bf16 v[80:83], v[128:131], v[212:215], v[80:83]
	v_mfma_f32_16x16x32_bf16 v[76:79], v[156:159], v[212:215], v[76:79]
	v_mfma_f32_16x16x32_bf16 v[124:127], v[152:155], v[192:195], v[124:127]
	v_mfma_f32_16x16x32_bf16 v[120:123], v[160:163], v[192:195], v[120:123]
	v_mfma_f32_16x16x32_bf16 v[116:119], v[152:155], v[200:203], v[116:119]
	v_mfma_f32_16x16x32_bf16 v[112:115], v[160:163], v[200:203], v[112:115]
	v_mfma_f32_16x16x32_bf16 v[100:103], v[152:155], v[208:211], v[100:103]
	v_mfma_f32_16x16x32_bf16 v[96:99], v[160:163], v[208:211], v[96:99]
	v_mfma_f32_16x16x32_bf16 v[80:83], v[152:155], v[216:219], v[80:83]
	v_mfma_f32_16x16x32_bf16 v[76:79], v[160:163], v[216:219], v[76:79]

	v_mfma_f32_16x16x32_bf16 v[108:111], v[164:167], v[188:191], v[108:111]
	v_mfma_f32_16x16x32_bf16 v[104:107], v[180:183], v[188:191], v[104:107]
	v_mfma_f32_16x16x32_bf16 v[92:95], v[164:167], v[196:199], v[92:95]
	v_mfma_f32_16x16x32_bf16 v[88:91], v[180:183], v[196:199], v[88:91]
	v_mfma_f32_16x16x32_bf16 v[84:87], v[164:167], v[204:207], v[84:87]
	v_mfma_f32_16x16x32_bf16 v[72:75], v[180:183], v[204:207], v[72:75]
	v_mfma_f32_16x16x32_bf16 v[68:71], v[164:167], v[212:215], v[68:71]
	v_mfma_f32_16x16x32_bf16 v[32:35], v[180:183], v[212:215], v[32:35]
	v_mfma_f32_16x16x32_bf16 v[108:111], v[168:171], v[192:195], v[108:111]
	v_mfma_f32_16x16x32_bf16 v[104:107], v[184:187], v[192:195], v[104:107]
	v_mfma_f32_16x16x32_bf16 v[92:95], v[168:171], v[200:203], v[92:95]
	v_mfma_f32_16x16x32_bf16 v[88:91], v[184:187], v[200:203], v[88:91]
	v_mfma_f32_16x16x32_bf16 v[84:87], v[168:171], v[208:211], v[84:87]
	v_mfma_f32_16x16x32_bf16 v[72:75], v[184:187], v[208:211], v[72:75]
	v_mfma_f32_16x16x32_bf16 v[68:71], v[168:171], v[216:219], v[68:71]
	v_mfma_f32_16x16x32_bf16 v[32:35], v[184:187], v[216:219], v[32:35]

	s_barrier
	s_add_i32 s57, s89, s66
	v_lshl_add_u64 v[220:221], s[62:63], 0, v[134:135]
	s_mov_b32 m0, s57
	ds_read_b128 v[188:191], v177 offset:16384
	ds_read_b128 v[192:195], v177 offset:17408
	ds_read_b128 v[196:199], v177 offset:18432
	ds_read_b128 v[200:203], v177 offset:19456
	ds_read_b128 v[204:207], v177 offset:20480
	ds_read_b128 v[208:211], v177 offset:21504
	ds_read_b128 v[212:215], v177 offset:22528
	ds_read_b128 v[216:219], v177 offset:23552
	global_load_lds_dwordx4 v[220:221], off
	s_add_i32 m0, s57, 0x2000
	s_add_u32 s58, s62, 0x40000
	v_lshl_add_u64 v[222:223], s[62:63], 0, v[138:139]
	s_addc_u32 s59, s63, 0
	s_add_i32 s57, s90, s66
	global_load_lds_dwordx4 v[222:223], off
	v_lshl_add_u64 v[224:225], s[58:59], 0, v[134:135]
	s_mov_b32 m0, s57
	v_lshl_add_u64 v[226:227], s[64:65], 0, v[136:137]
	global_load_lds_dwordx4 v[224:225], off
	v_lshl_add_u64 v[224:225], s[58:59], 0, v[138:139]
	s_add_i32 m0, s57, 0x2000
	s_nop 0
	global_load_lds_dwordx4 v[224:225], off
	v_lshl_add_u64 v[224:225], s[64:65], 0, v[132:133]
	s_mov_b32 m0, s79
	s_nop 0
	global_load_lds_dwordx4 v[224:225], off
	s_mov_b32 m0, s80
	s_nop 0
	global_load_lds_dwordx4 v[226:227], off
	s_waitcnt vmcnt(8)
	s_waitcnt lgkmcnt(0)
	s_barrier

	v_mfma_f32_16x16x32_bf16 v[64:67], v[128:131], v[188:191], v[64:67]
	v_mfma_f32_16x16x32_bf16 v[60:63], v[156:159], v[188:191], v[60:63]
	v_mfma_f32_16x16x32_bf16 v[56:59], v[128:131], v[196:199], v[56:59]
	v_mfma_f32_16x16x32_bf16 v[52:55], v[156:159], v[196:199], v[52:55]
	v_mfma_f32_16x16x32_bf16 v[48:51], v[128:131], v[204:207], v[48:51]
	v_mfma_f32_16x16x32_bf16 v[44:47], v[156:159], v[204:207], v[44:47]
	v_mfma_f32_16x16x32_bf16 v[40:43], v[128:131], v[212:215], v[40:43]
	v_mfma_f32_16x16x32_bf16 v[36:39], v[156:159], v[212:215], v[36:39]
	v_mfma_f32_16x16x32_bf16 v[64:67], v[152:155], v[192:195], v[64:67]
	v_mfma_f32_16x16x32_bf16 v[60:63], v[160:163], v[192:195], v[60:63]
	v_mfma_f32_16x16x32_bf16 v[56:59], v[152:155], v[200:203], v[56:59]
	v_mfma_f32_16x16x32_bf16 v[52:55], v[160:163], v[200:203], v[52:55]
	v_mfma_f32_16x16x32_bf16 v[48:51], v[152:155], v[208:211], v[48:51]
	v_mfma_f32_16x16x32_bf16 v[44:47], v[160:163], v[208:211], v[44:47]
	v_mfma_f32_16x16x32_bf16 v[40:43], v[152:155], v[216:219], v[40:43]
	v_mfma_f32_16x16x32_bf16 v[36:39], v[160:163], v[216:219], v[36:39]

	v_mfma_f32_16x16x32_bf16 v[28:31], v[164:167], v[188:191], v[28:31]
	v_mfma_f32_16x16x32_bf16 v[24:27], v[180:183], v[188:191], v[24:27]
	v_mfma_f32_16x16x32_bf16 v[20:23], v[164:167], v[196:199], v[20:23]
	v_mfma_f32_16x16x32_bf16 v[16:19], v[180:183], v[196:199], v[16:19]
	v_mfma_f32_16x16x32_bf16 v[12:15], v[164:167], v[204:207], v[12:15]
	v_mfma_f32_16x16x32_bf16 v[8:11], v[180:183], v[204:207], v[8:11]
	v_mfma_f32_16x16x32_bf16 v[4:7], v[164:167], v[212:215], v[4:7]
	v_mfma_f32_16x16x32_bf16 v[0:3], v[180:183], v[212:215], v[0:3]
	v_mfma_f32_16x16x32_bf16 v[28:31], v[168:171], v[192:195], v[28:31]
	v_mfma_f32_16x16x32_bf16 v[24:27], v[184:187], v[192:195], v[24:27]
	v_mfma_f32_16x16x32_bf16 v[20:23], v[168:171], v[200:203], v[20:23]
	v_mfma_f32_16x16x32_bf16 v[16:19], v[184:187], v[200:203], v[16:19]
	v_mfma_f32_16x16x32_bf16 v[12:15], v[168:171], v[208:211], v[12:15]
	v_mfma_f32_16x16x32_bf16 v[8:11], v[184:187], v[208:211], v[8:11]
	v_mfma_f32_16x16x32_bf16 v[4:7], v[168:171], v[216:219], v[4:7]
	v_mfma_f32_16x16x32_bf16 v[0:3], v[184:187], v[216:219], v[0:3]

	s_barrier
	s_add_i32 s57, 0, 0x18000
	v_add_u32_e32 v140, s57, v173
	s_add_i32 s68, 0, 0x1c000
	ds_read_b128 v[128:131], v140
	ds_read_b128 v[152:155], v140 offset:1024
	ds_read_b128 v[156:159], v140 offset:2048
	ds_read_b128 v[160:163], v140 offset:3072
	v_add_u32_e32 v140, s68, v173
	ds_read_b128 v[164:167], v140
	ds_read_b128 v[168:171], v140 offset:1024
	ds_read_b128 v[180:183], v140 offset:2048
	ds_read_b128 v[184:187], v140 offset:3072
	s_add_u32 s58, s64, 0x40000
	s_addc_u32 s59, s65, 0
	s_mov_b32 m0, s81
	v_lshl_add_u64 v[228:229], s[58:59], 0, v[132:133]
	ds_read_b128 v[188:191], v177 offset:32768
	ds_read_b128 v[192:195], v177 offset:33792
	ds_read_b128 v[196:199], v177 offset:34816
	ds_read_b128 v[200:203], v177 offset:35840
	ds_read_b128 v[204:207], v177 offset:36864
	ds_read_b128 v[208:211], v177 offset:37888
	ds_read_b128 v[212:215], v177 offset:38912
	ds_read_b128 v[216:219], v177 offset:39936
	global_load_lds_dwordx4 v[228:229], off
	v_lshl_add_u64 v[228:229], s[58:59], 0, v[136:137]
	s_mov_b32 m0, s82
	s_nop 0
	global_load_lds_dwordx4 v[228:229], off
	s_waitcnt vmcnt(8)
	s_waitcnt lgkmcnt(0)
	s_barrier

	v_mfma_f32_16x16x32_bf16 v[124:127], v[128:131], v[188:191], v[124:127]
	v_mfma_f32_16x16x32_bf16 v[120:123], v[156:159], v[188:191], v[120:123]
	v_mfma_f32_16x16x32_bf16 v[116:119], v[128:131], v[196:199], v[116:119]
	v_mfma_f32_16x16x32_bf16 v[112:115], v[156:159], v[196:199], v[112:115]
	v_mfma_f32_16x16x32_bf16 v[100:103], v[128:131], v[204:207], v[100:103]
	v_mfma_f32_16x16x32_bf16 v[96:99], v[156:159], v[204:207], v[96:99]
	v_mfma_f32_16x16x32_bf16 v[80:83], v[128:131], v[212:215], v[80:83]
	v_mfma_f32_16x16x32_bf16 v[76:79], v[156:159], v[212:215], v[76:79]
	v_mfma_f32_16x16x32_bf16 v[124:127], v[152:155], v[192:195], v[124:127]
	v_mfma_f32_16x16x32_bf16 v[120:123], v[160:163], v[192:195], v[120:123]
	v_mfma_f32_16x16x32_bf16 v[116:119], v[152:155], v[200:203], v[116:119]
	v_mfma_f32_16x16x32_bf16 v[112:115], v[160:163], v[200:203], v[112:115]
	v_mfma_f32_16x16x32_bf16 v[100:103], v[152:155], v[208:211], v[100:103]
	v_mfma_f32_16x16x32_bf16 v[96:99], v[160:163], v[208:211], v[96:99]
	v_mfma_f32_16x16x32_bf16 v[80:83], v[152:155], v[216:219], v[80:83]
	v_mfma_f32_16x16x32_bf16 v[76:79], v[160:163], v[216:219], v[76:79]

	v_mfma_f32_16x16x32_bf16 v[108:111], v[164:167], v[188:191], v[108:111]
	v_mfma_f32_16x16x32_bf16 v[104:107], v[180:183], v[188:191], v[104:107]
	v_mfma_f32_16x16x32_bf16 v[92:95], v[164:167], v[196:199], v[92:95]
	v_mfma_f32_16x16x32_bf16 v[88:91], v[180:183], v[196:199], v[88:91]
	v_mfma_f32_16x16x32_bf16 v[84:87], v[164:167], v[204:207], v[84:87]
	v_mfma_f32_16x16x32_bf16 v[72:75], v[180:183], v[204:207], v[72:75]
	v_mfma_f32_16x16x32_bf16 v[68:71], v[164:167], v[212:215], v[68:71]
	v_mfma_f32_16x16x32_bf16 v[32:35], v[180:183], v[212:215], v[32:35]
	v_mfma_f32_16x16x32_bf16 v[108:111], v[168:171], v[192:195], v[108:111]
	v_mfma_f32_16x16x32_bf16 v[104:107], v[184:187], v[192:195], v[104:107]
	v_mfma_f32_16x16x32_bf16 v[92:95], v[168:171], v[200:203], v[92:95]
	v_mfma_f32_16x16x32_bf16 v[88:91], v[184:187], v[200:203], v[88:91]
	v_mfma_f32_16x16x32_bf16 v[84:87], v[168:171], v[208:211], v[84:87]
	v_mfma_f32_16x16x32_bf16 v[72:75], v[184:187], v[208:211], v[72:75]
	v_mfma_f32_16x16x32_bf16 v[68:71], v[168:171], v[216:219], v[68:71]
	v_mfma_f32_16x16x32_bf16 v[32:35], v[184:187], v[216:219], v[32:35]

	s_barrier
	s_add_i32 s57, s57, s66
	v_lshl_add_u64 v[220:221], v[220:221], 0, s[12:13]
	s_mov_b32 m0, s57
	ds_read_b128 v[188:191], v177 offset:49152
	ds_read_b128 v[192:195], v177 offset:50176
	ds_read_b128 v[196:199], v177 offset:51200
	ds_read_b128 v[200:203], v177 offset:52224
	ds_read_b128 v[204:207], v177 offset:53248
	ds_read_b128 v[208:211], v177 offset:54272
	ds_read_b128 v[212:215], v177 offset:55296
	ds_read_b128 v[216:219], v177 offset:56320
	global_load_lds_dwordx4 v[220:221], off
	s_add_i32 m0, s57, 0x2000
	s_add_u32 s58, s62, 0x40080
	v_lshl_add_u64 v[220:221], v[222:223], 0, s[12:13]
	s_addc_u32 s59, s63, 0
	s_add_i32 s57, s68, s66
	global_load_lds_dwordx4 v[220:221], off
	v_lshl_add_u64 v[220:221], s[58:59], 0, v[134:135]
	s_mov_b32 m0, s57
	s_nop 0
	global_load_lds_dwordx4 v[220:221], off
	v_lshl_add_u64 v[220:221], s[58:59], 0, v[138:139]
	s_add_i32 m0, s57, 0x2000
	s_nop 0
	global_load_lds_dwordx4 v[220:221], off
	v_lshl_add_u64 v[220:221], v[224:225], 0, s[12:13]
	s_mov_b32 m0, s86
	s_nop 0
	global_load_lds_dwordx4 v[220:221], off
	v_lshl_add_u64 v[220:221], v[226:227], 0, s[12:13]
	s_mov_b32 m0, s87
	s_nop 0
	global_load_lds_dwordx4 v[220:221], off
	s_waitcnt vmcnt(8)
	s_waitcnt lgkmcnt(0)
	s_barrier

	v_mfma_f32_16x16x32_bf16 v[64:67], v[128:131], v[188:191], v[64:67]
	v_mfma_f32_16x16x32_bf16 v[60:63], v[156:159], v[188:191], v[60:63]
	v_mfma_f32_16x16x32_bf16 v[56:59], v[128:131], v[196:199], v[56:59]
	v_mfma_f32_16x16x32_bf16 v[52:55], v[156:159], v[196:199], v[52:55]
	v_mfma_f32_16x16x32_bf16 v[48:51], v[128:131], v[204:207], v[48:51]
	v_mfma_f32_16x16x32_bf16 v[44:47], v[156:159], v[204:207], v[44:47]
	v_mfma_f32_16x16x32_bf16 v[40:43], v[128:131], v[212:215], v[40:43]
	v_mfma_f32_16x16x32_bf16 v[36:39], v[156:159], v[212:215], v[36:39]
	v_mfma_f32_16x16x32_bf16 v[64:67], v[152:155], v[192:195], v[64:67]
	v_mfma_f32_16x16x32_bf16 v[60:63], v[160:163], v[192:195], v[60:63]
	v_mfma_f32_16x16x32_bf16 v[56:59], v[152:155], v[200:203], v[56:59]
	v_mfma_f32_16x16x32_bf16 v[52:55], v[160:163], v[200:203], v[52:55]
	v_mfma_f32_16x16x32_bf16 v[48:51], v[152:155], v[208:211], v[48:51]
	v_mfma_f32_16x16x32_bf16 v[44:47], v[160:163], v[208:211], v[44:47]
	v_mfma_f32_16x16x32_bf16 v[40:43], v[152:155], v[216:219], v[40:43]
	v_mfma_f32_16x16x32_bf16 v[36:39], v[160:163], v[216:219], v[36:39]

	v_mfma_f32_16x16x32_bf16 v[28:31], v[164:167], v[188:191], v[28:31]
	v_mfma_f32_16x16x32_bf16 v[24:27], v[180:183], v[188:191], v[24:27]
	v_mfma_f32_16x16x32_bf16 v[20:23], v[164:167], v[196:199], v[20:23]
	v_mfma_f32_16x16x32_bf16 v[16:19], v[180:183], v[196:199], v[16:19]
	v_mfma_f32_16x16x32_bf16 v[12:15], v[164:167], v[204:207], v[12:15]
	v_mfma_f32_16x16x32_bf16 v[8:11], v[180:183], v[204:207], v[8:11]
	v_mfma_f32_16x16x32_bf16 v[4:7], v[164:167], v[212:215], v[4:7]
	v_mfma_f32_16x16x32_bf16 v[0:3], v[180:183], v[212:215], v[0:3]
	v_mfma_f32_16x16x32_bf16 v[28:31], v[168:171], v[192:195], v[28:31]
	v_mfma_f32_16x16x32_bf16 v[24:27], v[184:187], v[192:195], v[24:27]
	v_mfma_f32_16x16x32_bf16 v[20:23], v[168:171], v[200:203], v[20:23]
	v_mfma_f32_16x16x32_bf16 v[16:19], v[184:187], v[200:203], v[16:19]
	v_mfma_f32_16x16x32_bf16 v[12:15], v[168:171], v[208:211], v[12:15]
	v_mfma_f32_16x16x32_bf16 v[8:11], v[184:187], v[208:211], v[8:11]
	v_mfma_f32_16x16x32_bf16 v[4:7], v[168:171], v[216:219], v[4:7]
	v_mfma_f32_16x16x32_bf16 v[0:3], v[184:187], v[216:219], v[0:3]

	s_barrier
	s_add_i32 s56, s56, 2
	s_add_u32 s2, s2, 0x100
	s_addc_u32 s3, s3, 0
	s_add_u32 s54, s54, 0x100
	s_addc_u32 s55, s55, 0
	s_cmp_gt_u32 s56, 13
	s_cbranch_scc0 .LBB0_1181
	s_and_b64 vcc, exec, s[14:15]
	s_cbranch_vccz .LBB0_1184
	s_barrier

.LBB0_1530:
	ds_read_b128 v[128:131], v187
	ds_read_b128 v[132:135], v187 offset:1024
	ds_read_b128 v[136:139], v187 offset:2048
	ds_read_b128 v[140:143], v187 offset:3072
	ds_read_b128 v[144:147], v188
	ds_read_b128 v[148:151], v188 offset:1024
	ds_read_b128 v[168:171], v188 offset:2048
	ds_read_b128 v[172:175], v188 offset:3072
	s_add_u32 s36, s24, 0xfffc0080
	s_addc_u32 s37, s25, -1
	s_cmp_eq_u32 s65, 12
	s_cselect_b32 s39, s11, s37
	s_cselect_b32 s38, s61, s36
	s_cselect_b32 s37, s13, s64
	s_cselect_b32 s36, s62, s63
	v_lshl_add_u64 v[216:217], s[24:25], 0, v[160:161]
	s_add_i32 m0, s46, 0xc000
	ds_read_b128 v[176:179], v189
	ds_read_b128 v[180:183], v189 offset:1024
	ds_read_b128 v[192:195], v189 offset:2048
	ds_read_b128 v[196:199], v189 offset:3072
	ds_read_b128 v[200:203], v189 offset:4096
	ds_read_b128 v[204:207], v189 offset:5120
	ds_read_b128 v[208:211], v189 offset:6144
	ds_read_b128 v[212:215], v189 offset:7168
	global_load_lds_dwordx4 v[216:217], off
	v_lshl_add_u64 v[216:217], s[24:25], 0, v[162:163]
	s_add_i32 m0, s46, 0xe000
	s_nop 0
	global_load_lds_dwordx4 v[216:217], off
	s_waitcnt vmcnt(8)
	s_waitcnt lgkmcnt(0)
	s_barrier

	v_mfma_f32_16x16x32_bf16 v[124:127], v[128:131], v[176:179], v[124:127]
	v_mfma_f32_16x16x32_bf16 v[120:123], v[136:139], v[176:179], v[120:123]
	v_mfma_f32_16x16x32_bf16 v[108:111], v[128:131], v[192:195], v[108:111]
	v_mfma_f32_16x16x32_bf16 v[104:107], v[136:139], v[192:195], v[104:107]
	v_mfma_f32_16x16x32_bf16 v[92:95], v[128:131], v[200:203], v[92:95]
	v_mfma_f32_16x16x32_bf16 v[88:91], v[136:139], v[200:203], v[88:91]
	v_mfma_f32_16x16x32_bf16 v[76:79], v[128:131], v[208:211], v[76:79]
	v_mfma_f32_16x16x32_bf16 v[72:75], v[136:139], v[208:211], v[72:75]
	v_mfma_f32_16x16x32_bf16 v[124:127], v[132:135], v[180:183], v[124:127]
	v_mfma_f32_16x16x32_bf16 v[120:123], v[140:143], v[180:183], v[120:123]
	v_mfma_f32_16x16x32_bf16 v[108:111], v[132:135], v[196:199], v[108:111]
	v_mfma_f32_16x16x32_bf16 v[104:107], v[140:143], v[196:199], v[104:107]
	v_mfma_f32_16x16x32_bf16 v[92:95], v[132:135], v[204:207], v[92:95]
	v_mfma_f32_16x16x32_bf16 v[88:91], v[140:143], v[204:207], v[88:91]
	v_mfma_f32_16x16x32_bf16 v[76:79], v[132:135], v[212:215], v[76:79]
	v_mfma_f32_16x16x32_bf16 v[72:75], v[140:143], v[212:215], v[72:75]

	v_mfma_f32_16x16x32_bf16 v[116:119], v[144:147], v[176:179], v[116:119]
	v_mfma_f32_16x16x32_bf16 v[112:115], v[168:171], v[176:179], v[112:115]
	v_mfma_f32_16x16x32_bf16 v[100:103], v[144:147], v[192:195], v[100:103]
	v_mfma_f32_16x16x32_bf16 v[96:99], v[168:171], v[192:195], v[96:99]
	v_mfma_f32_16x16x32_bf16 v[84:87], v[144:147], v[200:203], v[84:87]
	v_mfma_f32_16x16x32_bf16 v[80:83], v[168:171], v[200:203], v[80:83]
	v_mfma_f32_16x16x32_bf16 v[68:71], v[144:147], v[208:211], v[68:71]
	v_mfma_f32_16x16x32_bf16 v[64:67], v[168:171], v[208:211], v[64:67]
	v_mfma_f32_16x16x32_bf16 v[116:119], v[148:151], v[180:183], v[116:119]
	v_mfma_f32_16x16x32_bf16 v[112:115], v[172:175], v[180:183], v[112:115]
	v_mfma_f32_16x16x32_bf16 v[100:103], v[148:151], v[196:199], v[100:103]
	v_mfma_f32_16x16x32_bf16 v[96:99], v[172:175], v[196:199], v[96:99]
	v_mfma_f32_16x16x32_bf16 v[84:87], v[148:151], v[204:207], v[84:87]
	v_mfma_f32_16x16x32_bf16 v[80:83], v[172:175], v[204:207], v[80:83]
	v_mfma_f32_16x16x32_bf16 v[68:71], v[148:151], v[212:215], v[68:71]
	v_mfma_f32_16x16x32_bf16 v[64:67], v[172:175], v[212:215], v[64:67]

	s_barrier
	s_add_i32 s66, s55, s45
	v_lshl_add_u64 v[216:217], s[36:37], 0, v[154:155]
	s_mov_b32 m0, s66
	ds_read_b128 v[176:179], v189 offset:16384
	ds_read_b128 v[180:183], v189 offset:17408
	ds_read_b128 v[192:195], v189 offset:18432
	ds_read_b128 v[196:199], v189 offset:19456
	ds_read_b128 v[200:203], v189 offset:20480
	ds_read_b128 v[204:207], v189 offset:21504
	ds_read_b128 v[208:211], v189 offset:22528
	ds_read_b128 v[212:215], v189 offset:23552
	global_load_lds_dwordx4 v[216:217], off
	s_add_i32 m0, s66, 0x2000
	s_add_u32 s66, s36, 0x40000
	v_lshl_add_u64 v[218:219], s[36:37], 0, v[158:159]
	s_addc_u32 s67, s37, 0
	s_add_i32 s68, s56, s45
	global_load_lds_dwordx4 v[218:219], off
	v_lshl_add_u64 v[220:221], s[66:67], 0, v[154:155]
	s_mov_b32 m0, s68
	v_lshl_add_u64 v[222:223], s[38:39], 0, v[156:157]
	global_load_lds_dwordx4 v[220:221], off
	v_lshl_add_u64 v[220:221], s[66:67], 0, v[158:159]
	s_add_i32 m0, s68, 0x2000
	s_nop 0
	global_load_lds_dwordx4 v[220:221], off
	v_lshl_add_u64 v[220:221], s[38:39], 0, v[152:153]
	s_mov_b32 m0, s46
	s_nop 0
	global_load_lds_dwordx4 v[220:221], off
	s_mov_b32 m0, s47
	s_nop 0
	global_load_lds_dwordx4 v[222:223], off
	s_waitcnt vmcnt(8)
	s_waitcnt lgkmcnt(0)
	s_barrier

	v_mfma_f32_16x16x32_bf16 v[60:63], v[128:131], v[176:179], v[60:63]
	v_mfma_f32_16x16x32_bf16 v[56:59], v[136:139], v[176:179], v[56:59]
	v_mfma_f32_16x16x32_bf16 v[44:47], v[128:131], v[192:195], v[44:47]
	v_mfma_f32_16x16x32_bf16 v[40:43], v[136:139], v[192:195], v[40:43]
	v_mfma_f32_16x16x32_bf16 v[28:31], v[128:131], v[200:203], v[28:31]
	v_mfma_f32_16x16x32_bf16 v[24:27], v[136:139], v[200:203], v[24:27]
	v_mfma_f32_16x16x32_bf16 v[12:15], v[128:131], v[208:211], v[12:15]
	v_mfma_f32_16x16x32_bf16 v[8:11], v[136:139], v[208:211], v[8:11]
	v_mfma_f32_16x16x32_bf16 v[60:63], v[132:135], v[180:183], v[60:63]
	v_mfma_f32_16x16x32_bf16 v[56:59], v[140:143], v[180:183], v[56:59]
	v_mfma_f32_16x16x32_bf16 v[44:47], v[132:135], v[196:199], v[44:47]
	v_mfma_f32_16x16x32_bf16 v[40:43], v[140:143], v[196:199], v[40:43]
	v_mfma_f32_16x16x32_bf16 v[28:31], v[132:135], v[204:207], v[28:31]
	v_mfma_f32_16x16x32_bf16 v[24:27], v[140:143], v[204:207], v[24:27]
	v_mfma_f32_16x16x32_bf16 v[12:15], v[132:135], v[212:215], v[12:15]
	v_mfma_f32_16x16x32_bf16 v[8:11], v[140:143], v[212:215], v[8:11]

	v_mfma_f32_16x16x32_bf16 v[52:55], v[144:147], v[176:179], v[52:55]
	v_mfma_f32_16x16x32_bf16 v[48:51], v[168:171], v[176:179], v[48:51]
	v_mfma_f32_16x16x32_bf16 v[36:39], v[144:147], v[192:195], v[36:39]
	v_mfma_f32_16x16x32_bf16 v[32:35], v[168:171], v[192:195], v[32:35]
	v_mfma_f32_16x16x32_bf16 v[20:23], v[144:147], v[200:203], v[20:23]
	v_mfma_f32_16x16x32_bf16 v[16:19], v[168:171], v[200:203], v[16:19]
	v_mfma_f32_16x16x32_bf16 v[4:7], v[144:147], v[208:211], v[4:7]
	v_mfma_f32_16x16x32_bf16 v[0:3], v[168:171], v[208:211], v[0:3]
	v_mfma_f32_16x16x32_bf16 v[52:55], v[148:151], v[180:183], v[52:55]
	v_mfma_f32_16x16x32_bf16 v[48:51], v[172:175], v[180:183], v[48:51]
	v_mfma_f32_16x16x32_bf16 v[36:39], v[148:151], v[196:199], v[36:39]
	v_mfma_f32_16x16x32_bf16 v[32:35], v[172:175], v[196:199], v[32:35]
	v_mfma_f32_16x16x32_bf16 v[20:23], v[148:151], v[204:207], v[20:23]
	v_mfma_f32_16x16x32_bf16 v[16:19], v[172:175], v[204:207], v[16:19]
	v_mfma_f32_16x16x32_bf16 v[4:7], v[148:151], v[212:215], v[4:7]
	v_mfma_f32_16x16x32_bf16 v[0:3], v[172:175], v[212:215], v[0:3]

	s_barrier
	s_add_i32 s66, 0, 0x18000
	s_add_i32 s67, 0, 0x1c000
	v_add_u32_e32 v140, s66, v185
	v_add_u32_e32 v172, s67, v185
	ds_read_b128 v[128:131], v140
	ds_read_b128 v[132:135], v140 offset:1024
	ds_read_b128 v[136:139], v140 offset:2048
	ds_read_b128 v[140:143], v140 offset:3072
	ds_read_b128 v[144:147], v172
	ds_read_b128 v[148:151], v172 offset:1024
	ds_read_b128 v[168:171], v172 offset:2048
	ds_read_b128 v[172:175], v172 offset:3072
	s_add_u32 s38, s38, 0x40000
	s_addc_u32 s39, s39, 0
	s_mov_b32 m0, s48
	v_lshl_add_u64 v[224:225], s[38:39], 0, v[152:153]
	ds_read_b128 v[176:179], v189 offset:32768
	ds_read_b128 v[180:183], v189 offset:33792
	ds_read_b128 v[192:195], v189 offset:34816
	ds_read_b128 v[196:199], v189 offset:35840
	ds_read_b128 v[200:203], v189 offset:36864
	ds_read_b128 v[204:207], v189 offset:37888
	ds_read_b128 v[208:211], v189 offset:38912
	ds_read_b128 v[212:215], v189 offset:39936
	global_load_lds_dwordx4 v[224:225], off
	v_lshl_add_u64 v[224:225], s[38:39], 0, v[156:157]
	s_mov_b32 m0, s49
	s_nop 0
	global_load_lds_dwordx4 v[224:225], off
	s_waitcnt vmcnt(8)
	s_waitcnt lgkmcnt(0)
	s_barrier

	v_mfma_f32_16x16x32_bf16 v[124:127], v[128:131], v[176:179], v[124:127]
	v_mfma_f32_16x16x32_bf16 v[120:123], v[136:139], v[176:179], v[120:123]
	v_mfma_f32_16x16x32_bf16 v[108:111], v[128:131], v[192:195], v[108:111]
	v_mfma_f32_16x16x32_bf16 v[104:107], v[136:139], v[192:195], v[104:107]
	v_mfma_f32_16x16x32_bf16 v[92:95], v[128:131], v[200:203], v[92:95]
	v_mfma_f32_16x16x32_bf16 v[88:91], v[136:139], v[200:203], v[88:91]
	v_mfma_f32_16x16x32_bf16 v[76:79], v[128:131], v[208:211], v[76:79]
	v_mfma_f32_16x16x32_bf16 v[72:75], v[136:139], v[208:211], v[72:75]
	v_mfma_f32_16x16x32_bf16 v[124:127], v[132:135], v[180:183], v[124:127]
	v_mfma_f32_16x16x32_bf16 v[120:123], v[140:143], v[180:183], v[120:123]
	v_mfma_f32_16x16x32_bf16 v[108:111], v[132:135], v[196:199], v[108:111]
	v_mfma_f32_16x16x32_bf16 v[104:107], v[140:143], v[196:199], v[104:107]
	v_mfma_f32_16x16x32_bf16 v[92:95], v[132:135], v[204:207], v[92:95]
	v_mfma_f32_16x16x32_bf16 v[88:91], v[140:143], v[204:207], v[88:91]
	v_mfma_f32_16x16x32_bf16 v[76:79], v[132:135], v[212:215], v[76:79]
	v_mfma_f32_16x16x32_bf16 v[72:75], v[140:143], v[212:215], v[72:75]

	v_mfma_f32_16x16x32_bf16 v[116:119], v[144:147], v[176:179], v[116:119]
	v_mfma_f32_16x16x32_bf16 v[112:115], v[168:171], v[176:179], v[112:115]
	v_mfma_f32_16x16x32_bf16 v[100:103], v[144:147], v[192:195], v[100:103]
	v_mfma_f32_16x16x32_bf16 v[96:99], v[168:171], v[192:195], v[96:99]
	v_mfma_f32_16x16x32_bf16 v[84:87], v[144:147], v[200:203], v[84:87]
	v_mfma_f32_16x16x32_bf16 v[80:83], v[168:171], v[200:203], v[80:83]
	v_mfma_f32_16x16x32_bf16 v[68:71], v[144:147], v[208:211], v[68:71]
	v_mfma_f32_16x16x32_bf16 v[64:67], v[168:171], v[208:211], v[64:67]
	v_mfma_f32_16x16x32_bf16 v[116:119], v[148:151], v[180:183], v[116:119]
	v_mfma_f32_16x16x32_bf16 v[112:115], v[172:175], v[180:183], v[112:115]
	v_mfma_f32_16x16x32_bf16 v[100:103], v[148:151], v[196:199], v[100:103]
	v_mfma_f32_16x16x32_bf16 v[96:99], v[172:175], v[196:199], v[96:99]
	v_mfma_f32_16x16x32_bf16 v[84:87], v[148:151], v[204:207], v[84:87]
	v_mfma_f32_16x16x32_bf16 v[80:83], v[172:175], v[204:207], v[80:83]
	v_mfma_f32_16x16x32_bf16 v[68:71], v[148:151], v[212:215], v[68:71]
	v_mfma_f32_16x16x32_bf16 v[64:67], v[172:175], v[212:215], v[64:67]

	s_barrier
	s_add_i32 s38, s66, s45
	v_lshl_add_u64 v[216:217], v[216:217], 0, s[6:7]
	s_mov_b32 m0, s38
	ds_read_b128 v[176:179], v189 offset:49152
	ds_read_b128 v[180:183], v189 offset:50176
	ds_read_b128 v[192:195], v189 offset:51200
	ds_read_b128 v[196:199], v189 offset:52224
	ds_read_b128 v[200:203], v189 offset:53248
	ds_read_b128 v[204:207], v189 offset:54272
	ds_read_b128 v[208:211], v189 offset:55296
	ds_read_b128 v[212:215], v189 offset:56320
	global_load_lds_dwordx4 v[216:217], off
	s_add_i32 m0, s38, 0x2000
	s_add_u32 s36, s36, 0x40080
	v_lshl_add_u64 v[216:217], v[218:219], 0, s[6:7]
	s_addc_u32 s37, s37, 0
	s_add_i32 s38, s67, s45
	global_load_lds_dwordx4 v[216:217], off
	v_lshl_add_u64 v[216:217], s[36:37], 0, v[154:155]
	s_mov_b32 m0, s38
	s_nop 0
	global_load_lds_dwordx4 v[216:217], off
	v_lshl_add_u64 v[216:217], s[36:37], 0, v[158:159]
	s_add_i32 m0, s38, 0x2000
	s_nop 0
	global_load_lds_dwordx4 v[216:217], off
	v_lshl_add_u64 v[216:217], v[220:221], 0, s[6:7]
	s_mov_b32 m0, s51
	s_nop 0
	global_load_lds_dwordx4 v[216:217], off
	v_lshl_add_u64 v[216:217], v[222:223], 0, s[6:7]
	s_mov_b32 m0, s52
	s_nop 0
	global_load_lds_dwordx4 v[216:217], off
	s_waitcnt vmcnt(8)
	s_waitcnt lgkmcnt(0)
	s_barrier

	v_mfma_f32_16x16x32_bf16 v[60:63], v[128:131], v[176:179], v[60:63]
	v_mfma_f32_16x16x32_bf16 v[56:59], v[136:139], v[176:179], v[56:59]
	v_mfma_f32_16x16x32_bf16 v[44:47], v[128:131], v[192:195], v[44:47]
	v_mfma_f32_16x16x32_bf16 v[40:43], v[136:139], v[192:195], v[40:43]
	v_mfma_f32_16x16x32_bf16 v[28:31], v[128:131], v[200:203], v[28:31]
	v_mfma_f32_16x16x32_bf16 v[24:27], v[136:139], v[200:203], v[24:27]
	v_mfma_f32_16x16x32_bf16 v[12:15], v[128:131], v[208:211], v[12:15]
	v_mfma_f32_16x16x32_bf16 v[8:11], v[136:139], v[208:211], v[8:11]
	v_mfma_f32_16x16x32_bf16 v[60:63], v[132:135], v[180:183], v[60:63]
	v_mfma_f32_16x16x32_bf16 v[56:59], v[140:143], v[180:183], v[56:59]
	v_mfma_f32_16x16x32_bf16 v[44:47], v[132:135], v[196:199], v[44:47]
	v_mfma_f32_16x16x32_bf16 v[40:43], v[140:143], v[196:199], v[40:43]
	v_mfma_f32_16x16x32_bf16 v[28:31], v[132:135], v[204:207], v[28:31]
	v_mfma_f32_16x16x32_bf16 v[24:27], v[140:143], v[204:207], v[24:27]
	v_mfma_f32_16x16x32_bf16 v[12:15], v[132:135], v[212:215], v[12:15]
	v_mfma_f32_16x16x32_bf16 v[8:11], v[140:143], v[212:215], v[8:11]

	v_mfma_f32_16x16x32_bf16 v[52:55], v[144:147], v[176:179], v[52:55]
	v_mfma_f32_16x16x32_bf16 v[48:51], v[168:171], v[176:179], v[48:51]
	v_mfma_f32_16x16x32_bf16 v[36:39], v[144:147], v[192:195], v[36:39]
	v_mfma_f32_16x16x32_bf16 v[32:35], v[168:171], v[192:195], v[32:35]
	v_mfma_f32_16x16x32_bf16 v[20:23], v[144:147], v[200:203], v[20:23]
	v_mfma_f32_16x16x32_bf16 v[16:19], v[168:171], v[200:203], v[16:19]
	v_mfma_f32_16x16x32_bf16 v[4:7], v[144:147], v[208:211], v[4:7]
	v_mfma_f32_16x16x32_bf16 v[0:3], v[168:171], v[208:211], v[0:3]
	v_mfma_f32_16x16x32_bf16 v[52:55], v[148:151], v[180:183], v[52:55]
	v_mfma_f32_16x16x32_bf16 v[48:51], v[172:175], v[180:183], v[48:51]
	v_mfma_f32_16x16x32_bf16 v[36:39], v[148:151], v[196:199], v[36:39]
	v_mfma_f32_16x16x32_bf16 v[32:35], v[172:175], v[196:199], v[32:35]
	v_mfma_f32_16x16x32_bf16 v[20:23], v[148:151], v[204:207], v[20:23]
	v_mfma_f32_16x16x32_bf16 v[16:19], v[172:175], v[204:207], v[16:19]
	v_mfma_f32_16x16x32_bf16 v[4:7], v[148:151], v[212:215], v[4:7]
	v_mfma_f32_16x16x32_bf16 v[0:3], v[172:175], v[212:215], v[0:3]

	s_barrier
	s_add_i32 s65, s65, 2
	s_add_u32 s24, s24, 0x100
	s_addc_u32 s25, s25, 0
	s_add_u32 s63, s63, 0x100
	s_addc_u32 s64, s64, 0
	s_cmp_gt_u32 s65, 13
	s_cbranch_scc0 .LBB0_1530
	v_lshl_add_u32 v168, s60, 8, v184
	v_lshl_or_b32 v128, s8, 8, v186
	v_ashrrev_i32_e32 v169, 31, v168
	v_ashrrev_i32_e32 v129, 31, v128
	v_lshlrev_b64 v[130:131], 11, v[168:169]
	v_lshl_add_u64 v[130:131], s[34:35], 0, v[130:131]
	v_lshlrev_b64 v[170:171], 1, v[128:129]
	v_lshl_add_u64 v[200:201], v[130:131], 0, v[170:171]
	global_load_dwordx4 v[192:195], v[200:201], off
	global_load_dwordx4 v[196:199], v[200:201], off offset:256
	v_or_b32_e32 v180, 16, v168
	v_or_b32_e32 v176, 32, v168
	v_or_b32_e32 v172, 48, v168
	v_ashrrev_i32_e32 v181, 31, v180
	v_ashrrev_i32_e32 v177, 31, v176
	v_ashrrev_i32_e32 v173, 31, v172
	v_lshlrev_b64 v[128:129], 11, v[180:181]
	v_lshlrev_b64 v[130:131], 11, v[176:177]
	v_lshlrev_b64 v[132:133], 11, v[172:173]
	v_lshl_add_u64 v[128:129], s[34:35], 0, v[128:129]
	v_lshl_add_u64 v[130:131], s[34:35], 0, v[130:131]
	v_lshl_add_u64 v[132:133], s[34:35], 0, v[132:133]
	v_lshl_add_u64 v[182:183], v[128:129], 0, v[170:171]
	v_lshl_add_u64 v[178:179], v[130:131], 0, v[170:171]
	v_lshl_add_u64 v[174:175], v[132:133], 0, v[170:171]
	global_load_dwordx4 v[148:151], v[182:183], off
	global_load_dwordx4 v[144:147], v[182:183], off offset:256
	global_load_dwordx4 v[140:143], v[178:179], off
	global_load_dwordx4 v[136:139], v[178:179], off offset:256
	global_load_dwordx4 v[132:135], v[174:175], off
	global_load_dwordx4 v[128:131], v[174:175], off offset:256
	v_and_b32_e32 v202, 64, v190
	v_xor_b32_e32 v191, 16, v190
	v_add_u32_e32 v202, 64, v202
	v_xor_b32_e32 v203, 32, v190
	v_cmp_lt_i32_e32 vcc, v191, v202
	s_lshl_b32 s24, s8, 2
	s_ashr_i32 s25, s24, 31
	v_cndmask_b32_e32 v191, v190, v191, vcc
	v_cmp_lt_i32_e32 vcc, v203, v202
	v_lshlrev_b32_e32 v191, 2, v191
	s_waitcnt vmcnt(0)
	v_lshlrev_b32_e32 v202, 16, v192
	v_cndmask_b32_e32 v210, v190, v203, vcc
	v_and_b32_e32 v203, 0xffff0000, v192
	v_lshlrev_b32_e32 v192, 16, v193
	v_and_b32_e32 v193, 0xffff0000, v193
	v_lshlrev_b32_e32 v204, 16, v194
	v_and_b32_e32 v205, 0xffff0000, v194
	v_lshlrev_b32_e32 v194, 16, v195
	v_and_b32_e32 v195, 0xffff0000, v195
	v_lshlrev_b32_e32 v206, 16, v196
	v_and_b32_e32 v207, 0xffff0000, v196
	v_lshlrev_b32_e32 v196, 16, v197
	v_and_b32_e32 v197, 0xffff0000, v197
	v_lshlrev_b32_e32 v208, 16, v198
	v_and_b32_e32 v209, 0xffff0000, v198
	v_lshlrev_b32_e32 v198, 16, v199
	v_and_b32_e32 v199, 0xffff0000, v199
	v_pk_add_f32 v[126:127], v[126:127], v[192:193]
	v_pk_add_f32 v[124:125], v[124:125], v[202:203]
	v_pk_add_f32 v[122:123], v[122:123], v[194:195]
	v_pk_add_f32 v[120:121], v[120:121], v[204:205]
	v_pk_add_f32 v[118:119], v[118:119], v[196:197]
	v_pk_add_f32 v[116:117], v[116:117], v[206:207]
	v_pk_add_f32 v[192:193], v[114:115], v[198:199]
	v_pk_add_f32 v[194:195], v[112:113], v[208:209]
	v_cvt_pk_bf16_f32 v112, v124, v125
	v_cvt_pk_bf16_f32 v113, v126, v127
	v_mul_f32_e32 v114, v125, v125
	v_mul_f32_e32 v115, v127, v127
	v_mul_f32_e32 v125, v121, v121
	v_mul_f32_e32 v127, v123, v123
	v_mul_f32_e32 v196, v117, v117
	v_mul_f32_e32 v197, v119, v119
	v_mul_f32_e32 v198, v195, v195
	v_mul_f32_e32 v199, v193, v193
	v_fmac_f32_e32 v114, v124, v124
	v_fmac_f32_e32 v115, v126, v126
	v_fmac_f32_e32 v125, v120, v120
	v_fmac_f32_e32 v127, v122, v122
	v_fmac_f32_e32 v196, v116, v116
	v_fmac_f32_e32 v197, v118, v118
	v_fmac_f32_e32 v198, v194, v194
	v_fmac_f32_e32 v199, v192, v192
	v_add_f32_e32 v114, v114, v115
	v_add_f32_e32 v115, v125, v127
	v_add_f32_e32 v124, v196, v197
	v_add_f32_e32 v125, v198, v199
	v_add_f32_e32 v114, v114, v115
	v_add_f32_e32 v115, v124, v125
	v_add_f32_e32 v124, v114, v115
	ds_bpermute_b32 v125, v191, v124
	v_cvt_pk_bf16_f32 v114, v120, v121
	v_cvt_pk_bf16_f32 v115, v122, v123
	global_store_dwordx4 v[200:201], v[112:115], off
	v_cvt_pk_bf16_f32 v116, v116, v117
	v_cvt_pk_bf16_f32 v117, v118, v119
	s_waitcnt lgkmcnt(0)
	v_add_f32_e32 v113, v124, v125
	v_lshlrev_b32_e32 v112, 2, v210
	ds_bpermute_b32 v114, v112, v113
	v_cvt_pk_bf16_f32 v118, v194, v195
	v_cvt_pk_bf16_f32 v119, v192, v193
	global_store_dwordx4 v[200:201], v[116:119], off offset:256
	s_and_saveexec_b64 s[36:37], s[0:1]
	s_cbranch_execz .LBB0_1533
	s_waitcnt lgkmcnt(0)
	v_add_f32_e32 v113, v113, v114
	v_lshlrev_b64 v[114:115], 6, v[168:169]
	v_lshl_add_u64 v[114:115], s[74:75], 0, v[114:115]
	v_lshl_add_u64 v[114:115], s[24:25], 2, v[114:115]
	s_lshl_b32 s8, s50, 2
	v_lshl_add_u64 v[114:115], v[114:115], 0, s[8:9]
	global_store_dword v[114:115], v113, off

.LBB0_1658:
	ds_read_b128 v[96:99], v169
	ds_read_b128 v[100:103], v169 offset:1024
	ds_read_b128 v[104:107], v169 offset:2048
	ds_read_b128 v[108:111], v169 offset:3072
	ds_read_b128 v[112:115], v170
	ds_read_b128 v[116:119], v170 offset:1024
	ds_read_b128 v[120:123], v170 offset:2048
	ds_read_b128 v[124:127], v170 offset:3072
	s_add_u32 s54, s50, 0xfff80080
	s_addc_u32 s55, s51, -1
	s_cmp_eq_u32 s58, 12
	s_cselect_b32 s89, s3, s57
	s_cselect_b32 s88, s5, s56
	s_cselect_b32 s55, s39, s55
	s_cselect_b32 s54, s43, s54
	v_lshl_add_u64 v[164:165], s[50:51], 0, v[138:139]
	s_add_i32 m0, s53, 0xc000
	ds_read_b128 v[146:149], v171
	ds_read_b128 v[150:153], v171 offset:1024
	ds_read_b128 v[154:157], v171 offset:2048
	ds_read_b128 v[158:161], v171 offset:3072
	ds_read_b128 v[174:177], v171 offset:4096
	ds_read_b128 v[178:181], v171 offset:5120
	ds_read_b128 v[182:185], v171 offset:6144
	ds_read_b128 v[186:189], v171 offset:7168
	global_load_lds_dwordx4 v[164:165], off
	v_lshl_add_u64 v[164:165], s[50:51], 0, v[140:141]
	s_add_i32 m0, s53, 0xe000
	s_nop 0
	global_load_lds_dwordx4 v[164:165], off
	s_waitcnt vmcnt(8)
	s_waitcnt lgkmcnt(0)
	s_barrier

	v_mfma_f32_16x16x32_bf16 v[92:95], v[96:99], v[146:149], v[92:95]
	v_mfma_f32_16x16x32_bf16 v[88:91], v[104:107], v[146:149], v[88:91]
	v_mfma_f32_16x16x32_bf16 v[84:87], v[96:99], v[154:157], v[84:87]
	v_mfma_f32_16x16x32_bf16 v[80:83], v[104:107], v[154:157], v[80:83]
	v_mfma_f32_16x16x32_bf16 v[68:71], v[96:99], v[174:177], v[68:71]
	v_mfma_f32_16x16x32_bf16 v[64:67], v[104:107], v[174:177], v[64:67]
	v_mfma_f32_16x16x32_bf16 v[52:55], v[96:99], v[182:185], v[52:55]
	v_mfma_f32_16x16x32_bf16 v[48:51], v[104:107], v[182:185], v[48:51]
	v_mfma_f32_16x16x32_bf16 v[92:95], v[100:103], v[150:153], v[92:95]
	v_mfma_f32_16x16x32_bf16 v[88:91], v[108:111], v[150:153], v[88:91]
	v_mfma_f32_16x16x32_bf16 v[84:87], v[100:103], v[158:161], v[84:87]
	v_mfma_f32_16x16x32_bf16 v[80:83], v[108:111], v[158:161], v[80:83]
	v_mfma_f32_16x16x32_bf16 v[68:71], v[100:103], v[178:181], v[68:71]
	v_mfma_f32_16x16x32_bf16 v[64:67], v[108:111], v[178:181], v[64:67]
	v_mfma_f32_16x16x32_bf16 v[52:55], v[100:103], v[186:189], v[52:55]
	v_mfma_f32_16x16x32_bf16 v[48:51], v[108:111], v[186:189], v[48:51]

	v_mfma_f32_16x16x32_bf16 v[76:79], v[112:115], v[146:149], v[76:79]
	v_mfma_f32_16x16x32_bf16 v[72:75], v[120:123], v[146:149], v[72:75]
	v_mfma_f32_16x16x32_bf16 v[60:63], v[112:115], v[154:157], v[60:63]
	v_mfma_f32_16x16x32_bf16 v[56:59], v[120:123], v[154:157], v[56:59]
	v_mfma_f32_16x16x32_bf16 v[44:47], v[112:115], v[174:177], v[44:47]
	v_mfma_f32_16x16x32_bf16 v[40:43], v[120:123], v[174:177], v[40:43]
	v_mfma_f32_16x16x32_bf16 v[36:39], v[112:115], v[182:185], v[36:39]
	v_mfma_f32_16x16x32_bf16 v[32:35], v[120:123], v[182:185], v[32:35]
	v_mfma_f32_16x16x32_bf16 v[76:79], v[116:119], v[150:153], v[76:79]
	v_mfma_f32_16x16x32_bf16 v[72:75], v[124:127], v[150:153], v[72:75]
	v_mfma_f32_16x16x32_bf16 v[60:63], v[116:119], v[158:161], v[60:63]
	v_mfma_f32_16x16x32_bf16 v[56:59], v[124:127], v[158:161], v[56:59]
	v_mfma_f32_16x16x32_bf16 v[44:47], v[116:119], v[178:181], v[44:47]
	v_mfma_f32_16x16x32_bf16 v[40:43], v[124:127], v[178:181], v[40:43]
	v_mfma_f32_16x16x32_bf16 v[36:39], v[116:119], v[186:189], v[36:39]
	v_mfma_f32_16x16x32_bf16 v[32:35], v[124:127], v[186:189], v[32:35]

	s_barrier
	s_add_i32 s59, s73, s25
	v_lshl_add_u64 v[164:165], s[54:55], 0, v[130:131]
	s_mov_b32 m0, s59
	ds_read_b128 v[96:99], v172 offset:16384
	ds_read_b128 v[100:103], v172 offset:17408
	ds_read_b128 v[104:107], v172 offset:18432
	ds_read_b128 v[108:111], v172 offset:19456
	global_load_lds_dwordx4 v[164:165], off
	s_add_i32 m0, s59, 0x2000
	s_add_u32 s90, s54, 0x40000
	v_lshl_add_u64 v[190:191], s[54:55], 0, v[134:135]
	s_addc_u32 s91, s55, 0
	s_add_i32 s59, s76, s25
	global_load_lds_dwordx4 v[190:191], off
	v_lshl_add_u64 v[112:113], s[90:91], 0, v[130:131]
	s_mov_b32 m0, s59
	v_lshl_add_u64 v[192:193], s[88:89], 0, v[128:129]
	global_load_lds_dwordx4 v[112:113], off
	v_lshl_add_u64 v[112:113], s[90:91], 0, v[134:135]
	s_add_i32 m0, s59, 0x2000
	v_lshl_add_u64 v[194:195], s[88:89], 0, v[132:133]
	global_load_lds_dwordx4 v[112:113], off
	s_mov_b32 m0, s53
	s_nop 0
	global_load_lds_dwordx4 v[192:193], off
	s_mov_b32 m0, s60
	s_nop 0
	global_load_lds_dwordx4 v[194:195], off
	s_waitcnt vmcnt(8)
	s_waitcnt lgkmcnt(0)
	s_barrier

	v_mfma_f32_16x16x32_bf16 v[28:31], v[96:99], v[146:149], v[28:31]
	v_mfma_f32_16x16x32_bf16 v[24:27], v[104:107], v[146:149], v[24:27]
	v_mfma_f32_16x16x32_bf16 v[20:23], v[96:99], v[154:157], v[20:23]
	v_mfma_f32_16x16x32_bf16 v[16:19], v[104:107], v[154:157], v[16:19]
	v_mfma_f32_16x16x32_bf16 v[12:15], v[96:99], v[174:177], v[12:15]
	v_mfma_f32_16x16x32_bf16 v[8:11], v[104:107], v[174:177], v[8:11]
	v_mfma_f32_16x16x32_bf16 v[4:7], v[96:99], v[182:185], v[4:7]
	v_mfma_f32_16x16x32_bf16 v[0:3], v[104:107], v[182:185], v[0:3]
	v_mfma_f32_16x16x32_bf16 v[28:31], v[100:103], v[150:153], v[28:31]
	v_mfma_f32_16x16x32_bf16 v[24:27], v[108:111], v[150:153], v[24:27]
	v_mfma_f32_16x16x32_bf16 v[20:23], v[100:103], v[158:161], v[20:23]
	v_mfma_f32_16x16x32_bf16 v[16:19], v[108:111], v[158:161], v[16:19]
	v_mfma_f32_16x16x32_bf16 v[12:15], v[100:103], v[178:181], v[12:15]
	v_mfma_f32_16x16x32_bf16 v[8:11], v[108:111], v[178:181], v[8:11]
	v_mfma_f32_16x16x32_bf16 v[4:7], v[100:103], v[186:189], v[4:7]
	v_mfma_f32_16x16x32_bf16 v[0:3], v[108:111], v[186:189], v[0:3]

	s_barrier
	s_add_i32 s59, 0, 0x18000
	s_add_i32 s87, 0, 0x1c000
	v_add_u32_e32 v108, s59, v167
	v_add_u32_e32 v124, s87, v167
	ds_read_b128 v[96:99], v108
	ds_read_b128 v[100:103], v108 offset:1024
	ds_read_b128 v[104:107], v108 offset:2048
	ds_read_b128 v[108:111], v108 offset:3072
	ds_read_b128 v[112:115], v124
	ds_read_b128 v[116:119], v124 offset:1024
	ds_read_b128 v[120:123], v124 offset:2048
	ds_read_b128 v[124:127], v124 offset:3072
	s_add_u32 s88, s54, 0x80000
	s_addc_u32 s89, s55, 0
	s_mov_b32 m0, s61
	v_lshl_add_u64 v[196:197], s[88:89], 0, v[130:131]
	ds_read_b128 v[146:149], v171 offset:32768
	ds_read_b128 v[150:153], v171 offset:33792
	ds_read_b128 v[154:157], v171 offset:34816
	ds_read_b128 v[158:161], v171 offset:35840
	ds_read_b128 v[174:177], v171 offset:36864
	ds_read_b128 v[178:181], v171 offset:37888
	ds_read_b128 v[182:185], v171 offset:38912
	ds_read_b128 v[186:189], v171 offset:39936
	global_load_lds_dwordx4 v[196:197], off
	v_lshl_add_u64 v[196:197], s[88:89], 0, v[134:135]
	s_mov_b32 m0, s62
	s_nop 0
	global_load_lds_dwordx4 v[196:197], off
	s_waitcnt vmcnt(8)
	s_waitcnt lgkmcnt(0)
	s_barrier

	v_mfma_f32_16x16x32_bf16 v[92:95], v[96:99], v[146:149], v[92:95]
	v_mfma_f32_16x16x32_bf16 v[88:91], v[104:107], v[146:149], v[88:91]
	v_mfma_f32_16x16x32_bf16 v[84:87], v[96:99], v[154:157], v[84:87]
	v_mfma_f32_16x16x32_bf16 v[80:83], v[104:107], v[154:157], v[80:83]
	v_mfma_f32_16x16x32_bf16 v[68:71], v[96:99], v[174:177], v[68:71]
	v_mfma_f32_16x16x32_bf16 v[64:67], v[104:107], v[174:177], v[64:67]
	v_mfma_f32_16x16x32_bf16 v[52:55], v[96:99], v[182:185], v[52:55]
	v_mfma_f32_16x16x32_bf16 v[48:51], v[104:107], v[182:185], v[48:51]
	v_mfma_f32_16x16x32_bf16 v[92:95], v[100:103], v[150:153], v[92:95]
	v_mfma_f32_16x16x32_bf16 v[88:91], v[108:111], v[150:153], v[88:91]
	v_mfma_f32_16x16x32_bf16 v[84:87], v[100:103], v[158:161], v[84:87]
	v_mfma_f32_16x16x32_bf16 v[80:83], v[108:111], v[158:161], v[80:83]
	v_mfma_f32_16x16x32_bf16 v[68:71], v[100:103], v[178:181], v[68:71]
	v_mfma_f32_16x16x32_bf16 v[64:67], v[108:111], v[178:181], v[64:67]
	v_mfma_f32_16x16x32_bf16 v[52:55], v[100:103], v[186:189], v[52:55]
	v_mfma_f32_16x16x32_bf16 v[48:51], v[108:111], v[186:189], v[48:51]

	v_mfma_f32_16x16x32_bf16 v[76:79], v[112:115], v[146:149], v[76:79]
	v_mfma_f32_16x16x32_bf16 v[72:75], v[120:123], v[146:149], v[72:75]
	v_mfma_f32_16x16x32_bf16 v[60:63], v[112:115], v[154:157], v[60:63]
	v_mfma_f32_16x16x32_bf16 v[56:59], v[120:123], v[154:157], v[56:59]
	v_mfma_f32_16x16x32_bf16 v[44:47], v[112:115], v[174:177], v[44:47]
	v_mfma_f32_16x16x32_bf16 v[40:43], v[120:123], v[174:177], v[40:43]
	v_mfma_f32_16x16x32_bf16 v[36:39], v[112:115], v[182:185], v[36:39]
	v_mfma_f32_16x16x32_bf16 v[32:35], v[120:123], v[182:185], v[32:35]
	v_mfma_f32_16x16x32_bf16 v[76:79], v[116:119], v[150:153], v[76:79]
	v_mfma_f32_16x16x32_bf16 v[72:75], v[124:127], v[150:153], v[72:75]
	v_mfma_f32_16x16x32_bf16 v[60:63], v[116:119], v[158:161], v[60:63]
	v_mfma_f32_16x16x32_bf16 v[56:59], v[124:127], v[158:161], v[56:59]
	v_mfma_f32_16x16x32_bf16 v[44:47], v[116:119], v[178:181], v[44:47]
	v_mfma_f32_16x16x32_bf16 v[40:43], v[124:127], v[178:181], v[40:43]
	v_mfma_f32_16x16x32_bf16 v[36:39], v[116:119], v[186:189], v[36:39]
	v_mfma_f32_16x16x32_bf16 v[32:35], v[124:127], v[186:189], v[32:35]

	s_barrier
	s_add_i32 s59, s59, s25
	v_lshl_add_u64 v[112:113], v[164:165], 0, s[14:15]
	s_mov_b32 m0, s59
	ds_read_b128 v[96:99], v172 offset:49152
	ds_read_b128 v[100:103], v172 offset:50176
	ds_read_b128 v[104:107], v172 offset:51200
	ds_read_b128 v[108:111], v172 offset:52224
	global_load_lds_dwordx4 v[112:113], off
	s_add_i32 m0, s59, 0x2000
	s_add_u32 s54, s54, 0x40080
	v_lshl_add_u64 v[112:113], v[190:191], 0, s[14:15]
	s_addc_u32 s55, s55, 0
	s_add_i32 s59, s87, s25
	global_load_lds_dwordx4 v[112:113], off
	v_lshl_add_u64 v[112:113], s[54:55], 0, v[130:131]
	s_mov_b32 m0, s59
	s_nop 0
	global_load_lds_dwordx4 v[112:113], off
	v_lshl_add_u64 v[112:113], s[54:55], 0, v[134:135]
	s_add_i32 m0, s59, 0x2000
	s_nop 0
	global_load_lds_dwordx4 v[112:113], off
	v_lshl_add_u64 v[112:113], v[192:193], 0, s[14:15]
	s_mov_b32 m0, s63
	s_nop 0
	global_load_lds_dwordx4 v[112:113], off
	v_lshl_add_u64 v[112:113], v[194:195], 0, s[14:15]
	s_mov_b32 m0, s64
	s_nop 0
	global_load_lds_dwordx4 v[112:113], off
	s_waitcnt vmcnt(8)
	s_waitcnt lgkmcnt(0)
	s_barrier

	v_mfma_f32_16x16x32_bf16 v[28:31], v[96:99], v[146:149], v[28:31]
	v_mfma_f32_16x16x32_bf16 v[24:27], v[104:107], v[146:149], v[24:27]
	v_mfma_f32_16x16x32_bf16 v[20:23], v[96:99], v[154:157], v[20:23]
	v_mfma_f32_16x16x32_bf16 v[16:19], v[104:107], v[154:157], v[16:19]
	v_mfma_f32_16x16x32_bf16 v[12:15], v[96:99], v[174:177], v[12:15]
	v_mfma_f32_16x16x32_bf16 v[8:11], v[104:107], v[174:177], v[8:11]
	v_mfma_f32_16x16x32_bf16 v[4:7], v[96:99], v[182:185], v[4:7]
	v_mfma_f32_16x16x32_bf16 v[0:3], v[104:107], v[182:185], v[0:3]
	v_mfma_f32_16x16x32_bf16 v[28:31], v[100:103], v[150:153], v[28:31]
	v_mfma_f32_16x16x32_bf16 v[24:27], v[108:111], v[150:153], v[24:27]
	v_mfma_f32_16x16x32_bf16 v[20:23], v[100:103], v[158:161], v[20:23]
	v_mfma_f32_16x16x32_bf16 v[16:19], v[108:111], v[158:161], v[16:19]
	v_mfma_f32_16x16x32_bf16 v[12:15], v[100:103], v[178:181], v[12:15]
	v_mfma_f32_16x16x32_bf16 v[8:11], v[108:111], v[178:181], v[8:11]
	v_mfma_f32_16x16x32_bf16 v[4:7], v[100:103], v[186:189], v[4:7]
	v_mfma_f32_16x16x32_bf16 v[0:3], v[108:111], v[186:189], v[0:3]

	s_barrier
	s_add_i32 s58, s58, 2
	s_add_u32 s56, s56, 0x100
	s_addc_u32 s57, s57, 0
	s_add_u32 s50, s50, 0x100
	s_addc_u32 s51, s51, 0
	s_cmp_gt_u32 s58, 13
	s_cbranch_scc0 .LBB0_1658
	s_mov_b64 s[50:51], 0
	s_branch .LBB0_1661

.LBB0_1663:
	ds_read_b128 v[146:149], v169
	ds_read_b128 v[150:153], v169 offset:1024
	ds_read_b128 v[154:157], v169 offset:2048
	ds_read_b128 v[158:161], v169 offset:3072
	ds_read_b128 v[174:177], v170
	ds_read_b128 v[178:181], v170 offset:1024
	ds_read_b128 v[182:185], v170 offset:2048
	ds_read_b128 v[186:189], v170 offset:3072
	s_add_u32 s58, s48, 0xfffc0080
	s_addc_u32 s59, s49, -1
	s_cmp_eq_u32 s89, 12
	s_cselect_b64 s[56:57], -1, 0
	s_and_b64 s[54:55], s[56:57], exec
	s_cselect_b32 s55, s39, s86
	s_cselect_b32 s54, s43, s85
	s_cselect_b32 s59, s3, s59
	s_cselect_b32 s58, s5, s58
	v_lshl_add_u64 v[164:165], s[48:49], 0, v[142:143]
	s_add_i32 m0, s53, 0xc000
	ds_read_b128 v[190:193], v171
	ds_read_b128 v[194:197], v171 offset:1024
	ds_read_b128 v[198:201], v171 offset:2048
	ds_read_b128 v[202:205], v171 offset:3072
	ds_read_b128 v[206:209], v171 offset:4096
	ds_read_b128 v[210:213], v171 offset:5120
	ds_read_b128 v[214:217], v171 offset:6144
	ds_read_b128 v[218:221], v171 offset:7168
	global_load_lds_dwordx4 v[164:165], off
	v_lshl_add_u64 v[164:165], s[48:49], 0, v[132:133]
	s_add_i32 m0, s53, 0xe000
	s_nop 0
	global_load_lds_dwordx4 v[164:165], off
	s_waitcnt vmcnt(8)
	s_waitcnt lgkmcnt(0)
	s_barrier

	v_mfma_f32_16x16x32_bf16 v[92:95], v[146:149], v[190:193], v[92:95]
	v_mfma_f32_16x16x32_bf16 v[88:91], v[154:157], v[190:193], v[88:91]
	v_mfma_f32_16x16x32_bf16 v[84:87], v[146:149], v[198:201], v[84:87]
	v_mfma_f32_16x16x32_bf16 v[80:83], v[154:157], v[198:201], v[80:83]
	v_mfma_f32_16x16x32_bf16 v[68:71], v[146:149], v[206:209], v[68:71]
	v_mfma_f32_16x16x32_bf16 v[64:67], v[154:157], v[206:209], v[64:67]
	v_mfma_f32_16x16x32_bf16 v[52:55], v[146:149], v[214:217], v[52:55]
	v_mfma_f32_16x16x32_bf16 v[48:51], v[154:157], v[214:217], v[48:51]
	v_mfma_f32_16x16x32_bf16 v[92:95], v[150:153], v[194:197], v[92:95]
	v_mfma_f32_16x16x32_bf16 v[88:91], v[158:161], v[194:197], v[88:91]
	v_mfma_f32_16x16x32_bf16 v[84:87], v[150:153], v[202:205], v[84:87]
	v_mfma_f32_16x16x32_bf16 v[80:83], v[158:161], v[202:205], v[80:83]
	v_mfma_f32_16x16x32_bf16 v[68:71], v[150:153], v[210:213], v[68:71]
	v_mfma_f32_16x16x32_bf16 v[64:67], v[158:161], v[210:213], v[64:67]
	v_mfma_f32_16x16x32_bf16 v[52:55], v[150:153], v[218:221], v[52:55]
	v_mfma_f32_16x16x32_bf16 v[48:51], v[158:161], v[218:221], v[48:51]

	v_mfma_f32_16x16x32_bf16 v[76:79], v[174:177], v[190:193], v[76:79]
	v_mfma_f32_16x16x32_bf16 v[72:75], v[182:185], v[190:193], v[72:75]
	v_mfma_f32_16x16x32_bf16 v[60:63], v[174:177], v[198:201], v[60:63]
	v_mfma_f32_16x16x32_bf16 v[56:59], v[182:185], v[198:201], v[56:59]
	v_mfma_f32_16x16x32_bf16 v[44:47], v[174:177], v[206:209], v[44:47]
	v_mfma_f32_16x16x32_bf16 v[40:43], v[182:185], v[206:209], v[40:43]
	v_mfma_f32_16x16x32_bf16 v[36:39], v[174:177], v[214:217], v[36:39]
	v_mfma_f32_16x16x32_bf16 v[32:35], v[182:185], v[214:217], v[32:35]
	v_mfma_f32_16x16x32_bf16 v[76:79], v[178:181], v[194:197], v[76:79]
	v_mfma_f32_16x16x32_bf16 v[72:75], v[186:189], v[194:197], v[72:75]
	v_mfma_f32_16x16x32_bf16 v[60:63], v[178:181], v[202:205], v[60:63]
	v_mfma_f32_16x16x32_bf16 v[56:59], v[186:189], v[202:205], v[56:59]
	v_mfma_f32_16x16x32_bf16 v[44:47], v[178:181], v[210:213], v[44:47]
	v_mfma_f32_16x16x32_bf16 v[40:43], v[186:189], v[210:213], v[40:43]
	v_mfma_f32_16x16x32_bf16 v[36:39], v[178:181], v[218:221], v[36:39]
	v_mfma_f32_16x16x32_bf16 v[32:35], v[186:189], v[218:221], v[32:35]

	s_barrier
	s_add_i32 s90, s73, s25
	v_lshl_add_u64 v[164:165], s[54:55], 0, v[130:131]
	s_mov_b32 m0, s90
	ds_read_b128 v[190:193], v171 offset:16384
	ds_read_b128 v[194:197], v171 offset:17408
	ds_read_b128 v[198:201], v171 offset:18432
	ds_read_b128 v[202:205], v171 offset:19456
	ds_read_b128 v[206:209], v171 offset:20480
	ds_read_b128 v[210:213], v171 offset:21504
	ds_read_b128 v[214:217], v171 offset:22528
	ds_read_b128 v[218:221], v171 offset:23552
	global_load_lds_dwordx4 v[164:165], off
	s_add_i32 m0, s90, 0x2000
	s_add_u32 s90, s54, 0x40000
	v_lshl_add_u64 v[222:223], s[54:55], 0, v[134:135]
	s_addc_u32 s91, s55, 0
	s_add_i32 s92, s76, s25
	global_load_lds_dwordx4 v[222:223], off
	v_lshl_add_u64 v[224:225], s[90:91], 0, v[130:131]
	s_mov_b32 m0, s92
	v_lshl_add_u64 v[226:227], s[58:59], 0, v[132:133]
	global_load_lds_dwordx4 v[224:225], off
	v_lshl_add_u64 v[224:225], s[90:91], 0, v[134:135]
	s_add_i32 m0, s92, 0x2000
	s_nop 0
	global_load_lds_dwordx4 v[224:225], off
	v_lshl_add_u64 v[224:225], s[58:59], 0, v[128:129]
	s_mov_b32 m0, s53
	s_nop 0
	global_load_lds_dwordx4 v[224:225], off
	s_mov_b32 m0, s60
	s_nop 0
	global_load_lds_dwordx4 v[226:227], off
	s_waitcnt vmcnt(8)
	s_waitcnt lgkmcnt(0)
	s_barrier

	v_mfma_f32_16x16x32_bf16 v[28:31], v[146:149], v[190:193], v[28:31]
	v_mfma_f32_16x16x32_bf16 v[24:27], v[154:157], v[190:193], v[24:27]
	v_mfma_f32_16x16x32_bf16 v[20:23], v[146:149], v[198:201], v[20:23]
	v_mfma_f32_16x16x32_bf16 v[16:19], v[154:157], v[198:201], v[16:19]
	v_mfma_f32_16x16x32_bf16 v[12:15], v[146:149], v[206:209], v[12:15]
	v_mfma_f32_16x16x32_bf16 v[8:11], v[154:157], v[206:209], v[8:11]
	v_mfma_f32_16x16x32_bf16 v[4:7], v[146:149], v[214:217], v[4:7]
	v_mfma_f32_16x16x32_bf16 v[0:3], v[154:157], v[214:217], v[0:3]
	v_mfma_f32_16x16x32_bf16 v[28:31], v[150:153], v[194:197], v[28:31]
	v_mfma_f32_16x16x32_bf16 v[24:27], v[158:161], v[194:197], v[24:27]
	v_mfma_f32_16x16x32_bf16 v[20:23], v[150:153], v[202:205], v[20:23]
	v_mfma_f32_16x16x32_bf16 v[16:19], v[158:161], v[202:205], v[16:19]
	v_mfma_f32_16x16x32_bf16 v[12:15], v[150:153], v[210:213], v[12:15]
	v_mfma_f32_16x16x32_bf16 v[8:11], v[158:161], v[210:213], v[8:11]
	v_mfma_f32_16x16x32_bf16 v[4:7], v[150:153], v[218:221], v[4:7]
	v_mfma_f32_16x16x32_bf16 v[0:3], v[158:161], v[218:221], v[0:3]

	v_mfma_f32_16x16x32_bf16 v[124:127], v[174:177], v[190:193], v[124:127]
	v_mfma_f32_16x16x32_bf16 v[120:123], v[182:185], v[190:193], v[120:123]
	v_mfma_f32_16x16x32_bf16 v[116:119], v[174:177], v[198:201], v[116:119]
	v_mfma_f32_16x16x32_bf16 v[112:115], v[182:185], v[198:201], v[112:115]
	v_mfma_f32_16x16x32_bf16 v[108:111], v[174:177], v[206:209], v[108:111]
	v_mfma_f32_16x16x32_bf16 v[104:107], v[182:185], v[206:209], v[104:107]
	v_mfma_f32_16x16x32_bf16 v[100:103], v[174:177], v[214:217], v[100:103]
	v_mfma_f32_16x16x32_bf16 v[96:99], v[182:185], v[214:217], v[96:99]
	v_mfma_f32_16x16x32_bf16 v[124:127], v[178:181], v[194:197], v[124:127]
	v_mfma_f32_16x16x32_bf16 v[120:123], v[186:189], v[194:197], v[120:123]
	v_mfma_f32_16x16x32_bf16 v[116:119], v[178:181], v[202:205], v[116:119]
	v_mfma_f32_16x16x32_bf16 v[112:115], v[186:189], v[202:205], v[112:115]
	v_mfma_f32_16x16x32_bf16 v[108:111], v[178:181], v[210:213], v[108:111]
	v_mfma_f32_16x16x32_bf16 v[104:107], v[186:189], v[210:213], v[104:107]
	v_mfma_f32_16x16x32_bf16 v[100:103], v[178:181], v[218:221], v[100:103]
	v_mfma_f32_16x16x32_bf16 v[96:99], v[186:189], v[218:221], v[96:99]

	s_barrier
	s_add_i32 s90, 0, 0x18000
	s_add_i32 s91, 0, 0x1c000
	v_add_u32_e32 v158, s90, v167
	v_add_u32_e32 v162, s91, v167
	ds_read_b128 v[146:149], v158
	ds_read_b128 v[150:153], v158 offset:1024
	ds_read_b128 v[154:157], v158 offset:2048
	ds_read_b128 v[158:161], v158 offset:3072
	ds_read_b128 v[174:177], v162
	ds_read_b128 v[178:181], v162 offset:1024
	ds_read_b128 v[182:185], v162 offset:2048
	ds_read_b128 v[186:189], v162 offset:3072
	s_and_b64 s[56:57], s[40:41], s[56:57]
	s_and_b64 vcc, s[56:57], s[50:51]
	s_add_u32 s58, s58, 0x40000
	s_addc_u32 s59, s59, 0
	s_and_b64 s[56:57], vcc, exec
	s_mov_b32 m0, s61
	v_cndmask_b32_e32 v162, v128, v130, vcc
	s_cselect_b32 s57, s88, s59
	s_cselect_b32 s56, s87, s58
	ds_read_b128 v[190:193], v171 offset:32768
	ds_read_b128 v[194:197], v171 offset:33792
	ds_read_b128 v[198:201], v171 offset:34816
	ds_read_b128 v[202:205], v171 offset:35840
	ds_read_b128 v[206:209], v171 offset:36864
	ds_read_b128 v[210:213], v171 offset:37888
	ds_read_b128 v[214:217], v171 offset:38912
	ds_read_b128 v[218:221], v171 offset:39936
	v_cndmask_b32_e32 v166, v132, v134, vcc
	global_load_lds_dwordx4 v162, s[56:57]
	s_mov_b32 m0, s62
	s_nop 0
	global_load_lds_dwordx4 v166, s[56:57]
	s_waitcnt vmcnt(8)
	s_waitcnt lgkmcnt(0)
	s_barrier

	v_mfma_f32_16x16x32_bf16 v[92:95], v[146:149], v[190:193], v[92:95]
	v_mfma_f32_16x16x32_bf16 v[88:91], v[154:157], v[190:193], v[88:91]
	v_mfma_f32_16x16x32_bf16 v[84:87], v[146:149], v[198:201], v[84:87]
	v_mfma_f32_16x16x32_bf16 v[80:83], v[154:157], v[198:201], v[80:83]
	v_mfma_f32_16x16x32_bf16 v[68:71], v[146:149], v[206:209], v[68:71]
	v_mfma_f32_16x16x32_bf16 v[64:67], v[154:157], v[206:209], v[64:67]
	v_mfma_f32_16x16x32_bf16 v[52:55], v[146:149], v[214:217], v[52:55]
	v_mfma_f32_16x16x32_bf16 v[48:51], v[154:157], v[214:217], v[48:51]
	v_mfma_f32_16x16x32_bf16 v[92:95], v[150:153], v[194:197], v[92:95]
	v_mfma_f32_16x16x32_bf16 v[88:91], v[158:161], v[194:197], v[88:91]
	v_mfma_f32_16x16x32_bf16 v[84:87], v[150:153], v[202:205], v[84:87]
	v_mfma_f32_16x16x32_bf16 v[80:83], v[158:161], v[202:205], v[80:83]
	v_mfma_f32_16x16x32_bf16 v[68:71], v[150:153], v[210:213], v[68:71]
	v_mfma_f32_16x16x32_bf16 v[64:67], v[158:161], v[210:213], v[64:67]
	v_mfma_f32_16x16x32_bf16 v[52:55], v[150:153], v[218:221], v[52:55]
	v_mfma_f32_16x16x32_bf16 v[48:51], v[158:161], v[218:221], v[48:51]

	v_mfma_f32_16x16x32_bf16 v[76:79], v[174:177], v[190:193], v[76:79]
	v_mfma_f32_16x16x32_bf16 v[72:75], v[182:185], v[190:193], v[72:75]
	v_mfma_f32_16x16x32_bf16 v[60:63], v[174:177], v[198:201], v[60:63]
	v_mfma_f32_16x16x32_bf16 v[56:59], v[182:185], v[198:201], v[56:59]
	v_mfma_f32_16x16x32_bf16 v[44:47], v[174:177], v[206:209], v[44:47]
	v_mfma_f32_16x16x32_bf16 v[40:43], v[182:185], v[206:209], v[40:43]
	v_mfma_f32_16x16x32_bf16 v[36:39], v[174:177], v[214:217], v[36:39]
	v_mfma_f32_16x16x32_bf16 v[32:35], v[182:185], v[214:217], v[32:35]
	v_mfma_f32_16x16x32_bf16 v[76:79], v[178:181], v[194:197], v[76:79]
	v_mfma_f32_16x16x32_bf16 v[72:75], v[186:189], v[194:197], v[72:75]
	v_mfma_f32_16x16x32_bf16 v[60:63], v[178:181], v[202:205], v[60:63]
	v_mfma_f32_16x16x32_bf16 v[56:59], v[186:189], v[202:205], v[56:59]
	v_mfma_f32_16x16x32_bf16 v[44:47], v[178:181], v[210:213], v[44:47]
	v_mfma_f32_16x16x32_bf16 v[40:43], v[186:189], v[210:213], v[40:43]
	v_mfma_f32_16x16x32_bf16 v[36:39], v[178:181], v[218:221], v[36:39]
	v_mfma_f32_16x16x32_bf16 v[32:35], v[186:189], v[218:221], v[32:35]

	s_barrier
	s_add_i32 s56, s90, s25
	v_lshl_add_u64 v[164:165], v[164:165], 0, s[14:15]
	s_mov_b32 m0, s56
	ds_read_b128 v[190:193], v171 offset:49152
	ds_read_b128 v[194:197], v171 offset:50176
	ds_read_b128 v[198:201], v171 offset:51200
	ds_read_b128 v[202:205], v171 offset:52224
	ds_read_b128 v[206:209], v171 offset:53248
	ds_read_b128 v[210:213], v171 offset:54272
	ds_read_b128 v[214:217], v171 offset:55296
	ds_read_b128 v[218:221], v171 offset:56320
	global_load_lds_dwordx4 v[164:165], off
	s_add_i32 m0, s56, 0x2000
	s_add_u32 s54, s54, 0x40080
	v_lshl_add_u64 v[164:165], v[222:223], 0, s[14:15]
	s_addc_u32 s55, s55, 0
	s_add_i32 s56, s91, s25
	global_load_lds_dwordx4 v[164:165], off
	v_lshl_add_u64 v[164:165], s[54:55], 0, v[130:131]
	s_mov_b32 m0, s56
	s_nop 0
	global_load_lds_dwordx4 v[164:165], off
	v_lshl_add_u64 v[164:165], s[54:55], 0, v[134:135]
	s_add_i32 m0, s56, 0x2000
	s_nop 0
	global_load_lds_dwordx4 v[164:165], off
	v_lshl_add_u64 v[164:165], v[224:225], 0, s[14:15]
	s_mov_b32 m0, s63
	s_nop 0
	global_load_lds_dwordx4 v[164:165], off
	v_lshl_add_u64 v[164:165], v[226:227], 0, s[14:15]
	s_mov_b32 m0, s64
	s_nop 0
	global_load_lds_dwordx4 v[164:165], off
	s_waitcnt vmcnt(8)
	s_waitcnt lgkmcnt(0)
	s_barrier

	v_mfma_f32_16x16x32_bf16 v[28:31], v[146:149], v[190:193], v[28:31]
	v_mfma_f32_16x16x32_bf16 v[24:27], v[154:157], v[190:193], v[24:27]
	v_mfma_f32_16x16x32_bf16 v[20:23], v[146:149], v[198:201], v[20:23]
	v_mfma_f32_16x16x32_bf16 v[16:19], v[154:157], v[198:201], v[16:19]
	v_mfma_f32_16x16x32_bf16 v[12:15], v[146:149], v[206:209], v[12:15]
	v_mfma_f32_16x16x32_bf16 v[8:11], v[154:157], v[206:209], v[8:11]
	v_mfma_f32_16x16x32_bf16 v[4:7], v[146:149], v[214:217], v[4:7]
	v_mfma_f32_16x16x32_bf16 v[0:3], v[154:157], v[214:217], v[0:3]
	v_mfma_f32_16x16x32_bf16 v[28:31], v[150:153], v[194:197], v[28:31]
	v_mfma_f32_16x16x32_bf16 v[24:27], v[158:161], v[194:197], v[24:27]
	v_mfma_f32_16x16x32_bf16 v[20:23], v[150:153], v[202:205], v[20:23]
	v_mfma_f32_16x16x32_bf16 v[16:19], v[158:161], v[202:205], v[16:19]
	v_mfma_f32_16x16x32_bf16 v[12:15], v[150:153], v[210:213], v[12:15]
	v_mfma_f32_16x16x32_bf16 v[8:11], v[158:161], v[210:213], v[8:11]
	v_mfma_f32_16x16x32_bf16 v[4:7], v[150:153], v[218:221], v[4:7]
	v_mfma_f32_16x16x32_bf16 v[0:3], v[158:161], v[218:221], v[0:3]

	v_mfma_f32_16x16x32_bf16 v[124:127], v[174:177], v[190:193], v[124:127]
	v_mfma_f32_16x16x32_bf16 v[120:123], v[182:185], v[190:193], v[120:123]
	v_mfma_f32_16x16x32_bf16 v[116:119], v[174:177], v[198:201], v[116:119]
	v_mfma_f32_16x16x32_bf16 v[112:115], v[182:185], v[198:201], v[112:115]
	v_mfma_f32_16x16x32_bf16 v[108:111], v[174:177], v[206:209], v[108:111]
	v_mfma_f32_16x16x32_bf16 v[104:107], v[182:185], v[206:209], v[104:107]
	v_mfma_f32_16x16x32_bf16 v[100:103], v[174:177], v[214:217], v[100:103]
	v_mfma_f32_16x16x32_bf16 v[96:99], v[182:185], v[214:217], v[96:99]
	v_mfma_f32_16x16x32_bf16 v[124:127], v[178:181], v[194:197], v[124:127]
	v_mfma_f32_16x16x32_bf16 v[120:123], v[186:189], v[194:197], v[120:123]
	v_mfma_f32_16x16x32_bf16 v[116:119], v[178:181], v[202:205], v[116:119]
	v_mfma_f32_16x16x32_bf16 v[112:115], v[186:189], v[202:205], v[112:115]
	v_mfma_f32_16x16x32_bf16 v[108:111], v[178:181], v[210:213], v[108:111]
	v_mfma_f32_16x16x32_bf16 v[104:107], v[186:189], v[210:213], v[104:107]
	v_mfma_f32_16x16x32_bf16 v[100:103], v[178:181], v[218:221], v[100:103]
	v_mfma_f32_16x16x32_bf16 v[96:99], v[186:189], v[218:221], v[96:99]

	s_barrier
	s_add_i32 s89, s89, 2
	s_add_u32 s48, s48, 0x100
	s_addc_u32 s49, s49, 0
	s_add_u32 s85, s85, 0x100
	s_addc_u32 s86, s86, 0
	s_cmp_gt_u32 s89, 13
	s_cbranch_scc0 .LBB0_1663

.LBB0_1749:
	ds_read_b128 v[2:5], v243
	ds_read_b128 v[6:9], v243 offset:1024
	ds_read_b128 v[10:13], v243 offset:2048
	ds_read_b128 v[18:21], v243 offset:3072
	ds_read_b128 v[26:29], v244
	ds_read_b128 v[30:33], v244 offset:1024
	ds_read_b128 v[38:41], v244 offset:2048
	ds_read_b128 v[46:49], v244 offset:3072
	s_add_u32 s62, s60, 0xfff80080
	s_addc_u32 s63, s61, -1
	s_cmp_eq_u32 s66, 12
	s_cselect_b32 s69, s3, s65
	s_cselect_b32 s68, s5, s64
	s_cselect_b32 s63, s49, s63
	s_cselect_b32 s62, s52, s62
	v_lshl_add_u64 v[162:163], s[60:61], 0, v[192:193]
	s_add_i32 m0, s71, 0xc000
	ds_read_b128 v[130:133], v245
	ds_read_b128 v[134:137], v245 offset:1024
	ds_read_b128 v[138:141], v245 offset:2048
	ds_read_b128 v[142:145], v245 offset:3072
	ds_read_b128 v[146:149], v245 offset:4096
	ds_read_b128 v[150:153], v245 offset:5120
	ds_read_b128 v[154:157], v245 offset:6144
	ds_read_b128 v[158:161], v245 offset:7168
	global_load_lds_dwordx4 v[162:163], off
	v_lshl_add_u64 v[162:163], s[60:61], 0, v[194:195]
	s_add_i32 m0, s71, 0xe000
	s_nop 0
	global_load_lds_dwordx4 v[162:163], off
	s_waitcnt vmcnt(8)
	s_waitcnt lgkmcnt(0)
	s_barrier

	v_mfma_f32_16x16x32_bf16 v[126:129], v[2:5], v[130:133], v[126:129]
	v_mfma_f32_16x16x32_bf16 v[122:125], v[10:13], v[130:133], v[122:125]
	v_mfma_f32_16x16x32_bf16 v[118:121], v[2:5], v[138:141], v[118:121]
	v_mfma_f32_16x16x32_bf16 v[114:117], v[10:13], v[138:141], v[114:117]
	v_mfma_f32_16x16x32_bf16 v[110:113], v[2:5], v[146:149], v[110:113]
	v_mfma_f32_16x16x32_bf16 v[106:109], v[10:13], v[146:149], v[106:109]
	v_mfma_f32_16x16x32_bf16 v[2:5], v[2:5], v[154:157], v[102:105]
	v_mfma_f32_16x16x32_bf16 v[126:129], v[6:9], v[134:137], v[126:129]
	v_mfma_f32_16x16x32_bf16 v[122:125], v[18:21], v[134:137], v[122:125]
	v_mfma_f32_16x16x32_bf16 v[118:121], v[6:9], v[142:145], v[118:121]
	v_mfma_f32_16x16x32_bf16 v[114:117], v[18:21], v[142:145], v[114:117]
	v_mfma_f32_16x16x32_bf16 v[110:113], v[6:9], v[150:153], v[110:113]
	v_mfma_f32_16x16x32_bf16 v[106:109], v[18:21], v[150:153], v[106:109]
	v_mfma_f32_16x16x32_bf16 v[2:5], v[6:9], v[158:161], v[2:5]
	v_mfma_f32_16x16x32_bf16 v[6:9], v[10:13], v[154:157], v[98:101]
	v_mfma_f32_16x16x32_bf16 v[6:9], v[18:21], v[158:161], v[6:9]

	v_mfma_f32_16x16x32_bf16 v[10:13], v[26:29], v[130:133], v[94:97]
	v_mfma_f32_16x16x32_bf16 v[86:89], v[26:29], v[138:141], v[86:89]
	v_mfma_f32_16x16x32_bf16 v[82:85], v[38:41], v[138:141], v[82:85]
	v_mfma_f32_16x16x32_bf16 v[78:81], v[26:29], v[146:149], v[78:81]
	v_mfma_f32_16x16x32_bf16 v[74:77], v[38:41], v[146:149], v[74:77]
	v_mfma_f32_16x16x32_bf16 v[26:29], v[26:29], v[154:157], v[70:73]
	v_mfma_f32_16x16x32_bf16 v[10:13], v[30:33], v[134:137], v[10:13]
	v_mfma_f32_16x16x32_bf16 v[18:21], v[38:41], v[130:133], v[90:93]
	v_mfma_f32_16x16x32_bf16 v[86:89], v[30:33], v[142:145], v[86:89]
	v_mfma_f32_16x16x32_bf16 v[82:85], v[46:49], v[142:145], v[82:85]
	v_mfma_f32_16x16x32_bf16 v[78:81], v[30:33], v[150:153], v[78:81]
	v_mfma_f32_16x16x32_bf16 v[74:77], v[46:49], v[150:153], v[74:77]
	v_mfma_f32_16x16x32_bf16 v[26:29], v[30:33], v[158:161], v[26:29]
	v_mfma_f32_16x16x32_bf16 v[30:33], v[38:41], v[154:157], v[66:69]
	v_mfma_f32_16x16x32_bf16 v[18:21], v[46:49], v[134:137], v[18:21]
	v_mfma_f32_16x16x32_bf16 v[30:33], v[46:49], v[158:161], v[30:33]

	s_barrier
	s_add_i32 s67, s74, s70
	v_lshl_add_u64 v[178:179], s[62:63], 0, v[184:185]
	s_mov_b32 m0, s67
	ds_read_b128 v[38:41], v246 offset:16384
	ds_read_b128 v[46:49], v246 offset:17408
	ds_read_b128 v[66:69], v246 offset:18432
	ds_read_b128 v[70:73], v246 offset:19456
	global_load_lds_dwordx4 v[178:179], off
	s_add_i32 m0, s67, 0x2000
	s_add_u32 s72, s62, 0x40000
	v_lshl_add_u64 v[180:181], s[62:63], 0, v[188:189]
	s_addc_u32 s73, s63, 0
	s_add_i32 s67, s75, s70
	global_load_lds_dwordx4 v[180:181], off
	v_lshl_add_u64 v[90:91], s[72:73], 0, v[184:185]
	s_mov_b32 m0, s67
	v_lshl_add_u64 v[198:199], s[68:69], 0, v[182:183]
	global_load_lds_dwordx4 v[90:91], off
	v_lshl_add_u64 v[90:91], s[72:73], 0, v[188:189]
	s_add_i32 m0, s67, 0x2000
	v_lshl_add_u64 v[200:201], s[68:69], 0, v[186:187]
	global_load_lds_dwordx4 v[90:91], off
	s_mov_b32 m0, s71
	s_nop 0
	global_load_lds_dwordx4 v[198:199], off
	s_mov_b32 m0, s76
	s_nop 0
	global_load_lds_dwordx4 v[200:201], off
	s_waitcnt vmcnt(8)
	s_waitcnt lgkmcnt(0)
	s_barrier

	v_mfma_f32_16x16x32_bf16 v[62:65], v[38:41], v[130:133], v[62:65]
	v_mfma_f32_16x16x32_bf16 v[58:61], v[66:69], v[130:133], v[58:61]
	v_mfma_f32_16x16x32_bf16 v[54:57], v[38:41], v[138:141], v[54:57]
	v_mfma_f32_16x16x32_bf16 v[50:53], v[66:69], v[138:141], v[50:53]
	v_mfma_f32_16x16x32_bf16 v[42:45], v[38:41], v[146:149], v[42:45]
	v_mfma_f32_16x16x32_bf16 v[34:37], v[66:69], v[146:149], v[34:37]
	v_mfma_f32_16x16x32_bf16 v[22:25], v[38:41], v[154:157], v[22:25]
	v_mfma_f32_16x16x32_bf16 v[14:17], v[66:69], v[154:157], v[14:17]
	v_mfma_f32_16x16x32_bf16 v[62:65], v[46:49], v[134:137], v[62:65]
	v_mfma_f32_16x16x32_bf16 v[58:61], v[70:73], v[134:137], v[58:61]
	v_mfma_f32_16x16x32_bf16 v[54:57], v[46:49], v[142:145], v[54:57]
	v_mfma_f32_16x16x32_bf16 v[50:53], v[70:73], v[142:145], v[50:53]
	v_mfma_f32_16x16x32_bf16 v[42:45], v[46:49], v[150:153], v[42:45]
	v_mfma_f32_16x16x32_bf16 v[34:37], v[70:73], v[150:153], v[34:37]
	v_mfma_f32_16x16x32_bf16 v[22:25], v[46:49], v[158:161], v[22:25]
	v_mfma_f32_16x16x32_bf16 v[14:17], v[70:73], v[158:161], v[14:17]

	s_barrier
	s_add_i32 s67, 0, 0x18000
	v_add_u32_e32 v1, s67, v241
	s_add_i32 s72, 0, 0x1c000
	ds_read_b128 v[38:41], v1
	ds_read_b128 v[46:49], v1 offset:1024
	ds_read_b128 v[66:69], v1 offset:2048
	ds_read_b128 v[70:73], v1 offset:3072
	v_add_u32_e32 v1, s72, v241
	ds_read_b128 v[130:133], v1
	ds_read_b128 v[134:137], v1 offset:1024
	ds_read_b128 v[138:141], v1 offset:2048
	ds_read_b128 v[142:145], v1 offset:3072
	s_add_u32 s68, s62, 0x80000
	s_addc_u32 s69, s63, 0
	s_mov_b32 m0, s77
	v_lshl_add_u64 v[90:91], s[68:69], 0, v[184:185]
	ds_read_b128 v[146:149], v245 offset:32768
	ds_read_b128 v[150:153], v245 offset:33792
	ds_read_b128 v[154:157], v245 offset:34816
	ds_read_b128 v[158:161], v245 offset:35840
	ds_read_b128 v[162:165], v245 offset:36864
	ds_read_b128 v[166:169], v245 offset:37888
	ds_read_b128 v[170:173], v245 offset:38912
	ds_read_b128 v[174:177], v245 offset:39936
	global_load_lds_dwordx4 v[90:91], off
	v_lshl_add_u64 v[90:91], s[68:69], 0, v[188:189]
	s_mov_b32 m0, s78
	s_nop 0
	global_load_lds_dwordx4 v[90:91], off
	s_waitcnt vmcnt(8)
	s_waitcnt lgkmcnt(0)
	s_barrier

	v_mfma_f32_16x16x32_bf16 v[90:93], v[38:41], v[146:149], v[126:129]
	v_mfma_f32_16x16x32_bf16 v[126:129], v[46:49], v[150:153], v[90:93]
	v_mfma_f32_16x16x32_bf16 v[90:93], v[66:69], v[146:149], v[122:125]
	v_mfma_f32_16x16x32_bf16 v[122:125], v[70:73], v[150:153], v[90:93]
	v_mfma_f32_16x16x32_bf16 v[90:93], v[38:41], v[154:157], v[118:121]
	v_mfma_f32_16x16x32_bf16 v[118:121], v[46:49], v[158:161], v[90:93]
	v_mfma_f32_16x16x32_bf16 v[90:93], v[66:69], v[154:157], v[114:117]
	v_mfma_f32_16x16x32_bf16 v[114:117], v[70:73], v[158:161], v[90:93]
	v_mfma_f32_16x16x32_bf16 v[90:93], v[38:41], v[162:165], v[110:113]
	v_mfma_f32_16x16x32_bf16 v[2:5], v[38:41], v[170:173], v[2:5]
	v_mfma_f32_16x16x32_bf16 v[110:113], v[46:49], v[166:169], v[90:93]
	v_mfma_f32_16x16x32_bf16 v[90:93], v[66:69], v[162:165], v[106:109]
	v_mfma_f32_16x16x32_bf16 v[102:105], v[46:49], v[174:177], v[2:5]
	v_mfma_f32_16x16x32_bf16 v[2:5], v[66:69], v[170:173], v[6:9]
	v_mfma_f32_16x16x32_bf16 v[106:109], v[70:73], v[166:169], v[90:93]
	v_mfma_f32_16x16x32_bf16 v[98:101], v[70:73], v[174:177], v[2:5]

	v_mfma_f32_16x16x32_bf16 v[2:5], v[130:133], v[146:149], v[10:13]
	v_mfma_f32_16x16x32_bf16 v[94:97], v[134:137], v[150:153], v[2:5]
	v_mfma_f32_16x16x32_bf16 v[2:5], v[138:141], v[146:149], v[18:21]
	v_mfma_f32_16x16x32_bf16 v[90:93], v[142:145], v[150:153], v[2:5]
	v_mfma_f32_16x16x32_bf16 v[2:5], v[130:133], v[154:157], v[86:89]
	v_mfma_f32_16x16x32_bf16 v[86:89], v[134:137], v[158:161], v[2:5]
	v_mfma_f32_16x16x32_bf16 v[2:5], v[138:141], v[154:157], v[82:85]
	v_mfma_f32_16x16x32_bf16 v[82:85], v[142:145], v[158:161], v[2:5]
	v_mfma_f32_16x16x32_bf16 v[2:5], v[130:133], v[162:165], v[78:81]
	v_mfma_f32_16x16x32_bf16 v[78:81], v[134:137], v[166:169], v[2:5]
	v_mfma_f32_16x16x32_bf16 v[2:5], v[138:141], v[162:165], v[74:77]
	v_mfma_f32_16x16x32_bf16 v[74:77], v[142:145], v[166:169], v[2:5]
	v_mfma_f32_16x16x32_bf16 v[2:5], v[130:133], v[170:173], v[26:29]
	v_mfma_f32_16x16x32_bf16 v[70:73], v[134:137], v[174:177], v[2:5]
	v_mfma_f32_16x16x32_bf16 v[2:5], v[138:141], v[170:173], v[30:33]
	v_mfma_f32_16x16x32_bf16 v[66:69], v[142:145], v[174:177], v[2:5]

	s_barrier
	s_add_i32 s67, s67, s70
	v_lshl_add_u64 v[26:27], v[178:179], 0, s[38:39]
	s_mov_b32 m0, s67
	s_nop 1
	ds_read_b128 v[2:5], v246 offset:49152
	ds_read_b128 v[6:9], v246 offset:50176
	ds_read_b128 v[10:13], v246 offset:51200
	ds_read_b128 v[18:21], v246 offset:52224
	global_load_lds_dwordx4 v[26:27], off
	s_add_i32 m0, s67, 0x2000
	s_add_u32 s62, s62, 0x40080
	v_lshl_add_u64 v[26:27], v[180:181], 0, s[38:39]
	s_addc_u32 s63, s63, 0
	s_add_i32 s67, s72, s70
	global_load_lds_dwordx4 v[26:27], off
	v_lshl_add_u64 v[26:27], s[62:63], 0, v[184:185]
	s_mov_b32 m0, s67
	s_nop 0
	global_load_lds_dwordx4 v[26:27], off
	v_lshl_add_u64 v[26:27], s[62:63], 0, v[188:189]
	s_add_i32 m0, s67, 0x2000
	s_nop 0
	global_load_lds_dwordx4 v[26:27], off
	v_lshl_add_u64 v[26:27], v[198:199], 0, s[38:39]
	s_mov_b32 m0, s79
	s_nop 0
	global_load_lds_dwordx4 v[26:27], off
	v_lshl_add_u64 v[26:27], v[200:201], 0, s[38:39]
	s_mov_b32 m0, s80
	s_nop 0
	global_load_lds_dwordx4 v[26:27], off
	s_waitcnt vmcnt(8)
	s_waitcnt lgkmcnt(0)
	s_barrier

	v_mfma_f32_16x16x32_bf16 v[26:29], v[2:5], v[146:149], v[62:65]
	v_mfma_f32_16x16x32_bf16 v[62:65], v[6:9], v[150:153], v[26:29]
	v_mfma_f32_16x16x32_bf16 v[26:29], v[10:13], v[146:149], v[58:61]
	v_mfma_f32_16x16x32_bf16 v[58:61], v[18:21], v[150:153], v[26:29]
	v_mfma_f32_16x16x32_bf16 v[26:29], v[2:5], v[154:157], v[54:57]
	v_mfma_f32_16x16x32_bf16 v[54:57], v[6:9], v[158:161], v[26:29]
	v_mfma_f32_16x16x32_bf16 v[26:29], v[10:13], v[154:157], v[50:53]
	v_mfma_f32_16x16x32_bf16 v[50:53], v[18:21], v[158:161], v[26:29]
	v_mfma_f32_16x16x32_bf16 v[26:29], v[2:5], v[162:165], v[42:45]
	v_mfma_f32_16x16x32_bf16 v[2:5], v[2:5], v[170:173], v[22:25]
	v_mfma_f32_16x16x32_bf16 v[42:45], v[6:9], v[166:169], v[26:29]
	v_mfma_f32_16x16x32_bf16 v[26:29], v[10:13], v[162:165], v[34:37]
	v_mfma_f32_16x16x32_bf16 v[22:25], v[6:9], v[174:177], v[2:5]
	v_mfma_f32_16x16x32_bf16 v[2:5], v[10:13], v[170:173], v[14:17]
	v_mfma_f32_16x16x32_bf16 v[34:37], v[18:21], v[166:169], v[26:29]
	v_mfma_f32_16x16x32_bf16 v[14:17], v[18:21], v[174:177], v[2:5]

	s_barrier
	s_add_i32 s66, s66, 2
	s_add_u32 s64, s64, 0x100
	s_addc_u32 s65, s65, 0
	s_add_u32 s60, s60, 0x100
	s_addc_u32 s61, s61, 0
	s_cmp_gt_u32 s66, 13
	s_cbranch_scc0 .LBB0_1749
	s_branch .LBB0_1801

.LBB0_1752:
	ds_read_b128 v[130:133], v243
	ds_read_b128 v[134:137], v243 offset:1024
	ds_read_b128 v[138:141], v243 offset:2048
	ds_read_b128 v[142:145], v243 offset:3072
	ds_read_b128 v[146:149], v244
	ds_read_b128 v[150:153], v244 offset:1024
	ds_read_b128 v[154:157], v244 offset:2048
	ds_read_b128 v[158:161], v244 offset:3072
	s_add_u32 s66, s8, 0xfffc0080
	s_addc_u32 s67, s9, -1
	s_cmp_eq_u32 s72, 12
	s_cselect_b64 s[64:65], -1, 0
	s_and_b64 s[62:63], s[64:65], exec
	s_cselect_b32 s63, s49, s55
	s_cselect_b32 s62, s52, s53
	s_cselect_b32 s67, s3, s67
	s_cselect_b32 s66, s5, s66
	v_lshl_add_u64 v[210:211], s[8:9], 0, v[196:197]
	s_add_i32 m0, s71, 0xc000
	ds_read_b128 v[162:165], v245
	ds_read_b128 v[166:169], v245 offset:1024
	ds_read_b128 v[170:173], v245 offset:2048
	ds_read_b128 v[174:177], v245 offset:3072
	ds_read_b128 v[178:181], v245 offset:4096
	ds_read_b128 v[198:201], v245 offset:5120
	ds_read_b128 v[202:205], v245 offset:6144
	ds_read_b128 v[206:209], v245 offset:7168
	global_load_lds_dwordx4 v[210:211], off
	v_lshl_add_u64 v[210:211], s[8:9], 0, v[186:187]
	s_add_i32 m0, s71, 0xe000
	s_nop 0
	global_load_lds_dwordx4 v[210:211], off
	s_waitcnt vmcnt(8)
	s_waitcnt lgkmcnt(0)
	s_barrier

	v_mfma_f32_16x16x32_bf16 v[126:129], v[130:133], v[162:165], v[126:129]
	v_mfma_f32_16x16x32_bf16 v[122:125], v[138:141], v[162:165], v[122:125]
	v_mfma_f32_16x16x32_bf16 v[118:121], v[130:133], v[170:173], v[118:121]
	v_mfma_f32_16x16x32_bf16 v[114:117], v[138:141], v[170:173], v[114:117]
	v_mfma_f32_16x16x32_bf16 v[110:113], v[130:133], v[178:181], v[110:113]
	v_mfma_f32_16x16x32_bf16 v[106:109], v[138:141], v[178:181], v[106:109]
	v_mfma_f32_16x16x32_bf16 v[102:105], v[130:133], v[202:205], v[102:105]
	v_mfma_f32_16x16x32_bf16 v[98:101], v[138:141], v[202:205], v[98:101]
	v_mfma_f32_16x16x32_bf16 v[126:129], v[134:137], v[166:169], v[126:129]
	v_mfma_f32_16x16x32_bf16 v[122:125], v[142:145], v[166:169], v[122:125]
	v_mfma_f32_16x16x32_bf16 v[118:121], v[134:137], v[174:177], v[118:121]
	v_mfma_f32_16x16x32_bf16 v[114:117], v[142:145], v[174:177], v[114:117]
	v_mfma_f32_16x16x32_bf16 v[110:113], v[134:137], v[198:201], v[110:113]
	v_mfma_f32_16x16x32_bf16 v[106:109], v[142:145], v[198:201], v[106:109]
	v_mfma_f32_16x16x32_bf16 v[102:105], v[134:137], v[206:209], v[102:105]
	v_mfma_f32_16x16x32_bf16 v[98:101], v[142:145], v[206:209], v[98:101]

	v_mfma_f32_16x16x32_bf16 v[94:97], v[146:149], v[162:165], v[94:97]
	v_mfma_f32_16x16x32_bf16 v[90:93], v[154:157], v[162:165], v[90:93]
	v_mfma_f32_16x16x32_bf16 v[86:89], v[146:149], v[170:173], v[86:89]
	v_mfma_f32_16x16x32_bf16 v[82:85], v[154:157], v[170:173], v[82:85]
	v_mfma_f32_16x16x32_bf16 v[78:81], v[146:149], v[178:181], v[78:81]
	v_mfma_f32_16x16x32_bf16 v[74:77], v[154:157], v[178:181], v[74:77]
	v_mfma_f32_16x16x32_bf16 v[70:73], v[146:149], v[202:205], v[70:73]
	v_mfma_f32_16x16x32_bf16 v[66:69], v[154:157], v[202:205], v[66:69]
	v_mfma_f32_16x16x32_bf16 v[94:97], v[150:153], v[166:169], v[94:97]
	v_mfma_f32_16x16x32_bf16 v[90:93], v[158:161], v[166:169], v[90:93]
	v_mfma_f32_16x16x32_bf16 v[86:89], v[150:153], v[174:177], v[86:89]
	v_mfma_f32_16x16x32_bf16 v[82:85], v[158:161], v[174:177], v[82:85]
	v_mfma_f32_16x16x32_bf16 v[78:81], v[150:153], v[198:201], v[78:81]
	v_mfma_f32_16x16x32_bf16 v[74:77], v[158:161], v[198:201], v[74:77]
	v_mfma_f32_16x16x32_bf16 v[70:73], v[150:153], v[206:209], v[70:73]
	v_mfma_f32_16x16x32_bf16 v[66:69], v[158:161], v[206:209], v[66:69]

	s_barrier
	s_add_i32 s73, s74, s70
	v_lshl_add_u64 v[210:211], s[62:63], 0, v[184:185]
	s_mov_b32 m0, s73
	ds_read_b128 v[162:165], v245 offset:16384
	ds_read_b128 v[166:169], v245 offset:17408
	ds_read_b128 v[170:173], v245 offset:18432
	ds_read_b128 v[174:177], v245 offset:19456
	ds_read_b128 v[178:181], v245 offset:20480
	ds_read_b128 v[198:201], v245 offset:21504
	ds_read_b128 v[202:205], v245 offset:22528
	ds_read_b128 v[206:209], v245 offset:23552
	global_load_lds_dwordx4 v[210:211], off
	s_add_i32 m0, s73, 0x2000
	s_add_u32 vcc_lo, s62, 0x40000
	v_lshl_add_u64 v[212:213], s[62:63], 0, v[188:189]
	s_addc_u32 vcc_hi, s63, 0
	s_add_i32 s73, s75, s70
	global_load_lds_dwordx4 v[212:213], off
	v_lshl_add_u64 v[214:215], vcc, 0, v[184:185]
	s_mov_b32 m0, s73
	v_lshl_add_u64 v[216:217], s[66:67], 0, v[186:187]
	global_load_lds_dwordx4 v[214:215], off
	v_lshl_add_u64 v[214:215], vcc, 0, v[188:189]
	s_add_i32 m0, s73, 0x2000
	s_nop 0
	global_load_lds_dwordx4 v[214:215], off
	v_lshl_add_u64 v[214:215], s[66:67], 0, v[182:183]
	s_mov_b32 m0, s71
	s_nop 0
	global_load_lds_dwordx4 v[214:215], off
	s_mov_b32 m0, s76
	s_nop 0
	global_load_lds_dwordx4 v[216:217], off
	s_waitcnt vmcnt(8)
	s_waitcnt lgkmcnt(0)
	s_barrier

	v_mfma_f32_16x16x32_bf16 v[62:65], v[130:133], v[162:165], v[62:65]
	v_mfma_f32_16x16x32_bf16 v[58:61], v[138:141], v[162:165], v[58:61]
	v_mfma_f32_16x16x32_bf16 v[54:57], v[130:133], v[170:173], v[54:57]
	v_mfma_f32_16x16x32_bf16 v[50:53], v[138:141], v[170:173], v[50:53]
	v_mfma_f32_16x16x32_bf16 v[42:45], v[130:133], v[178:181], v[42:45]
	v_mfma_f32_16x16x32_bf16 v[34:37], v[138:141], v[178:181], v[34:37]
	v_mfma_f32_16x16x32_bf16 v[22:25], v[130:133], v[202:205], v[22:25]
	v_mfma_f32_16x16x32_bf16 v[14:17], v[138:141], v[202:205], v[14:17]
	v_mfma_f32_16x16x32_bf16 v[62:65], v[134:137], v[166:169], v[62:65]
	v_mfma_f32_16x16x32_bf16 v[58:61], v[142:145], v[166:169], v[58:61]
	v_mfma_f32_16x16x32_bf16 v[54:57], v[134:137], v[174:177], v[54:57]
	v_mfma_f32_16x16x32_bf16 v[50:53], v[142:145], v[174:177], v[50:53]
	v_mfma_f32_16x16x32_bf16 v[42:45], v[134:137], v[198:201], v[42:45]
	v_mfma_f32_16x16x32_bf16 v[34:37], v[142:145], v[198:201], v[34:37]
	v_mfma_f32_16x16x32_bf16 v[22:25], v[134:137], v[206:209], v[22:25]
	v_mfma_f32_16x16x32_bf16 v[14:17], v[142:145], v[206:209], v[14:17]

	v_mfma_f32_16x16x32_bf16 v[46:49], v[146:149], v[162:165], v[46:49]
	v_mfma_f32_16x16x32_bf16 v[38:41], v[154:157], v[162:165], v[38:41]
	v_mfma_f32_16x16x32_bf16 v[30:33], v[146:149], v[170:173], v[30:33]
	v_mfma_f32_16x16x32_bf16 v[26:29], v[154:157], v[170:173], v[26:29]
	v_mfma_f32_16x16x32_bf16 v[18:21], v[146:149], v[178:181], v[18:21]
	v_mfma_f32_16x16x32_bf16 v[10:13], v[154:157], v[178:181], v[10:13]
	v_mfma_f32_16x16x32_bf16 v[6:9], v[146:149], v[202:205], v[6:9]
	v_mfma_f32_16x16x32_bf16 v[2:5], v[154:157], v[202:205], v[2:5]
	v_mfma_f32_16x16x32_bf16 v[46:49], v[150:153], v[166:169], v[46:49]
	v_mfma_f32_16x16x32_bf16 v[38:41], v[158:161], v[166:169], v[38:41]
	v_mfma_f32_16x16x32_bf16 v[30:33], v[150:153], v[174:177], v[30:33]
	v_mfma_f32_16x16x32_bf16 v[26:29], v[158:161], v[174:177], v[26:29]
	v_mfma_f32_16x16x32_bf16 v[18:21], v[150:153], v[198:201], v[18:21]
	v_mfma_f32_16x16x32_bf16 v[10:13], v[158:161], v[198:201], v[10:13]
	v_mfma_f32_16x16x32_bf16 v[6:9], v[150:153], v[206:209], v[6:9]
	v_mfma_f32_16x16x32_bf16 v[2:5], v[158:161], v[206:209], v[2:5]

	s_barrier
	s_add_i32 s73, 0, 0x18000
	v_add_u32_e32 v1, s73, v241
	s_add_i32 s96, 0, 0x1c000
	ds_read_b128 v[130:133], v1
	ds_read_b128 v[134:137], v1 offset:1024
	ds_read_b128 v[138:141], v1 offset:2048
	ds_read_b128 v[142:145], v1 offset:3072
	v_add_u32_e32 v1, s96, v241
	ds_read_b128 v[146:149], v1
	ds_read_b128 v[150:153], v1 offset:1024
	ds_read_b128 v[154:157], v1 offset:2048
	ds_read_b128 v[158:161], v1 offset:3072
	s_and_b64 s[64:65], s[50:51], s[64:65]
	s_and_b64 vcc, s[64:65], s[60:61]
	s_add_u32 s66, s66, 0x40000
	s_addc_u32 s67, s67, 0
	s_and_b64 s[64:65], vcc, exec
	s_mov_b32 m0, s77
	v_cndmask_b32_e32 v1, v182, v184, vcc
	s_cselect_b32 s65, s69, s67
	s_cselect_b32 s64, s68, s66
	ds_read_b128 v[162:165], v245 offset:32768
	ds_read_b128 v[166:169], v245 offset:33792
	ds_read_b128 v[170:173], v245 offset:34816
	ds_read_b128 v[174:177], v245 offset:35840
	ds_read_b128 v[178:181], v245 offset:36864
	ds_read_b128 v[198:201], v245 offset:37888
	ds_read_b128 v[202:205], v245 offset:38912
	ds_read_b128 v[206:209], v245 offset:39936
	v_cndmask_b32_e32 v218, v186, v188, vcc
	global_load_lds_dwordx4 v1, s[64:65]
	s_mov_b32 m0, s78
	s_nop 0
	global_load_lds_dwordx4 v218, s[64:65]
	s_waitcnt vmcnt(8)
	s_waitcnt lgkmcnt(0)
	s_barrier

	v_mfma_f32_16x16x32_bf16 v[126:129], v[130:133], v[162:165], v[126:129]
	v_mfma_f32_16x16x32_bf16 v[122:125], v[138:141], v[162:165], v[122:125]
	v_mfma_f32_16x16x32_bf16 v[118:121], v[130:133], v[170:173], v[118:121]
	v_mfma_f32_16x16x32_bf16 v[114:117], v[138:141], v[170:173], v[114:117]
	v_mfma_f32_16x16x32_bf16 v[110:113], v[130:133], v[178:181], v[110:113]
	v_mfma_f32_16x16x32_bf16 v[106:109], v[138:141], v[178:181], v[106:109]
	v_mfma_f32_16x16x32_bf16 v[102:105], v[130:133], v[202:205], v[102:105]
	v_mfma_f32_16x16x32_bf16 v[98:101], v[138:141], v[202:205], v[98:101]
	v_mfma_f32_16x16x32_bf16 v[126:129], v[134:137], v[166:169], v[126:129]
	v_mfma_f32_16x16x32_bf16 v[122:125], v[142:145], v[166:169], v[122:125]
	v_mfma_f32_16x16x32_bf16 v[118:121], v[134:137], v[174:177], v[118:121]
	v_mfma_f32_16x16x32_bf16 v[114:117], v[142:145], v[174:177], v[114:117]
	v_mfma_f32_16x16x32_bf16 v[110:113], v[134:137], v[198:201], v[110:113]
	v_mfma_f32_16x16x32_bf16 v[106:109], v[142:145], v[198:201], v[106:109]
	v_mfma_f32_16x16x32_bf16 v[102:105], v[134:137], v[206:209], v[102:105]
	v_mfma_f32_16x16x32_bf16 v[98:101], v[142:145], v[206:209], v[98:101]

	v_mfma_f32_16x16x32_bf16 v[94:97], v[146:149], v[162:165], v[94:97]
	v_mfma_f32_16x16x32_bf16 v[90:93], v[154:157], v[162:165], v[90:93]
	v_mfma_f32_16x16x32_bf16 v[86:89], v[146:149], v[170:173], v[86:89]
	v_mfma_f32_16x16x32_bf16 v[82:85], v[154:157], v[170:173], v[82:85]
	v_mfma_f32_16x16x32_bf16 v[78:81], v[146:149], v[178:181], v[78:81]
	v_mfma_f32_16x16x32_bf16 v[74:77], v[154:157], v[178:181], v[74:77]
	v_mfma_f32_16x16x32_bf16 v[70:73], v[146:149], v[202:205], v[70:73]
	v_mfma_f32_16x16x32_bf16 v[66:69], v[154:157], v[202:205], v[66:69]
	v_mfma_f32_16x16x32_bf16 v[94:97], v[150:153], v[166:169], v[94:97]
	v_mfma_f32_16x16x32_bf16 v[90:93], v[158:161], v[166:169], v[90:93]
	v_mfma_f32_16x16x32_bf16 v[86:89], v[150:153], v[174:177], v[86:89]
	v_mfma_f32_16x16x32_bf16 v[82:85], v[158:161], v[174:177], v[82:85]
	v_mfma_f32_16x16x32_bf16 v[78:81], v[150:153], v[198:201], v[78:81]
	v_mfma_f32_16x16x32_bf16 v[74:77], v[158:161], v[198:201], v[74:77]
	v_mfma_f32_16x16x32_bf16 v[70:73], v[150:153], v[206:209], v[70:73]
	v_mfma_f32_16x16x32_bf16 v[66:69], v[158:161], v[206:209], v[66:69]

	s_barrier
	s_add_i32 s64, s73, s70
	v_lshl_add_u64 v[210:211], v[210:211], 0, s[38:39]
	s_mov_b32 m0, s64
	ds_read_b128 v[162:165], v245 offset:49152
	ds_read_b128 v[166:169], v245 offset:50176
	ds_read_b128 v[170:173], v245 offset:51200
	ds_read_b128 v[174:177], v245 offset:52224
	ds_read_b128 v[178:181], v245 offset:53248
	ds_read_b128 v[198:201], v245 offset:54272
	ds_read_b128 v[202:205], v245 offset:55296
	ds_read_b128 v[206:209], v245 offset:56320
	global_load_lds_dwordx4 v[210:211], off
	s_add_i32 m0, s64, 0x2000
	s_add_u32 s62, s62, 0x40080
	v_lshl_add_u64 v[210:211], v[212:213], 0, s[38:39]
	s_addc_u32 s63, s63, 0
	s_add_i32 s64, s96, s70
	global_load_lds_dwordx4 v[210:211], off
	v_lshl_add_u64 v[210:211], s[62:63], 0, v[184:185]
	s_mov_b32 m0, s64
	s_nop 0
	global_load_lds_dwordx4 v[210:211], off
	v_lshl_add_u64 v[210:211], s[62:63], 0, v[188:189]
	s_add_i32 m0, s64, 0x2000
	s_nop 0
	global_load_lds_dwordx4 v[210:211], off
	v_lshl_add_u64 v[210:211], v[214:215], 0, s[38:39]
	s_mov_b32 m0, s79
	s_nop 0
	global_load_lds_dwordx4 v[210:211], off
	v_lshl_add_u64 v[210:211], v[216:217], 0, s[38:39]
	s_mov_b32 m0, s80
	s_nop 0
	global_load_lds_dwordx4 v[210:211], off
	s_waitcnt vmcnt(8)
	s_waitcnt lgkmcnt(0)
	s_barrier

	v_mfma_f32_16x16x32_bf16 v[62:65], v[130:133], v[162:165], v[62:65]
	v_mfma_f32_16x16x32_bf16 v[58:61], v[138:141], v[162:165], v[58:61]
	v_mfma_f32_16x16x32_bf16 v[54:57], v[130:133], v[170:173], v[54:57]
	v_mfma_f32_16x16x32_bf16 v[50:53], v[138:141], v[170:173], v[50:53]
	v_mfma_f32_16x16x32_bf16 v[42:45], v[130:133], v[178:181], v[42:45]
	v_mfma_f32_16x16x32_bf16 v[34:37], v[138:141], v[178:181], v[34:37]
	v_mfma_f32_16x16x32_bf16 v[22:25], v[130:133], v[202:205], v[22:25]
	v_mfma_f32_16x16x32_bf16 v[14:17], v[138:141], v[202:205], v[14:17]
	v_mfma_f32_16x16x32_bf16 v[62:65], v[134:137], v[166:169], v[62:65]
	v_mfma_f32_16x16x32_bf16 v[58:61], v[142:145], v[166:169], v[58:61]
	v_mfma_f32_16x16x32_bf16 v[54:57], v[134:137], v[174:177], v[54:57]
	v_mfma_f32_16x16x32_bf16 v[50:53], v[142:145], v[174:177], v[50:53]
	v_mfma_f32_16x16x32_bf16 v[42:45], v[134:137], v[198:201], v[42:45]
	v_mfma_f32_16x16x32_bf16 v[34:37], v[142:145], v[198:201], v[34:37]
	v_mfma_f32_16x16x32_bf16 v[22:25], v[134:137], v[206:209], v[22:25]
	v_mfma_f32_16x16x32_bf16 v[14:17], v[142:145], v[206:209], v[14:17]

	v_mfma_f32_16x16x32_bf16 v[46:49], v[146:149], v[162:165], v[46:49]
	v_mfma_f32_16x16x32_bf16 v[38:41], v[154:157], v[162:165], v[38:41]
	v_mfma_f32_16x16x32_bf16 v[30:33], v[146:149], v[170:173], v[30:33]
	v_mfma_f32_16x16x32_bf16 v[26:29], v[154:157], v[170:173], v[26:29]
	v_mfma_f32_16x16x32_bf16 v[18:21], v[146:149], v[178:181], v[18:21]
	v_mfma_f32_16x16x32_bf16 v[10:13], v[154:157], v[178:181], v[10:13]
	v_mfma_f32_16x16x32_bf16 v[6:9], v[146:149], v[202:205], v[6:9]
	v_mfma_f32_16x16x32_bf16 v[2:5], v[154:157], v[202:205], v[2:5]
	v_mfma_f32_16x16x32_bf16 v[46:49], v[150:153], v[166:169], v[46:49]
	v_mfma_f32_16x16x32_bf16 v[38:41], v[158:161], v[166:169], v[38:41]
	v_mfma_f32_16x16x32_bf16 v[30:33], v[150:153], v[174:177], v[30:33]
	v_mfma_f32_16x16x32_bf16 v[26:29], v[158:161], v[174:177], v[26:29]
	v_mfma_f32_16x16x32_bf16 v[18:21], v[150:153], v[198:201], v[18:21]
	v_mfma_f32_16x16x32_bf16 v[10:13], v[158:161], v[198:201], v[10:13]
	v_mfma_f32_16x16x32_bf16 v[6:9], v[150:153], v[206:209], v[6:9]
	v_mfma_f32_16x16x32_bf16 v[2:5], v[158:161], v[206:209], v[2:5]

	s_barrier
	s_add_i32 s72, s72, 2
	s_add_u32 s8, s8, 0x100
	s_addc_u32 s9, s9, 0
	s_add_u32 s53, s53, 0x100
	s_addc_u32 s55, s55, 0
	s_cmp_gt_u32 s72, 13
	s_cbranch_scc0 .LBB0_1752
	s_andn2_b64 vcc, exec, s[40:41]
	s_cbranch_vccnz .LBB0_1755

.LBB0_1882:
	ds_read_b128 v[128:131], v203
	ds_read_b128 v[132:135], v203 offset:1024
	ds_read_b128 v[136:139], v203 offset:2048
	ds_read_b128 v[140:143], v203 offset:3072
	ds_read_b128 v[144:147], v204
	ds_read_b128 v[148:151], v204 offset:1024
	ds_read_b128 v[152:155], v204 offset:2048
	ds_read_b128 v[172:175], v204 offset:3072
	s_add_u32 s2, s22, 0x100
	s_addc_u32 s3, s23, 0
	s_cmp_eq_u32 s58, 40
	s_cselect_b32 s29, s21, s3
	s_cselect_b32 s28, s20, s2
	s_cselect_b32 s25, s5, s57
	s_cselect_b32 s24, s4, s56
	v_lshl_add_u64 v[214:215], s[22:23], 0, v[164:165]
	s_add_i32 m0, s39, 0xc000
	ds_read_b128 v[176:179], v205
	ds_read_b128 v[180:183], v205 offset:1024
	ds_read_b128 v[184:187], v205 offset:2048
	ds_read_b128 v[188:191], v205 offset:3072
	ds_read_b128 v[192:195], v205 offset:4096
	ds_read_b128 v[196:199], v205 offset:5120
	ds_read_b128 v[206:209], v205 offset:6144
	ds_read_b128 v[210:213], v205 offset:7168
	global_load_lds_dwordx4 v[214:215], off
	v_lshl_add_u64 v[214:215], s[22:23], 0, v[166:167]
	s_add_i32 m0, s39, 0xe000
	s_nop 0
	global_load_lds_dwordx4 v[214:215], off
	s_waitcnt vmcnt(8)
	s_waitcnt lgkmcnt(0)
	s_barrier

	v_mfma_f32_16x16x32_bf16 v[124:127], v[128:131], v[176:179], v[124:127]
	v_mfma_f32_16x16x32_bf16 v[120:123], v[136:139], v[176:179], v[120:123]
	v_mfma_f32_16x16x32_bf16 v[108:111], v[128:131], v[184:187], v[108:111]
	v_mfma_f32_16x16x32_bf16 v[104:107], v[136:139], v[184:187], v[104:107]
	v_mfma_f32_16x16x32_bf16 v[92:95], v[128:131], v[192:195], v[92:95]
	v_mfma_f32_16x16x32_bf16 v[88:91], v[136:139], v[192:195], v[88:91]
	v_mfma_f32_16x16x32_bf16 v[76:79], v[128:131], v[206:209], v[76:79]
	v_mfma_f32_16x16x32_bf16 v[72:75], v[136:139], v[206:209], v[72:75]
	v_mfma_f32_16x16x32_bf16 v[124:127], v[132:135], v[180:183], v[124:127]
	v_mfma_f32_16x16x32_bf16 v[120:123], v[140:143], v[180:183], v[120:123]
	v_mfma_f32_16x16x32_bf16 v[108:111], v[132:135], v[188:191], v[108:111]
	v_mfma_f32_16x16x32_bf16 v[104:107], v[140:143], v[188:191], v[104:107]
	v_mfma_f32_16x16x32_bf16 v[92:95], v[132:135], v[196:199], v[92:95]
	v_mfma_f32_16x16x32_bf16 v[88:91], v[140:143], v[196:199], v[88:91]
	v_mfma_f32_16x16x32_bf16 v[76:79], v[132:135], v[210:213], v[76:79]
	v_mfma_f32_16x16x32_bf16 v[72:75], v[140:143], v[210:213], v[72:75]

	v_mfma_f32_16x16x32_bf16 v[116:119], v[144:147], v[176:179], v[116:119]
	v_mfma_f32_16x16x32_bf16 v[112:115], v[152:155], v[176:179], v[112:115]
	v_mfma_f32_16x16x32_bf16 v[100:103], v[144:147], v[184:187], v[100:103]
	v_mfma_f32_16x16x32_bf16 v[96:99], v[152:155], v[184:187], v[96:99]
	v_mfma_f32_16x16x32_bf16 v[84:87], v[144:147], v[192:195], v[84:87]
	v_mfma_f32_16x16x32_bf16 v[80:83], v[152:155], v[192:195], v[80:83]
	v_mfma_f32_16x16x32_bf16 v[68:71], v[144:147], v[206:209], v[68:71]
	v_mfma_f32_16x16x32_bf16 v[64:67], v[152:155], v[206:209], v[64:67]
	v_mfma_f32_16x16x32_bf16 v[116:119], v[148:151], v[180:183], v[116:119]
	v_mfma_f32_16x16x32_bf16 v[112:115], v[172:175], v[180:183], v[112:115]
	v_mfma_f32_16x16x32_bf16 v[100:103], v[148:151], v[188:191], v[100:103]
	v_mfma_f32_16x16x32_bf16 v[96:99], v[172:175], v[188:191], v[96:99]
	v_mfma_f32_16x16x32_bf16 v[84:87], v[148:151], v[196:199], v[84:87]
	v_mfma_f32_16x16x32_bf16 v[80:83], v[172:175], v[196:199], v[80:83]
	v_mfma_f32_16x16x32_bf16 v[68:71], v[148:151], v[210:213], v[68:71]
	v_mfma_f32_16x16x32_bf16 v[64:67], v[172:175], v[210:213], v[64:67]

	s_barrier
	s_add_i32 s22, s48, s38
	v_lshl_add_u64 v[214:215], s[24:25], 0, v[158:159]
	s_mov_b32 m0, s22
	ds_read_b128 v[176:179], v205 offset:16384
	ds_read_b128 v[180:183], v205 offset:17408
	ds_read_b128 v[184:187], v205 offset:18432
	ds_read_b128 v[188:191], v205 offset:19456
	ds_read_b128 v[192:195], v205 offset:20480
	ds_read_b128 v[196:199], v205 offset:21504
	ds_read_b128 v[206:209], v205 offset:22528
	ds_read_b128 v[210:213], v205 offset:23552
	global_load_lds_dwordx4 v[214:215], off
	s_add_i32 m0, s22, 0x2000
	s_add_u32 s22, s24, 0xb0000
	v_lshl_add_u64 v[216:217], s[24:25], 0, v[162:163]
	s_addc_u32 s23, s25, 0
	s_add_i32 s59, s49, s38
	global_load_lds_dwordx4 v[216:217], off
	v_lshl_add_u64 v[218:219], s[22:23], 0, v[158:159]
	s_mov_b32 m0, s59
	v_lshl_add_u64 v[220:221], s[28:29], 0, v[160:161]
	global_load_lds_dwordx4 v[218:219], off
	v_lshl_add_u64 v[218:219], s[22:23], 0, v[162:163]
	s_add_i32 m0, s59, 0x2000
	s_nop 0
	global_load_lds_dwordx4 v[218:219], off
	v_lshl_add_u64 v[218:219], s[28:29], 0, v[156:157]
	s_mov_b32 m0, s39
	s_nop 0
	global_load_lds_dwordx4 v[218:219], off
	s_mov_b32 m0, s40
	s_nop 0
	global_load_lds_dwordx4 v[220:221], off
	s_waitcnt vmcnt(8)
	s_waitcnt lgkmcnt(0)
	s_barrier

	v_mfma_f32_16x16x32_bf16 v[60:63], v[128:131], v[176:179], v[60:63]
	v_mfma_f32_16x16x32_bf16 v[56:59], v[136:139], v[176:179], v[56:59]
	v_mfma_f32_16x16x32_bf16 v[44:47], v[128:131], v[184:187], v[44:47]
	v_mfma_f32_16x16x32_bf16 v[40:43], v[136:139], v[184:187], v[40:43]
	v_mfma_f32_16x16x32_bf16 v[28:31], v[128:131], v[192:195], v[28:31]
	v_mfma_f32_16x16x32_bf16 v[24:27], v[136:139], v[192:195], v[24:27]
	v_mfma_f32_16x16x32_bf16 v[12:15], v[128:131], v[206:209], v[12:15]
	v_mfma_f32_16x16x32_bf16 v[8:11], v[136:139], v[206:209], v[8:11]
	v_mfma_f32_16x16x32_bf16 v[60:63], v[132:135], v[180:183], v[60:63]
	v_mfma_f32_16x16x32_bf16 v[56:59], v[140:143], v[180:183], v[56:59]
	v_mfma_f32_16x16x32_bf16 v[44:47], v[132:135], v[188:191], v[44:47]
	v_mfma_f32_16x16x32_bf16 v[40:43], v[140:143], v[188:191], v[40:43]
	v_mfma_f32_16x16x32_bf16 v[28:31], v[132:135], v[196:199], v[28:31]
	v_mfma_f32_16x16x32_bf16 v[24:27], v[140:143], v[196:199], v[24:27]
	v_mfma_f32_16x16x32_bf16 v[12:15], v[132:135], v[210:213], v[12:15]
	v_mfma_f32_16x16x32_bf16 v[8:11], v[140:143], v[210:213], v[8:11]

	v_mfma_f32_16x16x32_bf16 v[52:55], v[144:147], v[176:179], v[52:55]
	v_mfma_f32_16x16x32_bf16 v[48:51], v[152:155], v[176:179], v[48:51]
	v_mfma_f32_16x16x32_bf16 v[36:39], v[144:147], v[184:187], v[36:39]
	v_mfma_f32_16x16x32_bf16 v[32:35], v[152:155], v[184:187], v[32:35]
	v_mfma_f32_16x16x32_bf16 v[20:23], v[144:147], v[192:195], v[20:23]
	v_mfma_f32_16x16x32_bf16 v[16:19], v[152:155], v[192:195], v[16:19]
	v_mfma_f32_16x16x32_bf16 v[4:7], v[144:147], v[206:209], v[4:7]
	v_mfma_f32_16x16x32_bf16 v[0:3], v[152:155], v[206:209], v[0:3]
	v_mfma_f32_16x16x32_bf16 v[52:55], v[148:151], v[180:183], v[52:55]
	v_mfma_f32_16x16x32_bf16 v[48:51], v[172:175], v[180:183], v[48:51]
	v_mfma_f32_16x16x32_bf16 v[36:39], v[148:151], v[188:191], v[36:39]
	v_mfma_f32_16x16x32_bf16 v[32:35], v[172:175], v[188:191], v[32:35]
	v_mfma_f32_16x16x32_bf16 v[20:23], v[148:151], v[196:199], v[20:23]
	v_mfma_f32_16x16x32_bf16 v[16:19], v[172:175], v[196:199], v[16:19]
	v_mfma_f32_16x16x32_bf16 v[4:7], v[148:151], v[210:213], v[4:7]
	v_mfma_f32_16x16x32_bf16 v[0:3], v[172:175], v[210:213], v[0:3]

	s_barrier
	s_add_i32 s59, 0, 0x18000
	s_add_i32 s60, 0, 0x1c000
	v_add_u32_e32 v140, s59, v201
	v_add_u32_e32 v172, s60, v201
	ds_read_b128 v[128:131], v140
	ds_read_b128 v[132:135], v140 offset:1024
	ds_read_b128 v[136:139], v140 offset:2048
	ds_read_b128 v[140:143], v140 offset:3072
	ds_read_b128 v[144:147], v172
	ds_read_b128 v[148:151], v172 offset:1024
	ds_read_b128 v[152:155], v172 offset:2048
	ds_read_b128 v[172:175], v172 offset:3072
	s_add_u32 s22, s28, 0xb0000
	s_addc_u32 s23, s29, 0
	s_mov_b32 m0, s41
	v_lshl_add_u64 v[222:223], s[22:23], 0, v[156:157]
	ds_read_b128 v[176:179], v205 offset:32768
	ds_read_b128 v[180:183], v205 offset:33792
	ds_read_b128 v[184:187], v205 offset:34816
	ds_read_b128 v[188:191], v205 offset:35840
	ds_read_b128 v[192:195], v205 offset:36864
	ds_read_b128 v[196:199], v205 offset:37888
	ds_read_b128 v[206:209], v205 offset:38912
	ds_read_b128 v[210:213], v205 offset:39936
	global_load_lds_dwordx4 v[222:223], off
	v_lshl_add_u64 v[222:223], s[22:23], 0, v[160:161]
	s_mov_b32 m0, s42
	s_nop 0
	global_load_lds_dwordx4 v[222:223], off
	s_waitcnt vmcnt(8)
	s_waitcnt lgkmcnt(0)
	s_barrier

	v_mfma_f32_16x16x32_bf16 v[124:127], v[128:131], v[176:179], v[124:127]
	v_mfma_f32_16x16x32_bf16 v[120:123], v[136:139], v[176:179], v[120:123]
	v_mfma_f32_16x16x32_bf16 v[108:111], v[128:131], v[184:187], v[108:111]
	v_mfma_f32_16x16x32_bf16 v[104:107], v[136:139], v[184:187], v[104:107]
	v_mfma_f32_16x16x32_bf16 v[92:95], v[128:131], v[192:195], v[92:95]
	v_mfma_f32_16x16x32_bf16 v[88:91], v[136:139], v[192:195], v[88:91]
	v_mfma_f32_16x16x32_bf16 v[76:79], v[128:131], v[206:209], v[76:79]
	v_mfma_f32_16x16x32_bf16 v[72:75], v[136:139], v[206:209], v[72:75]
	v_mfma_f32_16x16x32_bf16 v[124:127], v[132:135], v[180:183], v[124:127]
	v_mfma_f32_16x16x32_bf16 v[120:123], v[140:143], v[180:183], v[120:123]
	v_mfma_f32_16x16x32_bf16 v[108:111], v[132:135], v[188:191], v[108:111]
	v_mfma_f32_16x16x32_bf16 v[104:107], v[140:143], v[188:191], v[104:107]
	v_mfma_f32_16x16x32_bf16 v[92:95], v[132:135], v[196:199], v[92:95]
	v_mfma_f32_16x16x32_bf16 v[88:91], v[140:143], v[196:199], v[88:91]
	v_mfma_f32_16x16x32_bf16 v[76:79], v[132:135], v[210:213], v[76:79]
	v_mfma_f32_16x16x32_bf16 v[72:75], v[140:143], v[210:213], v[72:75]

	v_mfma_f32_16x16x32_bf16 v[116:119], v[144:147], v[176:179], v[116:119]
	v_mfma_f32_16x16x32_bf16 v[112:115], v[152:155], v[176:179], v[112:115]
	v_mfma_f32_16x16x32_bf16 v[100:103], v[144:147], v[184:187], v[100:103]
	v_mfma_f32_16x16x32_bf16 v[96:99], v[152:155], v[184:187], v[96:99]
	v_mfma_f32_16x16x32_bf16 v[84:87], v[144:147], v[192:195], v[84:87]
	v_mfma_f32_16x16x32_bf16 v[80:83], v[152:155], v[192:195], v[80:83]
	v_mfma_f32_16x16x32_bf16 v[68:71], v[144:147], v[206:209], v[68:71]
	v_mfma_f32_16x16x32_bf16 v[64:67], v[152:155], v[206:209], v[64:67]
	v_mfma_f32_16x16x32_bf16 v[116:119], v[148:151], v[180:183], v[116:119]
	v_mfma_f32_16x16x32_bf16 v[112:115], v[172:175], v[180:183], v[112:115]
	v_mfma_f32_16x16x32_bf16 v[100:103], v[148:151], v[188:191], v[100:103]
	v_mfma_f32_16x16x32_bf16 v[96:99], v[172:175], v[188:191], v[96:99]
	v_mfma_f32_16x16x32_bf16 v[84:87], v[148:151], v[196:199], v[84:87]
	v_mfma_f32_16x16x32_bf16 v[80:83], v[172:175], v[196:199], v[80:83]
	v_mfma_f32_16x16x32_bf16 v[68:71], v[148:151], v[210:213], v[68:71]
	v_mfma_f32_16x16x32_bf16 v[64:67], v[172:175], v[210:213], v[64:67]

	s_barrier
	s_add_i32 s22, s59, s38
	v_lshl_add_u64 v[214:215], v[214:215], 0, s[6:7]
	s_mov_b32 m0, s22
	ds_read_b128 v[176:179], v205 offset:49152
	ds_read_b128 v[180:183], v205 offset:50176
	ds_read_b128 v[184:187], v205 offset:51200
	ds_read_b128 v[188:191], v205 offset:52224
	ds_read_b128 v[192:195], v205 offset:53248
	ds_read_b128 v[196:199], v205 offset:54272
	ds_read_b128 v[206:209], v205 offset:55296
	ds_read_b128 v[210:213], v205 offset:56320
	global_load_lds_dwordx4 v[214:215], off
	s_add_i32 m0, s22, 0x2000
	s_add_u32 s22, s24, 0xb0080
	v_lshl_add_u64 v[214:215], v[216:217], 0, s[6:7]
	s_addc_u32 s23, s25, 0
	s_add_i32 s24, s60, s38
	global_load_lds_dwordx4 v[214:215], off
	v_lshl_add_u64 v[214:215], s[22:23], 0, v[158:159]
	s_mov_b32 m0, s24
	s_nop 0
	global_load_lds_dwordx4 v[214:215], off
	v_lshl_add_u64 v[214:215], s[22:23], 0, v[162:163]
	s_add_i32 m0, s24, 0x2000
	s_nop 0
	global_load_lds_dwordx4 v[214:215], off
	v_lshl_add_u64 v[214:215], v[218:219], 0, s[6:7]
	s_mov_b32 m0, s44
	s_nop 0
	global_load_lds_dwordx4 v[214:215], off
	v_lshl_add_u64 v[214:215], v[220:221], 0, s[6:7]
	s_mov_b32 m0, s45
	s_nop 0
	global_load_lds_dwordx4 v[214:215], off
	s_waitcnt vmcnt(8)
	s_waitcnt lgkmcnt(0)
	s_barrier

	v_mfma_f32_16x16x32_bf16 v[60:63], v[128:131], v[176:179], v[60:63]
	v_mfma_f32_16x16x32_bf16 v[56:59], v[136:139], v[176:179], v[56:59]
	v_mfma_f32_16x16x32_bf16 v[44:47], v[128:131], v[184:187], v[44:47]
	v_mfma_f32_16x16x32_bf16 v[40:43], v[136:139], v[184:187], v[40:43]
	v_mfma_f32_16x16x32_bf16 v[28:31], v[128:131], v[192:195], v[28:31]
	v_mfma_f32_16x16x32_bf16 v[24:27], v[136:139], v[192:195], v[24:27]
	v_mfma_f32_16x16x32_bf16 v[12:15], v[128:131], v[206:209], v[12:15]
	v_mfma_f32_16x16x32_bf16 v[8:11], v[136:139], v[206:209], v[8:11]
	v_mfma_f32_16x16x32_bf16 v[60:63], v[132:135], v[180:183], v[60:63]
	v_mfma_f32_16x16x32_bf16 v[56:59], v[140:143], v[180:183], v[56:59]
	v_mfma_f32_16x16x32_bf16 v[44:47], v[132:135], v[188:191], v[44:47]
	v_mfma_f32_16x16x32_bf16 v[40:43], v[140:143], v[188:191], v[40:43]
	v_mfma_f32_16x16x32_bf16 v[28:31], v[132:135], v[196:199], v[28:31]
	v_mfma_f32_16x16x32_bf16 v[24:27], v[140:143], v[196:199], v[24:27]
	v_mfma_f32_16x16x32_bf16 v[12:15], v[132:135], v[210:213], v[12:15]
	v_mfma_f32_16x16x32_bf16 v[8:11], v[140:143], v[210:213], v[8:11]

	v_mfma_f32_16x16x32_bf16 v[52:55], v[144:147], v[176:179], v[52:55]
	v_mfma_f32_16x16x32_bf16 v[48:51], v[152:155], v[176:179], v[48:51]
	v_mfma_f32_16x16x32_bf16 v[36:39], v[144:147], v[184:187], v[36:39]
	v_mfma_f32_16x16x32_bf16 v[32:35], v[152:155], v[184:187], v[32:35]
	v_mfma_f32_16x16x32_bf16 v[20:23], v[144:147], v[192:195], v[20:23]
	v_mfma_f32_16x16x32_bf16 v[16:19], v[152:155], v[192:195], v[16:19]
	v_mfma_f32_16x16x32_bf16 v[4:7], v[144:147], v[206:209], v[4:7]
	v_mfma_f32_16x16x32_bf16 v[0:3], v[152:155], v[206:209], v[0:3]
	v_mfma_f32_16x16x32_bf16 v[52:55], v[148:151], v[180:183], v[52:55]
	v_mfma_f32_16x16x32_bf16 v[48:51], v[172:175], v[180:183], v[48:51]
	v_mfma_f32_16x16x32_bf16 v[36:39], v[148:151], v[188:191], v[36:39]
	v_mfma_f32_16x16x32_bf16 v[32:35], v[172:175], v[188:191], v[32:35]
	v_mfma_f32_16x16x32_bf16 v[20:23], v[148:151], v[196:199], v[20:23]
	v_mfma_f32_16x16x32_bf16 v[16:19], v[172:175], v[196:199], v[16:19]
	v_mfma_f32_16x16x32_bf16 v[4:7], v[148:151], v[210:213], v[4:7]
	v_mfma_f32_16x16x32_bf16 v[0:3], v[172:175], v[210:213], v[0:3]

	s_barrier
	s_add_i32 s58, s58, 2
	s_add_u32 s56, s56, 0x100
	s_addc_u32 s57, s57, 0
	s_cmp_gt_u32 s58, 41
	s_mov_b64 s[22:23], s[2:3]
	s_cbranch_scc0 .LBB0_1882
	v_lshl_add_u32 v174, s55, 8, v200
	v_lshl_or_b32 v172, s54, 8, v202
	v_ashrrev_i32_e32 v175, 31, v174
	v_ashrrev_i32_e32 v173, 31, v172
	v_lshlrev_b64 v[128:129], 10, v[174:175]
	v_lshl_add_u64 v[198:199], v[128:129], 0, v[172:173]
	v_lshlrev_b64 v[128:129], 1, v[198:199]
	v_lshl_add_u64 v[196:197], s[34:35], 0, v[128:129]
	v_or_b32_e32 v128, 0x100, v128
	v_lshl_add_u64 v[194:195], s[34:35], 0, v[128:129]
	v_or_b32_e32 v128, 16, v174
	v_ashrrev_i32_e32 v129, 31, v128
	v_lshlrev_b64 v[128:129], 10, v[128:129]
	v_lshl_add_u64 v[192:193], v[128:129], 0, v[172:173]
	v_lshlrev_b64 v[128:129], 1, v[192:193]
	v_lshl_add_u64 v[190:191], s[34:35], 0, v[128:129]
	v_or_b32_e32 v128, 0x100, v128
	v_lshl_add_u64 v[188:189], s[34:35], 0, v[128:129]
	v_or_b32_e32 v128, 32, v174
	v_ashrrev_i32_e32 v129, 31, v128
	v_lshlrev_b64 v[128:129], 10, v[128:129]
	v_lshl_add_u64 v[186:187], v[128:129], 0, v[172:173]
	v_lshlrev_b64 v[128:129], 1, v[186:187]
	v_lshl_add_u64 v[184:185], s[34:35], 0, v[128:129]
	v_or_b32_e32 v128, 0x100, v128
	v_lshl_add_u64 v[182:183], s[34:35], 0, v[128:129]
	v_or_b32_e32 v128, 48, v174
	v_ashrrev_i32_e32 v129, 31, v128
	v_lshlrev_b64 v[128:129], 10, v[128:129]
	v_lshl_add_u64 v[180:181], v[128:129], 0, v[172:173]
	v_lshlrev_b64 v[128:129], 1, v[180:181]
	global_load_dwordx4 v[206:209], v[196:197], off
	global_load_dwordx4 v[152:155], v[194:195], off
	v_lshl_add_u64 v[178:179], s[34:35], 0, v[128:129]
	v_or_b32_e32 v128, 0x100, v128
	global_load_dwordx4 v[148:151], v[190:191], off
	global_load_dwordx4 v[144:147], v[188:189], off
	global_load_dwordx4 v[140:143], v[184:185], off
	global_load_dwordx4 v[136:139], v[182:183], off
	v_lshl_add_u64 v[176:177], s[34:35], 0, v[128:129]
	global_load_dwordx4 v[132:135], v[178:179], off
	global_load_dwordx4 v[128:131], v[176:177], off
	v_cndmask_b32_e64 v210, 0, 1, s[8:9]
	v_cmp_ne_u32_e64 s[2:3], 1, v210
	s_andn2_b64 vcc, exec, s[8:9]
	v_lshl_add_u64 v[198:199], v[198:199], 2, s[26:27]
	s_waitcnt vmcnt(0)
	v_lshlrev_b32_e32 v210, 16, v206
	v_and_b32_e32 v211, 0xffff0000, v206
	v_lshlrev_b32_e32 v206, 16, v207
	v_and_b32_e32 v207, 0xffff0000, v207
	v_lshlrev_b32_e32 v212, 16, v208
	v_and_b32_e32 v213, 0xffff0000, v208
	v_lshlrev_b32_e32 v208, 16, v209
	v_and_b32_e32 v209, 0xffff0000, v209
	v_pk_add_f32 v[126:127], v[126:127], v[206:207]
	v_pk_add_f32 v[124:125], v[124:125], v[210:211]
	v_pk_add_f32 v[122:123], v[122:123], v[208:209]
	v_pk_add_f32 v[120:121], v[120:121], v[212:213]
	s_cbranch_vccnz .LBB0_1930
	global_store_dwordx4 v[198:199], v[124:127], off nt
	global_store_dwordx4 v[198:199], v[120:123], off offset:16 nt
	s_cbranch_execnz .LBB0_1886
